# EpiIn0 log-forget epilogue: guarded fast path (per-wave max(lb logit diff) <= 80 -> skip denormal/inf handling of logf, bit-identical), slow path kept
# speedup vs baseline: 1.0065x; 1.0065x over previous
.LBB0_756:
	s_and_b64 vcc, exec, s[6:7]
	s_cbranch_vccz .LBB0_237
	s_lshl_b32 s0, s0, 8
	v_bitop3_b32 v136, s0, v173, v168 bitop3:0xc8
	v_lshlrev_b32_e32 v136, 2, v136
	global_load_dwordx4 v[160:163], v136, s[58:59] offset:2064
	global_load_dwordx4 v[152:155], v136, s[58:59] offset:2048
	global_load_dwordx4 v[176:179], v136, s[58:59] offset:16
	global_load_dwordx4 v[180:183], v136, s[58:59]
	v_mul_f32_e32 v124, 0xbfb8aa3b, v124
	v_exp_f32_e32 v124, v124
	v_ashrrev_i32_e32 v147, 31, v146
	v_lshlrev_b64 v[148:149], 11, v[146:147]
	v_mul_f32_e32 v125, 0xbfb8aa3b, v125
	v_add_f32_e32 v124, 1.0, v124
	v_rcp_f32_e32 v147, v124
	v_exp_f32_e32 v125, v125
	v_mul_f32_e32 v126, 0xbfb8aa3b, v126
	v_exp_f32_e32 v126, v126
	v_mul_f32_e32 v127, 0xbfb8aa3b, v127
	v_add_f32_e32 v125, 1.0, v125
	v_exp_f32_e32 v127, v127
	v_add_f32_e32 v126, 1.0, v126
	v_mul_f32_e32 v120, 0xbfb8aa3b, v120
	v_exp_f32_e32 v120, v120
	v_add_f32_e32 v127, 1.0, v127
	v_mul_f32_e32 v121, 0xbfb8aa3b, v121
	v_exp_f32_e32 v121, v121
	v_add_f32_e32 v120, 1.0, v120
	v_rcp_f32_e32 v120, v120
	v_mul_f32_e32 v122, 0xbfb8aa3b, v122
	v_add_f32_e32 v121, 1.0, v121
	v_rcp_f32_e32 v121, v121
	v_exp_f32_e32 v122, v122
	v_mul_f32_e32 v116, 0xbfb8aa3b, v116
	v_exp_f32_e32 v116, v116
	v_mul_f32_e32 v117, 0xbfb8aa3b, v117
	v_add_f32_e32 v122, 1.0, v122
	v_rcp_f32_e32 v122, v122
	v_add_f32_e32 v116, 1.0, v116
	v_rcp_f32_e32 v116, v116
	v_exp_f32_e32 v117, v117
	v_mul_f32_e32 v118, 0xbfb8aa3b, v118
	v_exp_f32_e32 v118, v118
	v_mul_f32_e32 v119, 0xbfb8aa3b, v119
	v_add_f32_e32 v117, 1.0, v117
	v_rcp_f32_e32 v117, v117
	v_add_f32_e32 v118, 1.0, v118
	v_rcp_f32_e32 v118, v118
	v_exp_f32_e32 v119, v119
	v_mul_f32_e32 v112, 0xbfb8aa3b, v112
	v_exp_f32_e32 v112, v112
	v_mul_f32_e32 v113, 0xbfb8aa3b, v113
	v_add_f32_e32 v119, 1.0, v119
	v_rcp_f32_e32 v119, v119
	v_add_f32_e32 v112, 1.0, v112
	v_rcp_f32_e32 v112, v112
	v_exp_f32_e32 v113, v113
	v_mul_f32_e32 v114, 0xbfb8aa3b, v114
	v_exp_f32_e32 v114, v114
	v_mul_f32_e32 v115, 0xbfb8aa3b, v115
	v_add_f32_e32 v113, 1.0, v113
	v_rcp_f32_e32 v113, v113
	v_add_f32_e32 v114, 1.0, v114
	v_rcp_f32_e32 v114, v114
	v_exp_f32_e32 v115, v115
	v_mul_f32_e32 v108, 0xbfb8aa3b, v108
	v_exp_f32_e32 v108, v108
	v_or_b32_e32 v150, s0, v168
	v_add_f32_e32 v115, 1.0, v115
	v_rcp_f32_e32 v115, v115
	v_add_f32_e32 v108, 1.0, v108
	v_rcp_f32_e32 v108, v108
	v_mul_f32_e32 v109, 0xbfb8aa3b, v109
	v_exp_f32_e32 v109, v109
	v_mul_f32_e32 v110, 0xbfb8aa3b, v110
	v_exp_f32_e32 v110, v110
	v_mul_f32_e32 v111, 0xbfb8aa3b, v111
	v_add_f32_e32 v109, 1.0, v109
	v_rcp_f32_e32 v109, v109
	v_add_f32_e32 v110, 1.0, v110
	v_rcp_f32_e32 v110, v110
	v_exp_f32_e32 v111, v111
	v_mul_f32_e32 v104, 0xbfb8aa3b, v104
	v_exp_f32_e32 v104, v104
	v_mul_f32_e32 v105, 0xbfb8aa3b, v105
	v_add_f32_e32 v111, 1.0, v111
	v_rcp_f32_e32 v111, v111
	s_waitcnt vmcnt(0)
	v_sub_f32_e32 v136, v152, v180
	v_sub_f32_e32 v158, v153, v181
	v_max_f32_e32 v136, v136, v158
	v_sub_f32_e32 v158, v154, v182
	v_max_f32_e32 v136, v136, v158
	v_sub_f32_e32 v158, v155, v183
	v_max_f32_e32 v136, v136, v158
	v_sub_f32_e32 v158, v160, v176
	v_max_f32_e32 v136, v136, v158
	v_sub_f32_e32 v158, v161, v177
	v_max_f32_e32 v136, v136, v158
	v_sub_f32_e32 v158, v162, v178
	v_max_f32_e32 v136, v136, v158
	v_sub_f32_e32 v158, v163, v179
	v_max_f32_e32 v136, v136, v158
	v_cmp_nge_f32_e32 vcc, 0x42a00000, v136
	s_cbranch_vccz .Lhvy_fast1
	v_sub_f32_e32 v136, v152, v180
	v_mul_f32_e32 v136, 0x3fb8aa3b, v136
	v_exp_f32_e32 v136, v136
	v_add_f32_e32 v104, 1.0, v104
	v_rcp_f32_e32 v104, v104
	v_exp_f32_e32 v105, v105
	v_add_f32_e32 v136, 1.0, v136
	v_rcp_f32_e32 v158, v136
	v_sub_f32_e32 v136, v153, v181
	v_mul_f32_e32 v136, 0x3fb8aa3b, v136
	v_exp_f32_e32 v136, v136
	v_sub_f32_e32 v124, 1.0, v158
	v_fma_f32 v147, v147, v124, v158
	v_cmp_gt_f32_e32 vcc, s86, v147
	v_add_f32_e32 v136, 1.0, v136
	v_rcp_f32_e32 v157, v136
	v_sub_f32_e32 v136, v154, v182
	v_mul_f32_e32 v136, 0x3fb8aa3b, v136
	v_exp_f32_e32 v136, v136
	v_cndmask_b32_e64 v159, 0, 32, vcc
	v_ldexp_f32 v147, v147, v159
	v_log_f32_e32 v147, v147
	v_add_f32_e32 v136, 1.0, v136
	v_rcp_f32_e32 v156, v136
	v_sub_f32_e32 v136, v155, v183
	v_mul_f32_e32 v136, 0x3fb8aa3b, v136
	v_exp_f32_e32 v136, v136
	v_mul_f32_e32 v159, 0x3f317217, v147
	v_fma_f32 v159, v147, s87, -v159
	v_fmac_f32_e32 v159, 0x3377d1cf, v147
	v_add_f32_e32 v136, 1.0, v136
	v_rcp_f32_e32 v155, v136
	v_sub_f32_e32 v136, v160, v176
	v_mul_f32_e32 v136, 0x3fb8aa3b, v136
	v_exp_f32_e32 v136, v136
	v_fmac_f32_e32 v159, 0x3f317217, v147
	v_cmp_lt_f32_e64 s[6:7], |v147|, s88
	v_fma_f32 v116, v116, v124, v158
	v_add_f32_e32 v136, 1.0, v136
	v_cndmask_b32_e64 v147, v147, v159, s[6:7]
	v_cndmask_b32_e32 v159, 0, v174, vcc
	v_rcp_f32_e32 v154, v136
	v_sub_f32_e32 v136, v161, v177
	v_sub_f32_e32 v161, v147, v159
	v_rcp_f32_e32 v147, v125
	v_sub_f32_e32 v125, 1.0, v157
	v_mul_f32_e32 v136, 0x3fb8aa3b, v136
	v_exp_f32_e32 v136, v136
	v_fma_f32 v147, v147, v125, v157
	v_cmp_gt_f32_e32 vcc, s86, v147
	v_sub_f32_e32 v160, 1.0, v154
	v_add_f32_e32 v136, 1.0, v136
	v_cndmask_b32_e64 v159, 0, 32, vcc
	v_ldexp_f32 v147, v147, v159
	v_log_f32_e32 v147, v147
	v_rcp_f32_e32 v153, v136
	v_sub_f32_e32 v136, v162, v178
	v_mul_f32_e32 v136, 0x3fb8aa3b, v136
	v_mul_f32_e32 v159, 0x3f317217, v147
	v_fma_f32 v159, v147, s87, -v159
	v_fmac_f32_e32 v159, 0x3377d1cf, v147
	v_fmac_f32_e32 v159, 0x3f317217, v147
	v_cmp_lt_f32_e64 s[6:7], |v147|, s88
	v_exp_f32_e32 v136, v136
	v_fma_f32 v120, v120, v160, v154
	v_cndmask_b32_e64 v147, v147, v159, s[6:7]
	v_cndmask_b32_e32 v159, 0, v174, vcc
	v_sub_f32_e32 v162, v147, v159
	v_rcp_f32_e32 v147, v126
	v_sub_f32_e32 v126, 1.0, v156
	v_add_f32_e32 v136, 1.0, v136
	v_rcp_f32_e32 v152, v136
	v_fma_f32 v147, v147, v126, v156
	v_cmp_gt_f32_e32 vcc, s86, v147
	v_sub_f32_e32 v136, v163, v179
	v_mul_f32_e32 v136, 0x3fb8aa3b, v136
	v_cndmask_b32_e64 v159, 0, 32, vcc
	v_ldexp_f32 v147, v147, v159
	v_log_f32_e32 v147, v147
	v_exp_f32_e32 v136, v136
	v_fma_f32 v117, v117, v125, v157
	v_fma_f32 v118, v118, v126, v156
	v_mul_f32_e32 v159, 0x3f317217, v147
	v_fma_f32 v159, v147, s87, -v159
	v_fmac_f32_e32 v159, 0x3377d1cf, v147
	v_fmac_f32_e32 v159, 0x3f317217, v147
	v_cmp_lt_f32_e64 s[6:7], |v147|, s88
	v_add_f32_e32 v136, 1.0, v136
	v_rcp_f32_e32 v151, v136
	v_cndmask_b32_e64 v147, v147, v159, s[6:7]
	v_cndmask_b32_e32 v159, 0, v174, vcc
	v_sub_f32_e32 v163, v147, v159
	v_rcp_f32_e32 v147, v127
	v_sub_f32_e32 v127, 1.0, v155
	v_fma_f32 v119, v119, v127, v155
	v_fma_f32 v112, v112, v160, v154
	v_fma_f32 v147, v147, v127, v155
	v_cmp_gt_f32_e32 vcc, s86, v147
	v_lshlrev_b32_e32 v136, 1, v150
	v_fma_f32 v108, v108, v124, v158
	v_cndmask_b32_e64 v159, 0, 32, vcc
	v_ldexp_f32 v147, v147, v159
	v_log_f32_e32 v147, v147
	v_fma_f32 v109, v109, v125, v157
	v_fma_f32 v110, v110, v126, v156
	v_fma_f32 v111, v111, v127, v155
	v_mul_f32_e32 v159, 0x3f317217, v147
	v_fma_f32 v159, v147, s87, -v159
	v_fmac_f32_e32 v159, 0x3377d1cf, v147
	v_fmac_f32_e32 v159, 0x3f317217, v147
	v_cmp_lt_f32_e64 s[6:7], |v147|, s88
	v_fma_f32 v104, v104, v160, v154
	v_add_f32_e32 v105, 1.0, v105
	v_cndmask_b32_e64 v147, v147, v159, s[6:7]
	v_cndmask_b32_e32 v159, 0, v174, vcc
	v_cmp_gt_f32_e32 vcc, s86, v120
	v_sub_f32_e32 v176, v147, v159
	v_rcp_f32_e32 v105, v105
	v_cndmask_b32_e64 v147, 0, 32, vcc
	v_ldexp_f32 v120, v120, v147
	v_log_f32_e32 v120, v120
	v_mul_f32_e32 v106, 0xbfb8aa3b, v106
	v_exp_f32_e32 v106, v106
	v_mul_f32_e32 v107, 0xbfb8aa3b, v107
	v_mul_f32_e32 v147, 0x3f317217, v120
	v_fma_f32 v147, v120, s87, -v147
	v_fmac_f32_e32 v147, 0x3377d1cf, v120
	v_fmac_f32_e32 v147, 0x3f317217, v120
	v_cmp_lt_f32_e64 s[6:7], |v120|, s88
	v_add_f32_e32 v106, 1.0, v106
	v_rcp_f32_e32 v106, v106
	v_cndmask_b32_e64 v120, v120, v147, s[6:7]
	v_cndmask_b32_e32 v147, 0, v174, vcc
	v_sub_f32_e32 v120, v120, v147
	v_sub_f32_e32 v147, 1.0, v153
	v_fma_f32 v121, v121, v147, v153
	v_cmp_gt_f32_e32 vcc, s86, v121
	v_fma_f32 v113, v113, v147, v153
	v_fma_f32 v105, v105, v147, v153
	v_cndmask_b32_e64 v159, 0, 32, vcc
	v_ldexp_f32 v121, v121, v159
	v_log_f32_e32 v121, v121
	v_exp_f32_e32 v107, v107
	v_mul_f32_e32 v100, 0xbfb8aa3b, v100
	v_exp_f32_e32 v100, v100
	v_mul_f32_e32 v159, 0x3f317217, v121
	v_fma_f32 v159, v121, s87, -v159
	v_fmac_f32_e32 v159, 0x3377d1cf, v121
	v_fmac_f32_e32 v159, 0x3f317217, v121
	v_cmp_lt_f32_e64 s[6:7], |v121|, s88
	v_add_f32_e32 v107, 1.0, v107
	v_rcp_f32_e32 v107, v107
	v_cndmask_b32_e64 v121, v121, v159, s[6:7]
	v_cndmask_b32_e32 v159, 0, v174, vcc
	v_sub_f32_e32 v121, v121, v159
	v_sub_f32_e32 v159, 1.0, v152
	v_fma_f32 v122, v122, v159, v152
	v_cmp_gt_f32_e32 vcc, s86, v122
	v_fma_f32 v114, v114, v159, v152
	v_fma_f32 v106, v106, v159, v152
	v_cndmask_b32_e64 v164, 0, 32, vcc
	v_ldexp_f32 v122, v122, v164
	v_log_f32_e32 v122, v122
	v_add_f32_e32 v100, 1.0, v100
	v_rcp_f32_e32 v100, v100
	v_mul_f32_e32 v101, 0xbfb8aa3b, v101
	v_mul_f32_e32 v164, 0x3f317217, v122
	v_fma_f32 v164, v122, s87, -v164
	v_fmac_f32_e32 v164, 0x3377d1cf, v122
	v_fmac_f32_e32 v164, 0x3f317217, v122
	v_cmp_lt_f32_e64 s[6:7], |v122|, s88
	v_fma_f32 v100, v100, v124, v158
	v_exp_f32_e32 v101, v101
	v_cndmask_b32_e64 v122, v122, v164, s[6:7]
	v_cndmask_b32_e32 v164, 0, v174, vcc
	v_sub_f32_e32 v164, v122, v164
	v_mul_f32_e32 v122, 0xbfb8aa3b, v123
	v_exp_f32_e32 v122, v122
	v_add_f32_e32 v101, 1.0, v101
	v_rcp_f32_e32 v101, v101
	v_mul_f32_e32 v102, 0xbfb8aa3b, v102
	v_add_f32_e32 v122, 1.0, v122
	v_rcp_f32_e32 v123, v122
	v_sub_f32_e32 v122, 1.0, v151
	v_fma_f32 v115, v115, v122, v151
	v_fma_f32 v107, v107, v122, v151
	v_fma_f32 v123, v123, v122, v151
	v_cmp_gt_f32_e32 vcc, s86, v123
	v_fma_f32 v101, v101, v125, v157
	v_exp_f32_e32 v102, v102
	v_cndmask_b32_e64 v165, 0, 32, vcc
	v_ldexp_f32 v123, v123, v165
	v_log_f32_e32 v123, v123
	v_add_f32_e32 v102, 1.0, v102
	v_rcp_f32_e32 v102, v102
	v_mul_f32_e32 v103, 0xbfb8aa3b, v103
	v_mul_f32_e32 v165, 0x3f317217, v123
	v_fma_f32 v165, v123, s87, -v165
	v_fmac_f32_e32 v165, 0x3377d1cf, v123
	v_fmac_f32_e32 v165, 0x3f317217, v123
	v_cmp_lt_f32_e64 s[6:7], |v123|, s88
	v_fma_f32 v102, v102, v126, v156
	v_exp_f32_e32 v103, v103
	v_cndmask_b32_e64 v123, v123, v165, s[6:7]
	v_cndmask_b32_e32 v165, 0, v174, vcc
	v_sub_f32_e32 v123, v123, v165
	v_cmp_gt_f32_e32 vcc, s86, v116
	v_cvt_pk_f16_f32 v165, v164, v123
	v_cvt_pk_f16_f32 v164, v120, v121
	v_cndmask_b32_e64 v123, 0, 32, vcc
	v_ldexp_f32 v116, v116, v123
	v_log_f32_e32 v116, v116
	v_or_b32_e32 v120, 16, v146
	v_ashrrev_i32_e32 v121, 31, v120
	v_lshlrev_b64 v[120:121], 11, v[120:121]
	v_mul_f32_e32 v123, 0x3f317217, v116
	v_fma_f32 v123, v116, s87, -v123
	v_fmac_f32_e32 v123, 0x3377d1cf, v116
	v_fmac_f32_e32 v123, 0x3f317217, v116
	v_cmp_lt_f32_e64 s[6:7], |v116|, s88
	v_lshl_add_u64 v[120:121], s[84:85], 0, v[120:121]
	v_lshl_add_u64 v[120:121], v[120:121], 0, v[136:137]
	v_cndmask_b32_e64 v116, v116, v123, s[6:7]
	v_cndmask_b32_e32 v123, 0, v174, vcc
	v_cmp_gt_f32_e32 vcc, s86, v117
	v_sub_f32_e32 v116, v116, v123
	v_add_f32_e32 v103, 1.0, v103
	v_cndmask_b32_e64 v123, 0, 32, vcc
	v_ldexp_f32 v117, v117, v123
	v_log_f32_e32 v117, v117
	v_rcp_f32_e32 v103, v103
	v_mul_f32_e32 v96, 0xbfb8aa3b, v96
	v_exp_f32_e32 v96, v96
	v_mul_f32_e32 v123, 0x3f317217, v117
	v_fma_f32 v123, v117, s87, -v123
	v_fmac_f32_e32 v123, 0x3377d1cf, v117
	v_fmac_f32_e32 v123, 0x3f317217, v117
	v_cmp_lt_f32_e64 s[6:7], |v117|, s88
	v_fma_f32 v103, v103, v127, v155
	v_add_f32_e32 v96, 1.0, v96
	v_cndmask_b32_e64 v117, v117, v123, s[6:7]
	v_cndmask_b32_e32 v123, 0, v174, vcc
	v_cmp_gt_f32_e32 vcc, s86, v118
	v_sub_f32_e32 v117, v117, v123
	v_rcp_f32_e32 v96, v96
	v_cndmask_b32_e64 v123, 0, 32, vcc
	v_ldexp_f32 v118, v118, v123
	v_log_f32_e32 v118, v118
	v_fma_f32 v96, v96, v160, v154
	v_mul_f32_e32 v97, 0xbfb8aa3b, v97
	v_exp_f32_e32 v97, v97
	v_mul_f32_e32 v123, 0x3f317217, v118
	v_fma_f32 v123, v118, s87, -v123
	v_fmac_f32_e32 v123, 0x3377d1cf, v118
	v_fmac_f32_e32 v123, 0x3f317217, v118
	v_cmp_lt_f32_e64 s[6:7], |v118|, s88
	v_add_f32_e32 v97, 1.0, v97
	v_rcp_f32_e32 v97, v97
	v_cndmask_b32_e64 v118, v118, v123, s[6:7]
	v_cndmask_b32_e32 v123, 0, v174, vcc
	v_cmp_gt_f32_e32 vcc, s86, v119
	v_sub_f32_e32 v118, v118, v123
	v_fma_f32 v97, v97, v147, v153
	v_cndmask_b32_e64 v123, 0, 32, vcc
	v_ldexp_f32 v119, v119, v123
	v_log_f32_e32 v119, v119
	v_mul_f32_e32 v98, 0xbfb8aa3b, v98
	v_exp_f32_e32 v98, v98
	v_mul_f32_e32 v99, 0xbfb8aa3b, v99
	v_mul_f32_e32 v123, 0x3f317217, v119
	v_fma_f32 v123, v119, s87, -v123
	v_fmac_f32_e32 v123, 0x3377d1cf, v119
	v_fmac_f32_e32 v123, 0x3f317217, v119
	v_cmp_lt_f32_e64 s[6:7], |v119|, s88
	v_add_f32_e32 v98, 1.0, v98
	v_rcp_f32_e32 v98, v98
	v_cndmask_b32_e64 v119, v119, v123, s[6:7]
	v_cndmask_b32_e32 v123, 0, v174, vcc
	v_cmp_gt_f32_e32 vcc, s86, v112
	v_sub_f32_e32 v119, v119, v123
	v_fma_f32 v98, v98, v159, v152
	v_cndmask_b32_e64 v123, 0, 32, vcc
	v_ldexp_f32 v112, v112, v123
	v_log_f32_e32 v112, v112
	v_exp_f32_e32 v99, v99
	v_mul_f32_e32 v92, 0xbfb8aa3b, v92
	v_exp_f32_e32 v92, v92
	v_mul_f32_e32 v123, 0x3f317217, v112
	v_fma_f32 v123, v112, s87, -v123
	v_fmac_f32_e32 v123, 0x3377d1cf, v112
	v_fmac_f32_e32 v123, 0x3f317217, v112
	v_cmp_lt_f32_e64 s[6:7], |v112|, s88
	v_add_f32_e32 v99, 1.0, v99
	v_rcp_f32_e32 v99, v99
	v_cndmask_b32_e64 v112, v112, v123, s[6:7]
	v_cndmask_b32_e32 v123, 0, v174, vcc
	v_cmp_gt_f32_e32 vcc, s86, v113
	v_sub_f32_e32 v112, v112, v123
	v_fma_f32 v99, v99, v122, v151
	v_cndmask_b32_e64 v123, 0, 32, vcc
	v_ldexp_f32 v113, v113, v123
	v_log_f32_e32 v113, v113
	v_add_f32_e32 v92, 1.0, v92
	v_rcp_f32_e32 v92, v92
	v_mul_f32_e32 v93, 0xbfb8aa3b, v93
	v_mul_f32_e32 v123, 0x3f317217, v113
	v_fma_f32 v123, v113, s87, -v123
	v_fmac_f32_e32 v123, 0x3377d1cf, v113
	v_fmac_f32_e32 v123, 0x3f317217, v113
	v_cmp_lt_f32_e64 s[6:7], |v113|, s88
	v_fma_f32 v92, v92, v124, v158
	v_exp_f32_e32 v93, v93
	v_cndmask_b32_e64 v113, v113, v123, s[6:7]
	v_cndmask_b32_e32 v123, 0, v174, vcc
	v_cmp_gt_f32_e32 vcc, s86, v114
	v_sub_f32_e32 v113, v113, v123
	v_add_f32_e32 v93, 1.0, v93
	v_cndmask_b32_e64 v123, 0, 32, vcc
	v_ldexp_f32 v114, v114, v123
	v_log_f32_e32 v114, v114
	v_rcp_f32_e32 v93, v93
	v_lshl_add_u64 v[148:149], s[84:85], 0, v[148:149]
	v_lshl_add_u64 v[148:149], v[148:149], 0, v[136:137]
	v_mul_f32_e32 v123, 0x3f317217, v114
	v_fma_f32 v123, v114, s87, -v123
	v_fmac_f32_e32 v123, 0x3377d1cf, v114
	v_fmac_f32_e32 v123, 0x3f317217, v114
	v_cmp_lt_f32_e64 s[6:7], |v114|, s88
	v_fma_f32 v93, v93, v125, v157
	v_mul_f32_e32 v94, 0xbfb8aa3b, v94
	v_cndmask_b32_e64 v114, v114, v123, s[6:7]
	v_cndmask_b32_e32 v123, 0, v174, vcc
	v_cmp_gt_f32_e32 vcc, s86, v115
	v_sub_f32_e32 v114, v114, v123
	v_exp_f32_e32 v94, v94
	v_cndmask_b32_e64 v123, 0, 32, vcc
	v_ldexp_f32 v115, v115, v123
	v_log_f32_e32 v115, v115
	v_add_f32_e32 v94, 1.0, v94
	v_rcp_f32_e32 v94, v94
	v_mul_f32_e32 v95, 0xbfb8aa3b, v95
	v_mul_f32_e32 v123, 0x3f317217, v115
	v_fma_f32 v123, v115, s87, -v123
	v_fmac_f32_e32 v123, 0x3377d1cf, v115
	v_fmac_f32_e32 v123, 0x3f317217, v115
	v_cmp_lt_f32_e64 s[6:7], |v115|, s88
	v_fma_f32 v94, v94, v126, v156
	v_exp_f32_e32 v95, v95
	v_cndmask_b32_e64 v115, v115, v123, s[6:7]
	v_cndmask_b32_e32 v123, 0, v174, vcc
	v_sub_f32_e32 v115, v115, v123
	v_cvt_pk_f16_f32 v115, v114, v115
	v_cvt_pk_f16_f32 v114, v112, v113
	v_cvt_pk_f16_f32 v113, v118, v119
	v_cvt_pk_f16_f32 v112, v116, v117
	v_cmp_gt_f32_e32 vcc, s86, v108
	global_store_dwordx4 v[120:121], v[112:115], off offset:-2048
	v_add_f32_e32 v95, 1.0, v95
	v_rcp_f32_e32 v95, v95
	v_cndmask_b32_e64 v114, 0, 32, vcc
	v_ldexp_f32 v108, v108, v114
	v_log_f32_e32 v108, v108
	v_or_b32_e32 v112, 32, v146
	v_ashrrev_i32_e32 v113, 31, v112
	v_lshlrev_b64 v[112:113], 11, v[112:113]
	v_mul_f32_e32 v114, 0x3f317217, v108
	v_fma_f32 v114, v108, s87, -v114
	v_fmac_f32_e32 v114, 0x3377d1cf, v108
	v_fmac_f32_e32 v114, 0x3f317217, v108
	v_cmp_lt_f32_e64 s[6:7], |v108|, s88
	v_lshl_add_u64 v[112:113], s[84:85], 0, v[112:113]
	v_lshl_add_u64 v[112:113], v[112:113], 0, v[136:137]
	v_cndmask_b32_e64 v108, v108, v114, s[6:7]
	v_cndmask_b32_e32 v114, 0, v174, vcc
	v_cmp_gt_f32_e32 vcc, s86, v109
	v_sub_f32_e32 v108, v108, v114
	v_fma_f32 v95, v95, v127, v155
	v_cndmask_b32_e64 v114, 0, 32, vcc
	v_ldexp_f32 v109, v109, v114
	v_log_f32_e32 v109, v109
	v_mul_f32_e32 v88, 0xbfb8aa3b, v88
	v_exp_f32_e32 v88, v88
	v_mul_f32_e32 v89, 0xbfb8aa3b, v89
	v_mul_f32_e32 v114, 0x3f317217, v109
	v_fma_f32 v114, v109, s87, -v114
	v_fmac_f32_e32 v114, 0x3377d1cf, v109
	v_fmac_f32_e32 v114, 0x3f317217, v109
	v_cmp_lt_f32_e64 s[6:7], |v109|, s88
	v_add_f32_e32 v88, 1.0, v88
	v_rcp_f32_e32 v88, v88
	v_cndmask_b32_e64 v109, v109, v114, s[6:7]
	v_cndmask_b32_e32 v114, 0, v174, vcc
	v_cmp_gt_f32_e32 vcc, s86, v110
	v_sub_f32_e32 v109, v109, v114
	v_fma_f32 v88, v88, v160, v154
	v_cndmask_b32_e64 v114, 0, 32, vcc
	v_ldexp_f32 v110, v110, v114
	v_log_f32_e32 v110, v110
	v_exp_f32_e32 v89, v89
	v_mul_f32_e32 v90, 0xbfb8aa3b, v90
	v_exp_f32_e32 v90, v90
	v_mul_f32_e32 v114, 0x3f317217, v110
	v_fma_f32 v114, v110, s87, -v114
	v_fmac_f32_e32 v114, 0x3377d1cf, v110
	v_fmac_f32_e32 v114, 0x3f317217, v110
	v_cmp_lt_f32_e64 s[6:7], |v110|, s88
	v_add_f32_e32 v89, 1.0, v89
	v_rcp_f32_e32 v89, v89
	v_cndmask_b32_e64 v110, v110, v114, s[6:7]
	v_cndmask_b32_e32 v114, 0, v174, vcc
	v_cmp_gt_f32_e32 vcc, s86, v111
	v_sub_f32_e32 v110, v110, v114
	v_fma_f32 v89, v89, v147, v153
	v_cndmask_b32_e64 v114, 0, 32, vcc
	v_ldexp_f32 v111, v111, v114
	v_log_f32_e32 v111, v111
	v_add_f32_e32 v90, 1.0, v90
	v_rcp_f32_e32 v90, v90
	v_mul_f32_e32 v91, 0xbfb8aa3b, v91
	v_mul_f32_e32 v114, 0x3f317217, v111
	v_fma_f32 v114, v111, s87, -v114
	v_fmac_f32_e32 v114, 0x3377d1cf, v111
	v_fmac_f32_e32 v114, 0x3f317217, v111
	v_cmp_lt_f32_e64 s[6:7], |v111|, s88
	v_fma_f32 v90, v90, v159, v152
	v_exp_f32_e32 v91, v91
	v_cndmask_b32_e64 v111, v111, v114, s[6:7]
	v_cndmask_b32_e32 v114, 0, v174, vcc
	v_cmp_gt_f32_e32 vcc, s86, v104
	v_sub_f32_e32 v111, v111, v114
	v_add_f32_e32 v91, 1.0, v91
	v_cndmask_b32_e64 v114, 0, 32, vcc
	v_ldexp_f32 v104, v104, v114
	v_log_f32_e32 v104, v104
	v_rcp_f32_e32 v91, v91
	v_mul_f32_e32 v84, 0xbfb8aa3b, v84
	v_exp_f32_e32 v84, v84
	v_mul_f32_e32 v114, 0x3f317217, v104
	v_fma_f32 v114, v104, s87, -v114
	v_fmac_f32_e32 v114, 0x3377d1cf, v104
	v_fmac_f32_e32 v114, 0x3f317217, v104
	v_cmp_lt_f32_e64 s[6:7], |v104|, s88
	v_fma_f32 v91, v91, v122, v151
	v_add_f32_e32 v84, 1.0, v84
	v_cndmask_b32_e64 v104, v104, v114, s[6:7]
	v_cndmask_b32_e32 v114, 0, v174, vcc
	v_cmp_gt_f32_e32 vcc, s86, v105
	v_sub_f32_e32 v104, v104, v114
	v_rcp_f32_e32 v84, v84
	v_cndmask_b32_e64 v114, 0, 32, vcc
	v_ldexp_f32 v105, v105, v114
	v_log_f32_e32 v105, v105
	v_fma_f32 v84, v84, v124, v158
	v_mul_f32_e32 v85, 0xbfb8aa3b, v85
	v_exp_f32_e32 v85, v85
	v_mul_f32_e32 v114, 0x3f317217, v105
	v_fma_f32 v114, v105, s87, -v114
	v_fmac_f32_e32 v114, 0x3377d1cf, v105
	v_fmac_f32_e32 v114, 0x3f317217, v105
	v_cmp_lt_f32_e64 s[6:7], |v105|, s88
	v_add_f32_e32 v85, 1.0, v85
	v_rcp_f32_e32 v85, v85
	v_cndmask_b32_e64 v105, v105, v114, s[6:7]
	v_cndmask_b32_e32 v114, 0, v174, vcc
	v_cmp_gt_f32_e32 vcc, s86, v106
	v_sub_f32_e32 v105, v105, v114
	v_fma_f32 v85, v85, v125, v157
	v_cndmask_b32_e64 v114, 0, 32, vcc
	v_ldexp_f32 v106, v106, v114
	v_log_f32_e32 v106, v106
	v_mul_f32_e32 v86, 0xbfb8aa3b, v86
	v_exp_f32_e32 v86, v86
	v_mul_f32_e32 v87, 0xbfb8aa3b, v87
	v_mul_f32_e32 v114, 0x3f317217, v106
	v_fma_f32 v114, v106, s87, -v114
	v_fmac_f32_e32 v114, 0x3377d1cf, v106
	v_fmac_f32_e32 v114, 0x3f317217, v106
	v_cmp_lt_f32_e64 s[6:7], |v106|, s88
	v_add_f32_e32 v86, 1.0, v86
	v_rcp_f32_e32 v86, v86
	v_cndmask_b32_e64 v106, v106, v114, s[6:7]
	v_cndmask_b32_e32 v114, 0, v174, vcc
	v_cmp_gt_f32_e32 vcc, s86, v107
	v_sub_f32_e32 v106, v106, v114
	v_fma_f32 v86, v86, v126, v156
	v_cndmask_b32_e64 v114, 0, 32, vcc
	v_ldexp_f32 v107, v107, v114
	v_log_f32_e32 v107, v107
	v_exp_f32_e32 v87, v87
	v_mul_f32_e32 v80, 0xbfb8aa3b, v80
	v_exp_f32_e32 v80, v80
	v_mul_f32_e32 v114, 0x3f317217, v107
	v_fma_f32 v114, v107, s87, -v114
	v_fmac_f32_e32 v114, 0x3377d1cf, v107
	v_fmac_f32_e32 v114, 0x3f317217, v107
	v_cmp_lt_f32_e64 s[6:7], |v107|, s88
	v_add_f32_e32 v87, 1.0, v87
	v_rcp_f32_e32 v87, v87
	v_cndmask_b32_e64 v107, v107, v114, s[6:7]
	v_cndmask_b32_e32 v114, 0, v174, vcc
	v_sub_f32_e32 v107, v107, v114
	v_cvt_pk_f16_f32 v107, v106, v107
	v_cvt_pk_f16_f32 v106, v104, v105
	v_cvt_pk_f16_f32 v105, v110, v111
	v_cvt_pk_f16_f32 v104, v108, v109
	v_cmp_gt_f32_e32 vcc, s86, v100
	global_store_dwordx4 v[112:113], v[104:107], off offset:-2048
	v_fma_f32 v87, v87, v127, v155
	v_add_f32_e32 v80, 1.0, v80
	v_cndmask_b32_e64 v106, 0, 32, vcc
	v_ldexp_f32 v100, v100, v106
	v_log_f32_e32 v100, v100
	v_or_b32_e32 v104, 48, v146
	v_ashrrev_i32_e32 v105, 31, v104
	v_lshlrev_b64 v[104:105], 11, v[104:105]
	v_mul_f32_e32 v106, 0x3f317217, v100
	v_fma_f32 v106, v100, s87, -v106
	v_fmac_f32_e32 v106, 0x3377d1cf, v100
	v_fmac_f32_e32 v106, 0x3f317217, v100
	v_cmp_lt_f32_e64 s[6:7], |v100|, s88
	v_lshl_add_u64 v[104:105], s[84:85], 0, v[104:105]
	v_lshl_add_u64 v[104:105], v[104:105], 0, v[136:137]
	v_cndmask_b32_e64 v100, v100, v106, s[6:7]
	v_cndmask_b32_e32 v106, 0, v174, vcc
	v_cmp_gt_f32_e32 vcc, s86, v101
	v_sub_f32_e32 v100, v100, v106
	v_rcp_f32_e32 v80, v80
	v_cndmask_b32_e64 v106, 0, 32, vcc
	v_ldexp_f32 v101, v101, v106
	v_log_f32_e32 v101, v101
	v_fma_f32 v80, v80, v160, v154
	v_mul_f32_e32 v81, 0xbfb8aa3b, v81
	v_exp_f32_e32 v81, v81
	v_mul_f32_e32 v106, 0x3f317217, v101
	v_fma_f32 v106, v101, s87, -v106
	v_fmac_f32_e32 v106, 0x3377d1cf, v101
	v_fmac_f32_e32 v106, 0x3f317217, v101
	v_cmp_lt_f32_e64 s[6:7], |v101|, s88
	v_add_f32_e32 v81, 1.0, v81
	v_rcp_f32_e32 v81, v81
	v_cndmask_b32_e64 v101, v101, v106, s[6:7]
	v_cndmask_b32_e32 v106, 0, v174, vcc
	v_cmp_gt_f32_e32 vcc, s86, v102
	v_sub_f32_e32 v101, v101, v106
	v_fma_f32 v81, v81, v147, v153
	v_cndmask_b32_e64 v106, 0, 32, vcc
	v_ldexp_f32 v102, v102, v106
	v_log_f32_e32 v102, v102
	v_mul_f32_e32 v82, 0xbfb8aa3b, v82
	v_exp_f32_e32 v82, v82
	v_mul_f32_e32 v83, 0xbfb8aa3b, v83
	v_mul_f32_e32 v106, 0x3f317217, v102
	v_fma_f32 v106, v102, s87, -v106
	v_fmac_f32_e32 v106, 0x3377d1cf, v102
	v_fmac_f32_e32 v106, 0x3f317217, v102
	v_cmp_lt_f32_e64 s[6:7], |v102|, s88
	v_add_f32_e32 v82, 1.0, v82
	v_rcp_f32_e32 v82, v82
	v_cndmask_b32_e64 v102, v102, v106, s[6:7]
	v_cndmask_b32_e32 v106, 0, v174, vcc
	v_cmp_gt_f32_e32 vcc, s86, v103
	v_sub_f32_e32 v102, v102, v106
	v_fma_f32 v82, v82, v159, v152
	v_cndmask_b32_e64 v106, 0, 32, vcc
	v_ldexp_f32 v103, v103, v106
	v_log_f32_e32 v103, v103
	v_exp_f32_e32 v83, v83
	v_mul_f32_e32 v76, 0xbfb8aa3b, v76
	v_exp_f32_e32 v76, v76
	v_mul_f32_e32 v106, 0x3f317217, v103
	v_fma_f32 v106, v103, s87, -v106
	v_fmac_f32_e32 v106, 0x3377d1cf, v103
	v_fmac_f32_e32 v106, 0x3f317217, v103
	v_cmp_lt_f32_e64 s[6:7], |v103|, s88
	v_add_f32_e32 v83, 1.0, v83
	v_rcp_f32_e32 v83, v83
	v_cndmask_b32_e64 v103, v103, v106, s[6:7]
	v_cndmask_b32_e32 v106, 0, v174, vcc
	v_cmp_gt_f32_e32 vcc, s86, v96
	v_sub_f32_e32 v103, v103, v106
	v_fma_f32 v83, v83, v122, v151
	v_cndmask_b32_e64 v106, 0, 32, vcc
	v_ldexp_f32 v96, v96, v106
	v_log_f32_e32 v96, v96
	v_add_f32_e32 v76, 1.0, v76
	v_rcp_f32_e32 v76, v76
	v_mul_f32_e32 v77, 0xbfb8aa3b, v77
	v_mul_f32_e32 v106, 0x3f317217, v96
	v_fma_f32 v106, v96, s87, -v106
	v_fmac_f32_e32 v106, 0x3377d1cf, v96
	v_fmac_f32_e32 v106, 0x3f317217, v96
	v_cmp_lt_f32_e64 s[6:7], |v96|, s88
	v_fma_f32 v76, v76, v124, v158
	v_exp_f32_e32 v77, v77
	v_cndmask_b32_e64 v96, v96, v106, s[6:7]
	v_cndmask_b32_e32 v106, 0, v174, vcc
	v_cmp_gt_f32_e32 vcc, s86, v97
	v_sub_f32_e32 v96, v96, v106
	v_add_f32_e32 v77, 1.0, v77
	v_cndmask_b32_e64 v106, 0, 32, vcc
	v_ldexp_f32 v97, v97, v106
	v_log_f32_e32 v97, v97
	v_rcp_f32_e32 v77, v77
	v_mul_f32_e32 v78, 0xbfb8aa3b, v78
	v_exp_f32_e32 v78, v78
	v_mul_f32_e32 v106, 0x3f317217, v97
	v_fma_f32 v106, v97, s87, -v106
	v_fmac_f32_e32 v106, 0x3377d1cf, v97
	v_fmac_f32_e32 v106, 0x3f317217, v97
	v_cmp_lt_f32_e64 s[6:7], |v97|, s88
	v_fma_f32 v77, v77, v125, v157
	v_add_f32_e32 v78, 1.0, v78
	v_cndmask_b32_e64 v97, v97, v106, s[6:7]
	v_cndmask_b32_e32 v106, 0, v174, vcc
	v_cmp_gt_f32_e32 vcc, s86, v98
	v_sub_f32_e32 v97, v97, v106
	v_rcp_f32_e32 v78, v78
	v_cndmask_b32_e64 v106, 0, 32, vcc
	v_ldexp_f32 v98, v98, v106
	v_log_f32_e32 v98, v98
	v_fma_f32 v78, v78, v126, v156
	v_mul_f32_e32 v79, 0xbfb8aa3b, v79
	v_exp_f32_e32 v79, v79
	v_mul_f32_e32 v106, 0x3f317217, v98
	v_fma_f32 v106, v98, s87, -v106
	v_fmac_f32_e32 v106, 0x3377d1cf, v98
	v_fmac_f32_e32 v106, 0x3f317217, v98
	v_cmp_lt_f32_e64 s[6:7], |v98|, s88
	v_add_f32_e32 v79, 1.0, v79
	v_rcp_f32_e32 v79, v79
	v_cndmask_b32_e64 v98, v98, v106, s[6:7]
	v_cndmask_b32_e32 v106, 0, v174, vcc
	v_cmp_gt_f32_e32 vcc, s86, v99
	v_sub_f32_e32 v98, v98, v106
	v_fma_f32 v79, v79, v127, v155
	v_cndmask_b32_e64 v106, 0, 32, vcc
	v_ldexp_f32 v99, v99, v106
	v_log_f32_e32 v99, v99
	v_mul_f32_e32 v72, 0xbfb8aa3b, v72
	v_exp_f32_e32 v72, v72
	v_mul_f32_e32 v73, 0xbfb8aa3b, v73
	v_mul_f32_e32 v106, 0x3f317217, v99
	v_fma_f32 v106, v99, s87, -v106
	v_fmac_f32_e32 v106, 0x3377d1cf, v99
	v_fmac_f32_e32 v106, 0x3f317217, v99
	v_cmp_lt_f32_e64 s[6:7], |v99|, s88
	v_add_f32_e32 v72, 1.0, v72
	v_rcp_f32_e32 v72, v72
	v_cndmask_b32_e64 v99, v99, v106, s[6:7]
	v_cndmask_b32_e32 v106, 0, v174, vcc
	v_sub_f32_e32 v99, v99, v106
	v_cvt_pk_f16_f32 v99, v98, v99
	v_cvt_pk_f16_f32 v98, v96, v97
	v_cvt_pk_f16_f32 v97, v102, v103
	v_cvt_pk_f16_f32 v96, v100, v101
	v_cmp_gt_f32_e32 vcc, s86, v92
	global_store_dwordx4 v[104:105], v[96:99], off offset:-2048
	s_mov_b64 s[6:7], 0x40000
	v_fma_f32 v72, v72, v160, v154
	v_cndmask_b32_e64 v98, 0, 32, vcc
	v_ldexp_f32 v92, v92, v98
	v_log_f32_e32 v92, v92
	v_lshl_add_u64 v[96:97], v[148:149], 0, s[6:7]
	v_exp_f32_e32 v73, v73
	v_mul_f32_e32 v74, 0xbfb8aa3b, v74
	v_mul_f32_e32 v98, 0x3f317217, v92
	v_fma_f32 v98, v92, s87, -v98
	v_fmac_f32_e32 v98, 0x3377d1cf, v92
	v_fmac_f32_e32 v98, 0x3f317217, v92
	v_cmp_lt_f32_e64 s[6:7], |v92|, s88
	v_add_f32_e32 v73, 1.0, v73
	v_rcp_f32_e32 v73, v73
	v_cndmask_b32_e64 v92, v92, v98, s[6:7]
	v_cndmask_b32_e32 v98, 0, v174, vcc
	v_cmp_gt_f32_e32 vcc, s86, v93
	v_sub_f32_e32 v92, v92, v98
	v_fma_f32 v73, v73, v147, v153
	v_cndmask_b32_e64 v98, 0, 32, vcc
	v_ldexp_f32 v93, v93, v98
	v_log_f32_e32 v93, v93
	v_exp_f32_e32 v74, v74
	v_mul_f32_e32 v75, 0xbfb8aa3b, v75
	v_exp_f32_e32 v75, v75
	v_mul_f32_e32 v98, 0x3f317217, v93
	v_fma_f32 v98, v93, s87, -v98
	v_fmac_f32_e32 v98, 0x3377d1cf, v93
	v_fmac_f32_e32 v98, 0x3f317217, v93
	v_cmp_lt_f32_e64 s[6:7], |v93|, s88
	v_add_f32_e32 v74, 1.0, v74
	v_rcp_f32_e32 v74, v74
	v_cndmask_b32_e64 v93, v93, v98, s[6:7]
	v_cndmask_b32_e32 v98, 0, v174, vcc
	v_cmp_gt_f32_e32 vcc, s86, v94
	v_sub_f32_e32 v93, v93, v98
	v_fma_f32 v74, v74, v159, v152
	v_cndmask_b32_e64 v98, 0, 32, vcc
	v_ldexp_f32 v94, v94, v98
	v_log_f32_e32 v94, v94
	v_add_f32_e32 v75, 1.0, v75
	v_rcp_f32_e32 v75, v75
	v_mul_f32_e32 v68, 0xbfb8aa3b, v68
	v_mul_f32_e32 v98, 0x3f317217, v94
	v_fma_f32 v98, v94, s87, -v98
	v_fmac_f32_e32 v98, 0x3377d1cf, v94
	v_fmac_f32_e32 v98, 0x3f317217, v94
	v_cmp_lt_f32_e64 s[6:7], |v94|, s88
	v_fma_f32 v75, v75, v122, v151
	v_exp_f32_e32 v68, v68
	v_cndmask_b32_e64 v94, v94, v98, s[6:7]
	v_cndmask_b32_e32 v98, 0, v174, vcc
	v_cmp_gt_f32_e32 vcc, s86, v95
	v_sub_f32_e32 v94, v94, v98
	v_add_f32_e32 v68, 1.0, v68
	v_cndmask_b32_e64 v98, 0, 32, vcc
	v_ldexp_f32 v95, v95, v98
	v_log_f32_e32 v95, v95
	v_rcp_f32_e32 v68, v68
	v_mul_f32_e32 v69, 0xbfb8aa3b, v69
	v_exp_f32_e32 v69, v69
	v_mul_f32_e32 v98, 0x3f317217, v95
	v_fma_f32 v98, v95, s87, -v98
	v_fmac_f32_e32 v98, 0x3377d1cf, v95
	v_fmac_f32_e32 v98, 0x3f317217, v95
	v_cmp_lt_f32_e64 s[6:7], |v95|, s88
	v_fmac_f32_e32 v158, v68, v124
	v_add_f32_e32 v69, 1.0, v69
	v_cndmask_b32_e64 v95, v95, v98, s[6:7]
	v_cndmask_b32_e32 v98, 0, v174, vcc
	v_cmp_gt_f32_e32 vcc, s86, v88
	v_sub_f32_e32 v95, v95, v98
	v_rcp_f32_e32 v69, v69
	v_cndmask_b32_e64 v98, 0, 32, vcc
	v_ldexp_f32 v88, v88, v98
	v_log_f32_e32 v88, v88
	v_fmac_f32_e32 v157, v69, v125
	v_mul_f32_e32 v70, 0xbfb8aa3b, v70
	v_exp_f32_e32 v70, v70
	v_mul_f32_e32 v98, 0x3f317217, v88
	v_fma_f32 v98, v88, s87, -v98
	v_fmac_f32_e32 v98, 0x3377d1cf, v88
	v_fmac_f32_e32 v98, 0x3f317217, v88
	v_cmp_lt_f32_e64 s[6:7], |v88|, s88
	v_add_f32_e32 v70, 1.0, v70
	v_rcp_f32_e32 v70, v70
	v_cndmask_b32_e64 v88, v88, v98, s[6:7]
	v_cndmask_b32_e32 v98, 0, v174, vcc
	v_cmp_gt_f32_e32 vcc, s86, v89
	v_sub_f32_e32 v88, v88, v98
	v_fmac_f32_e32 v156, v70, v126
	v_cndmask_b32_e64 v98, 0, 32, vcc
	v_ldexp_f32 v89, v89, v98
	v_log_f32_e32 v89, v89
	v_mul_f32_e32 v71, 0xbfb8aa3b, v71
	v_exp_f32_e32 v71, v71
	v_mul_f32_e32 v64, 0xbfb8aa3b, v64
	v_mul_f32_e32 v98, 0x3f317217, v89
	v_fma_f32 v98, v89, s87, -v98
	v_fmac_f32_e32 v98, 0x3377d1cf, v89
	v_fmac_f32_e32 v98, 0x3f317217, v89
	v_cmp_lt_f32_e64 s[6:7], |v89|, s88
	v_add_f32_e32 v71, 1.0, v71
	v_rcp_f32_e32 v71, v71
	v_cndmask_b32_e64 v89, v89, v98, s[6:7]
	v_cndmask_b32_e32 v98, 0, v174, vcc
	v_cmp_gt_f32_e32 vcc, s86, v90
	v_sub_f32_e32 v89, v89, v98
	v_fmac_f32_e32 v155, v71, v127
	v_cndmask_b32_e64 v98, 0, 32, vcc
	v_ldexp_f32 v90, v90, v98
	v_log_f32_e32 v90, v90
	v_exp_f32_e32 v64, v64
	v_mul_f32_e32 v65, 0xbfb8aa3b, v65
	v_exp_f32_e32 v65, v65
	v_mul_f32_e32 v98, 0x3f317217, v90
	v_fma_f32 v98, v90, s87, -v98
	v_fmac_f32_e32 v98, 0x3377d1cf, v90
	v_fmac_f32_e32 v98, 0x3f317217, v90
	v_cmp_lt_f32_e64 s[6:7], |v90|, s88
	v_add_f32_e32 v64, 1.0, v64
	v_rcp_f32_e32 v64, v64
	v_cndmask_b32_e64 v90, v90, v98, s[6:7]
	v_cndmask_b32_e32 v98, 0, v174, vcc
	v_cmp_gt_f32_e32 vcc, s86, v91
	v_sub_f32_e32 v90, v90, v98
	v_fmac_f32_e32 v154, v64, v160
	v_cndmask_b32_e64 v98, 0, 32, vcc
	v_ldexp_f32 v91, v91, v98
	v_log_f32_e32 v91, v91
	v_add_f32_e32 v65, 1.0, v65
	v_rcp_f32_e32 v65, v65
	v_mul_f32_e32 v66, 0xbfb8aa3b, v66
	v_mul_f32_e32 v98, 0x3f317217, v91
	v_fma_f32 v98, v91, s87, -v98
	v_fmac_f32_e32 v98, 0x3377d1cf, v91
	v_fmac_f32_e32 v98, 0x3f317217, v91
	v_cmp_lt_f32_e64 s[6:7], |v91|, s88
	v_fmac_f32_e32 v153, v65, v147
	v_exp_f32_e32 v66, v66
	v_cndmask_b32_e64 v91, v91, v98, s[6:7]
	v_cndmask_b32_e32 v98, 0, v174, vcc
	v_sub_f32_e32 v91, v91, v98
	v_cvt_pk_f16_f32 v91, v90, v91
	v_cvt_pk_f16_f32 v90, v88, v89
	v_cvt_pk_f16_f32 v89, v94, v95
	v_cvt_pk_f16_f32 v88, v92, v93
	v_cmp_gt_f32_e32 vcc, s86, v84
	global_store_dwordx4 v[96:97], v[88:91], off offset:-2048
	s_mov_b64 s[6:7], 0x48000
	v_add_f32_e32 v66, 1.0, v66
	v_cndmask_b32_e64 v90, 0, 32, vcc
	v_ldexp_f32 v84, v84, v90
	v_log_f32_e32 v84, v84
	v_lshl_add_u64 v[88:89], v[148:149], 0, s[6:7]
	v_rcp_f32_e32 v66, v66
	v_mul_f32_e32 v67, 0xbfb8aa3b, v67
	v_mul_f32_e32 v90, 0x3f317217, v84
	v_fma_f32 v90, v84, s87, -v90
	v_fmac_f32_e32 v90, 0x3377d1cf, v84
	v_fmac_f32_e32 v90, 0x3f317217, v84
	v_cmp_lt_f32_e64 s[6:7], |v84|, s88
	v_fmac_f32_e32 v152, v66, v159
	v_exp_f32_e32 v67, v67
	v_cndmask_b32_e64 v84, v84, v90, s[6:7]
	v_cndmask_b32_e32 v90, 0, v174, vcc
	v_cmp_gt_f32_e32 vcc, s86, v85
	v_sub_f32_e32 v84, v84, v90
	v_add_f32_e32 v67, 1.0, v67
	v_cndmask_b32_e64 v90, 0, 32, vcc
	v_ldexp_f32 v85, v85, v90
	v_log_f32_e32 v85, v85
	v_rcp_f32_e32 v67, v67
	s_movk_i32 s0, 0x1f8
	v_cvt_pk_f16_f32 v163, v163, v176
	v_mul_f32_e32 v90, 0x3f317217, v85
	v_fma_f32 v90, v85, s87, -v90
	v_fmac_f32_e32 v90, 0x3377d1cf, v85
	v_fmac_f32_e32 v90, 0x3f317217, v85
	v_cmp_lt_f32_e64 s[6:7], |v85|, s88
	v_fmac_f32_e32 v151, v67, v122
	v_cvt_pk_f16_f32 v162, v161, v162
	v_cndmask_b32_e64 v85, v85, v90, s[6:7]
	v_cndmask_b32_e32 v90, 0, v174, vcc
	v_cmp_gt_f32_e32 vcc, s86, v86
	v_sub_f32_e32 v85, v85, v90
	global_store_dwordx4 v[148:149], v[162:165], off offset:-2048
	v_cndmask_b32_e64 v90, 0, 32, vcc
	v_ldexp_f32 v86, v86, v90
	v_log_f32_e32 v86, v86
	v_mul_f32_e32 v60, 0xbfb8aa3b, v60
	v_exp_f32_e32 v60, v60
	v_mul_f32_e32 v56, 0xbfb8aa3b, v56
	v_mul_f32_e32 v90, 0x3f317217, v86
	v_fma_f32 v90, v86, s87, -v90
	v_fmac_f32_e32 v90, 0x3377d1cf, v86
	v_fmac_f32_e32 v90, 0x3f317217, v86
	v_cmp_lt_f32_e64 s[6:7], |v86|, s88
	v_add_f32_e32 v60, 1.0, v60
	v_rcp_f32_e32 v60, v60
	v_cndmask_b32_e64 v86, v86, v90, s[6:7]
	v_cndmask_b32_e32 v90, 0, v174, vcc
	v_cmp_gt_f32_e32 vcc, s86, v87
	v_sub_f32_e32 v86, v86, v90
	v_exp_f32_e32 v56, v56
	v_cndmask_b32_e64 v90, 0, 32, vcc
	v_ldexp_f32 v87, v87, v90
	v_log_f32_e32 v87, v87
	v_add_f32_e32 v56, 1.0, v56
	v_rcp_f32_e32 v56, v56
	v_mul_f32_e32 v52, 0xbfb8aa3b, v52
	v_mul_f32_e32 v90, 0x3f317217, v87
	v_fma_f32 v90, v87, s87, -v90
	v_fmac_f32_e32 v90, 0x3377d1cf, v87
	v_fmac_f32_e32 v90, 0x3f317217, v87
	v_cmp_lt_f32_e64 s[6:7], |v87|, s88
	v_exp_f32_e32 v52, v52
	v_mul_f32_e32 v53, 0xbfb8aa3b, v53
	v_cndmask_b32_e64 v87, v87, v90, s[6:7]
	v_cndmask_b32_e32 v90, 0, v174, vcc
	v_cmp_gt_f32_e32 vcc, s86, v80
	v_sub_f32_e32 v87, v87, v90
	v_add_f32_e32 v52, 1.0, v52
	v_cndmask_b32_e64 v90, 0, 32, vcc
	v_ldexp_f32 v80, v80, v90
	v_log_f32_e32 v80, v80
	v_rcp_f32_e32 v52, v52
	v_exp_f32_e32 v53, v53
	v_mul_f32_e32 v54, 0xbfb8aa3b, v54
	v_mul_f32_e32 v90, 0x3f317217, v80
	v_fma_f32 v90, v80, s87, -v90
	v_fmac_f32_e32 v90, 0x3377d1cf, v80
	v_fmac_f32_e32 v90, 0x3f317217, v80
	v_cmp_lt_f32_e64 s[6:7], |v80|, s88
	v_add_f32_e32 v53, 1.0, v53
	v_rcp_f32_e32 v53, v53
	v_cndmask_b32_e64 v80, v80, v90, s[6:7]
	v_cndmask_b32_e32 v90, 0, v174, vcc
	v_cmp_gt_f32_e32 vcc, s86, v81
	v_sub_f32_e32 v80, v80, v90
	v_exp_f32_e32 v54, v54
	v_cndmask_b32_e64 v90, 0, 32, vcc
	v_ldexp_f32 v81, v81, v90
	v_log_f32_e32 v81, v81
	v_add_f32_e32 v54, 1.0, v54
	v_rcp_f32_e32 v54, v54
	v_mul_f32_e32 v55, 0xbfb8aa3b, v55
	v_mul_f32_e32 v90, 0x3f317217, v81
	v_fma_f32 v90, v81, s87, -v90
	v_fmac_f32_e32 v90, 0x3377d1cf, v81
	v_fmac_f32_e32 v90, 0x3f317217, v81
	v_cmp_lt_f32_e64 s[6:7], |v81|, s88
	v_exp_f32_e32 v55, v55
	v_mul_f32_e32 v48, 0xbfb8aa3b, v48
	v_cndmask_b32_e64 v81, v81, v90, s[6:7]
	v_cndmask_b32_e32 v90, 0, v174, vcc
	v_cmp_gt_f32_e32 vcc, s86, v82
	v_sub_f32_e32 v81, v81, v90
	v_add_f32_e32 v55, 1.0, v55
	v_cndmask_b32_e64 v90, 0, 32, vcc
	v_ldexp_f32 v82, v82, v90
	v_log_f32_e32 v82, v82
	v_rcp_f32_e32 v55, v55
	v_exp_f32_e32 v48, v48
	v_mul_f32_e32 v49, 0xbfb8aa3b, v49
	v_mul_f32_e32 v90, 0x3f317217, v82
	v_fma_f32 v90, v82, s87, -v90
	v_fmac_f32_e32 v90, 0x3377d1cf, v82
	v_fmac_f32_e32 v90, 0x3f317217, v82
	v_cmp_lt_f32_e64 s[6:7], |v82|, s88
	v_add_f32_e32 v48, 1.0, v48
	v_rcp_f32_e32 v48, v48
	v_cndmask_b32_e64 v82, v82, v90, s[6:7]
	v_cndmask_b32_e32 v90, 0, v174, vcc
	v_cmp_gt_f32_e32 vcc, s86, v83
	v_sub_f32_e32 v82, v82, v90
	v_exp_f32_e32 v49, v49
	v_cndmask_b32_e64 v90, 0, 32, vcc
	v_ldexp_f32 v83, v83, v90
	v_log_f32_e32 v83, v83
	v_add_f32_e32 v49, 1.0, v49
	v_rcp_f32_e32 v49, v49
	v_mul_f32_e32 v50, 0xbfb8aa3b, v50
	v_mul_f32_e32 v90, 0x3f317217, v83
	v_fma_f32 v90, v83, s87, -v90
	v_fmac_f32_e32 v90, 0x3377d1cf, v83
	v_fmac_f32_e32 v90, 0x3f317217, v83
	v_cmp_lt_f32_e64 s[6:7], |v83|, s88
	v_exp_f32_e32 v50, v50
	v_mul_f32_e32 v51, 0xbfb8aa3b, v51
	v_cndmask_b32_e64 v83, v83, v90, s[6:7]
	v_cndmask_b32_e32 v90, 0, v174, vcc
	v_sub_f32_e32 v83, v83, v90
	v_cvt_pk_f16_f32 v83, v82, v83
	v_cvt_pk_f16_f32 v82, v80, v81
	v_cvt_pk_f16_f32 v81, v86, v87
	v_cvt_pk_f16_f32 v80, v84, v85
	v_cmp_gt_f32_e32 vcc, s86, v76
	global_store_dwordx4 v[88:89], v[80:83], off offset:-2048
	s_mov_b64 s[6:7], 0x50000
	v_add_f32_e32 v50, 1.0, v50
	v_cndmask_b32_e64 v82, 0, 32, vcc
	v_ldexp_f32 v76, v76, v82
	v_log_f32_e32 v76, v76
	v_lshl_add_u64 v[80:81], v[148:149], 0, s[6:7]
	v_rcp_f32_e32 v50, v50
	v_exp_f32_e32 v51, v51
	v_mul_f32_e32 v82, 0x3f317217, v76
	v_fma_f32 v82, v76, s87, -v82
	v_fmac_f32_e32 v82, 0x3377d1cf, v76
	v_fmac_f32_e32 v82, 0x3f317217, v76
	v_cmp_lt_f32_e64 s[6:7], |v76|, s88
	v_add_f32_e32 v51, 1.0, v51
	v_rcp_f32_e32 v51, v51
	v_cndmask_b32_e64 v76, v76, v82, s[6:7]
	v_cndmask_b32_e32 v82, 0, v174, vcc
	v_cmp_gt_f32_e32 vcc, s86, v77
	v_sub_f32_e32 v76, v76, v82
	v_mul_f32_e32 v44, 0xbfb8aa3b, v44
	v_cndmask_b32_e64 v82, 0, 32, vcc
	v_ldexp_f32 v77, v77, v82
	v_log_f32_e32 v77, v77
	v_exp_f32_e32 v44, v44
	v_mul_f32_e32 v45, 0xbfb8aa3b, v45
	v_exp_f32_e32 v45, v45
	v_mul_f32_e32 v82, 0x3f317217, v77
	v_fma_f32 v82, v77, s87, -v82
	v_fmac_f32_e32 v82, 0x3377d1cf, v77
	v_fmac_f32_e32 v82, 0x3f317217, v77
	v_cmp_lt_f32_e64 s[6:7], |v77|, s88
	v_add_f32_e32 v44, 1.0, v44
	v_rcp_f32_e32 v44, v44
	v_cndmask_b32_e64 v77, v77, v82, s[6:7]
	v_cndmask_b32_e32 v82, 0, v174, vcc
	v_cmp_gt_f32_e32 vcc, s86, v78
	v_sub_f32_e32 v77, v77, v82
	v_add_f32_e32 v45, 1.0, v45
	v_cndmask_b32_e64 v82, 0, 32, vcc
	v_ldexp_f32 v78, v78, v82
	v_log_f32_e32 v78, v78
	v_rcp_f32_e32 v45, v45
	v_mul_f32_e32 v46, 0xbfb8aa3b, v46
	v_exp_f32_e32 v46, v46
	v_mul_f32_e32 v82, 0x3f317217, v78
	v_fma_f32 v82, v78, s87, -v82
	v_fmac_f32_e32 v82, 0x3377d1cf, v78
	v_fmac_f32_e32 v82, 0x3f317217, v78
	v_cmp_lt_f32_e64 s[6:7], |v78|, s88
	v_add_f32_e32 v46, 1.0, v46
	v_rcp_f32_e32 v46, v46
	v_cndmask_b32_e64 v78, v78, v82, s[6:7]
	v_cndmask_b32_e32 v82, 0, v174, vcc
	v_cmp_gt_f32_e32 vcc, s86, v79
	v_sub_f32_e32 v78, v78, v82
	v_mul_f32_e32 v47, 0xbfb8aa3b, v47
	v_cndmask_b32_e64 v82, 0, 32, vcc
	v_ldexp_f32 v79, v79, v82
	v_log_f32_e32 v79, v79
	v_exp_f32_e32 v47, v47
	v_mul_f32_e32 v40, 0xbfb8aa3b, v40
	v_exp_f32_e32 v40, v40
	v_mul_f32_e32 v82, 0x3f317217, v79
	v_fma_f32 v82, v79, s87, -v82
	v_fmac_f32_e32 v82, 0x3377d1cf, v79
	v_fmac_f32_e32 v82, 0x3f317217, v79
	v_cmp_lt_f32_e64 s[6:7], |v79|, s88
	v_add_f32_e32 v47, 1.0, v47
	v_rcp_f32_e32 v47, v47
	v_cndmask_b32_e64 v79, v79, v82, s[6:7]
	v_cndmask_b32_e32 v82, 0, v174, vcc
	v_cmp_gt_f32_e32 vcc, s86, v72
	v_sub_f32_e32 v79, v79, v82
	v_add_f32_e32 v40, 1.0, v40
	v_cndmask_b32_e64 v82, 0, 32, vcc
	v_ldexp_f32 v72, v72, v82
	v_log_f32_e32 v72, v72
	v_rcp_f32_e32 v40, v40
	v_mul_f32_e32 v41, 0xbfb8aa3b, v41
	v_exp_f32_e32 v41, v41
	v_mul_f32_e32 v82, 0x3f317217, v72
	v_fma_f32 v82, v72, s87, -v82
	v_fmac_f32_e32 v82, 0x3377d1cf, v72
	v_fmac_f32_e32 v82, 0x3f317217, v72
	v_cmp_lt_f32_e64 s[6:7], |v72|, s88
	v_add_f32_e32 v41, 1.0, v41
	v_rcp_f32_e32 v41, v41
	v_cndmask_b32_e64 v72, v72, v82, s[6:7]
	v_cndmask_b32_e32 v82, 0, v174, vcc
	v_cmp_gt_f32_e32 vcc, s86, v73
	v_sub_f32_e32 v72, v72, v82
	v_mul_f32_e32 v42, 0xbfb8aa3b, v42
	v_cndmask_b32_e64 v82, 0, 32, vcc
	v_ldexp_f32 v73, v73, v82
	v_log_f32_e32 v73, v73
	v_exp_f32_e32 v42, v42
	v_mul_f32_e32 v43, 0xbfb8aa3b, v43
	v_exp_f32_e32 v43, v43
	v_mul_f32_e32 v82, 0x3f317217, v73
	v_fma_f32 v82, v73, s87, -v82
	v_fmac_f32_e32 v82, 0x3377d1cf, v73
	v_fmac_f32_e32 v82, 0x3f317217, v73
	v_cmp_lt_f32_e64 s[6:7], |v73|, s88
	v_add_f32_e32 v42, 1.0, v42
	v_rcp_f32_e32 v42, v42
	v_cndmask_b32_e64 v73, v73, v82, s[6:7]
	v_cndmask_b32_e32 v82, 0, v174, vcc
	v_cmp_gt_f32_e32 vcc, s86, v74
	v_sub_f32_e32 v73, v73, v82
	v_add_f32_e32 v43, 1.0, v43
	v_cndmask_b32_e64 v82, 0, 32, vcc
	v_ldexp_f32 v74, v74, v82
	v_log_f32_e32 v74, v74
	v_rcp_f32_e32 v43, v43
	v_mul_f32_e32 v36, 0xbfb8aa3b, v36
	v_exp_f32_e32 v36, v36
	v_mul_f32_e32 v82, 0x3f317217, v74
	v_fma_f32 v82, v74, s87, -v82
	v_fmac_f32_e32 v82, 0x3377d1cf, v74
	v_fmac_f32_e32 v82, 0x3f317217, v74
	v_cmp_lt_f32_e64 s[6:7], |v74|, s88
	v_add_f32_e32 v36, 1.0, v36
	v_rcp_f32_e32 v36, v36
	v_cndmask_b32_e64 v74, v74, v82, s[6:7]
	v_cndmask_b32_e32 v82, 0, v174, vcc
	v_cmp_gt_f32_e32 vcc, s86, v75
	v_sub_f32_e32 v74, v74, v82
	v_mul_f32_e32 v37, 0xbfb8aa3b, v37
	v_cndmask_b32_e64 v82, 0, 32, vcc
	v_ldexp_f32 v75, v75, v82
	v_log_f32_e32 v75, v75
	v_exp_f32_e32 v37, v37
	v_mul_f32_e32 v38, 0xbfb8aa3b, v38
	v_exp_f32_e32 v38, v38
	v_mul_f32_e32 v82, 0x3f317217, v75
	v_fma_f32 v82, v75, s87, -v82
	v_fmac_f32_e32 v82, 0x3377d1cf, v75
	v_fmac_f32_e32 v82, 0x3f317217, v75
	v_cmp_lt_f32_e64 s[6:7], |v75|, s88
	v_add_f32_e32 v37, 1.0, v37
	v_rcp_f32_e32 v37, v37
	v_cndmask_b32_e64 v75, v75, v82, s[6:7]
	v_cndmask_b32_e32 v82, 0, v174, vcc
	v_cmp_gt_f32_e32 vcc, s86, v158
	v_sub_f32_e32 v75, v75, v82
	v_cvt_pk_f16_f32 v75, v74, v75
	v_cndmask_b32_e64 v68, 0, 32, vcc
	v_ldexp_f32 v68, v158, v68
	v_log_f32_e32 v68, v68
	v_cvt_pk_f16_f32 v74, v72, v73
	v_cvt_pk_f16_f32 v73, v78, v79
	v_cvt_pk_f16_f32 v72, v76, v77
	global_store_dwordx4 v[80:81], v[72:75], off offset:-2048
	s_mov_b64 s[6:7], 0x58000
	v_add_f32_e32 v38, 1.0, v38
	v_mul_f32_e32 v74, 0x3f317217, v68
	v_fma_f32 v74, v68, s87, -v74
	v_fmac_f32_e32 v74, 0x3377d1cf, v68
	v_lshl_add_u64 v[72:73], v[148:149], 0, s[6:7]
	v_fmac_f32_e32 v74, 0x3f317217, v68
	v_cmp_lt_f32_e64 s[6:7], |v68|, s88
	v_rcp_f32_e32 v38, v38
	v_mul_f32_e32 v39, 0xbfb8aa3b, v39
	v_cndmask_b32_e64 v68, v68, v74, s[6:7]
	v_cndmask_b32_e32 v74, 0, v174, vcc
	v_cmp_gt_f32_e32 vcc, s86, v157
	v_sub_f32_e32 v68, v68, v74
	v_exp_f32_e32 v39, v39
	v_cndmask_b32_e64 v69, 0, 32, vcc
	v_ldexp_f32 v69, v157, v69
	v_log_f32_e32 v69, v69
	v_add_f32_e32 v39, 1.0, v39
	v_rcp_f32_e32 v39, v39
	v_mul_f32_e32 v32, 0xbfb8aa3b, v32
	v_mul_f32_e32 v74, 0x3f317217, v69
	v_fma_f32 v74, v69, s87, -v74
	v_fmac_f32_e32 v74, 0x3377d1cf, v69
	v_fmac_f32_e32 v74, 0x3f317217, v69
	v_cmp_lt_f32_e64 s[6:7], |v69|, s88
	v_exp_f32_e32 v32, v32
	v_mul_f32_e32 v33, 0xbfb8aa3b, v33
	v_cndmask_b32_e64 v69, v69, v74, s[6:7]
	v_cndmask_b32_e32 v74, 0, v174, vcc
	v_cmp_gt_f32_e32 vcc, s86, v156
	v_sub_f32_e32 v69, v69, v74
	v_add_f32_e32 v32, 1.0, v32
	v_cndmask_b32_e64 v70, 0, 32, vcc
	v_ldexp_f32 v70, v156, v70
	v_log_f32_e32 v70, v70
	v_rcp_f32_e32 v32, v32
	v_exp_f32_e32 v33, v33
	v_mul_f32_e32 v34, 0xbfb8aa3b, v34
	v_mul_f32_e32 v74, 0x3f317217, v70
	v_fma_f32 v74, v70, s87, -v74
	v_fmac_f32_e32 v74, 0x3377d1cf, v70
	v_fmac_f32_e32 v74, 0x3f317217, v70
	v_cmp_lt_f32_e64 s[6:7], |v70|, s88
	v_add_f32_e32 v33, 1.0, v33
	v_rcp_f32_e32 v33, v33
	v_cndmask_b32_e64 v70, v70, v74, s[6:7]
	v_cndmask_b32_e32 v74, 0, v174, vcc
	v_cmp_gt_f32_e32 vcc, s86, v155
	v_sub_f32_e32 v70, v70, v74
	v_exp_f32_e32 v34, v34
	v_cndmask_b32_e64 v71, 0, 32, vcc
	v_ldexp_f32 v71, v155, v71
	v_log_f32_e32 v71, v71
	v_add_f32_e32 v34, 1.0, v34
	v_rcp_f32_e32 v34, v34
	v_mul_f32_e32 v35, 0xbfb8aa3b, v35
	v_mul_f32_e32 v74, 0x3f317217, v71
	v_fma_f32 v74, v71, s87, -v74
	v_fmac_f32_e32 v74, 0x3377d1cf, v71
	v_fmac_f32_e32 v74, 0x3f317217, v71
	v_cmp_lt_f32_e64 s[6:7], |v71|, s88
	v_exp_f32_e32 v35, v35
	v_mul_f32_e32 v28, 0xbfb8aa3b, v28
	v_cndmask_b32_e64 v71, v71, v74, s[6:7]
	v_cndmask_b32_e32 v74, 0, v174, vcc
	v_cmp_gt_f32_e32 vcc, s86, v154
	v_sub_f32_e32 v71, v71, v74
	v_add_f32_e32 v35, 1.0, v35
	v_cndmask_b32_e64 v64, 0, 32, vcc
	v_ldexp_f32 v64, v154, v64
	v_log_f32_e32 v64, v64
	v_rcp_f32_e32 v35, v35
	v_exp_f32_e32 v28, v28
	v_mul_f32_e32 v29, 0xbfb8aa3b, v29
	v_mul_f32_e32 v74, 0x3f317217, v64
	v_fma_f32 v74, v64, s87, -v74
	v_fmac_f32_e32 v74, 0x3377d1cf, v64
	v_fmac_f32_e32 v74, 0x3f317217, v64
	v_cmp_lt_f32_e64 s[6:7], |v64|, s88
	v_add_f32_e32 v28, 1.0, v28
	v_rcp_f32_e32 v28, v28
	v_cndmask_b32_e64 v64, v64, v74, s[6:7]
	v_cndmask_b32_e32 v74, 0, v174, vcc
	v_cmp_gt_f32_e32 vcc, s86, v153
	v_sub_f32_e32 v64, v64, v74
	v_exp_f32_e32 v29, v29
	v_cndmask_b32_e64 v65, 0, 32, vcc
	v_ldexp_f32 v65, v153, v65
	v_log_f32_e32 v65, v65
	v_add_f32_e32 v29, 1.0, v29
	v_rcp_f32_e32 v29, v29
	v_mul_f32_e32 v30, 0xbfb8aa3b, v30
	v_mul_f32_e32 v74, 0x3f317217, v65
	v_fma_f32 v74, v65, s87, -v74
	v_fmac_f32_e32 v74, 0x3377d1cf, v65
	v_fmac_f32_e32 v74, 0x3f317217, v65
	v_cmp_lt_f32_e64 s[6:7], |v65|, s88
	v_exp_f32_e32 v30, v30
	v_mul_f32_e32 v31, 0xbfb8aa3b, v31
	v_cndmask_b32_e64 v65, v65, v74, s[6:7]
	v_cndmask_b32_e32 v74, 0, v174, vcc
	v_cmp_gt_f32_e32 vcc, s86, v152
	v_sub_f32_e32 v65, v65, v74
	v_add_f32_e32 v30, 1.0, v30
	v_cndmask_b32_e64 v66, 0, 32, vcc
	v_ldexp_f32 v66, v152, v66
	v_log_f32_e32 v66, v66
	v_rcp_f32_e32 v30, v30
	v_exp_f32_e32 v31, v31
	v_mul_f32_e32 v24, 0xbfb8aa3b, v24
	v_mul_f32_e32 v74, 0x3f317217, v66
	v_fma_f32 v74, v66, s87, -v74
	v_fmac_f32_e32 v74, 0x3377d1cf, v66
	v_fmac_f32_e32 v74, 0x3f317217, v66
	v_cmp_lt_f32_e64 s[6:7], |v66|, s88
	v_add_f32_e32 v31, 1.0, v31
	v_rcp_f32_e32 v31, v31
	v_cndmask_b32_e64 v66, v66, v74, s[6:7]
	v_cndmask_b32_e32 v74, 0, v174, vcc
	v_cmp_gt_f32_e32 vcc, s86, v151
	v_sub_f32_e32 v66, v66, v74
	v_exp_f32_e32 v24, v24
	v_cndmask_b32_e64 v67, 0, 32, vcc
	v_ldexp_f32 v67, v151, v67
	v_log_f32_e32 v67, v67
	v_add_f32_e32 v24, 1.0, v24
	v_rcp_f32_e32 v24, v24
	v_mul_f32_e32 v25, 0xbfb8aa3b, v25
	v_mul_f32_e32 v74, 0x3f317217, v67
	v_fma_f32 v74, v67, s87, -v74
	v_fmac_f32_e32 v74, 0x3377d1cf, v67
	v_fmac_f32_e32 v74, 0x3f317217, v67
	v_cmp_lt_f32_e64 s[6:7], |v67|, s88
	v_exp_f32_e32 v25, v25
	v_mul_f32_e32 v26, 0xbfb8aa3b, v26
	v_cndmask_b32_e64 v67, v67, v74, s[6:7]
	v_cndmask_b32_e32 v74, 0, v174, vcc
	v_sub_f32_e32 v67, v67, v74
	v_cvt_pk_f16_f32 v67, v66, v67
	v_cvt_pk_f16_f32 v66, v64, v65
	v_cvt_pk_f16_f32 v65, v70, v71
	v_cvt_pk_f16_f32 v64, v68, v69
	global_store_dwordx4 v[72:73], v[64:67], off offset:-2048
	v_add_f32_e32 v25, 1.0, v25
	v_rcp_f32_e32 v25, v25
.Lhvy_join1:
	v_bitop3_b32 v64, v150, s0, v175 bitop3:0xc8
	v_lshlrev_b32_e32 v68, 2, v64
	global_load_dwordx4 v[74:77], v68, s[58:59] offset:2064
	global_load_dwordx4 v[64:67], v68, s[58:59] offset:2048
	global_load_dwordx4 v[82:85], v68, s[58:59] offset:16
	global_load_dwordx4 v[90:93], v68, s[58:59]
	v_exp_f32_e32 v26, v26
	v_mul_f32_e32 v27, 0xbfb8aa3b, v27
	v_exp_f32_e32 v27, v27
	v_mul_f32_e32 v20, 0xbfb8aa3b, v20
	v_add_f32_e32 v26, 1.0, v26
	v_rcp_f32_e32 v26, v26
	v_add_f32_e32 v27, 1.0, v27
	v_rcp_f32_e32 v27, v27
	v_exp_f32_e32 v20, v20
	v_mul_f32_e32 v21, 0xbfb8aa3b, v21
	v_exp_f32_e32 v21, v21
	v_mul_f32_e32 v22, 0xbfb8aa3b, v22
	v_add_f32_e32 v20, 1.0, v20
	v_rcp_f32_e32 v20, v20
	v_add_f32_e32 v21, 1.0, v21
	v_rcp_f32_e32 v21, v21
	v_exp_f32_e32 v22, v22
	v_mul_f32_e32 v23, 0xbfb8aa3b, v23
	v_exp_f32_e32 v23, v23
	v_mul_f32_e32 v16, 0xbfb8aa3b, v16
	v_add_f32_e32 v22, 1.0, v22
	v_rcp_f32_e32 v22, v22
	v_add_f32_e32 v23, 1.0, v23
	v_rcp_f32_e32 v23, v23
	v_exp_f32_e32 v16, v16
	v_mul_f32_e32 v17, 0xbfb8aa3b, v17
	v_exp_f32_e32 v17, v17
	v_mul_f32_e32 v18, 0xbfb8aa3b, v18
	v_add_f32_e32 v16, 1.0, v16
	v_rcp_f32_e32 v16, v16
	v_add_f32_e32 v17, 1.0, v17
	v_rcp_f32_e32 v17, v17
	v_exp_f32_e32 v18, v18
	v_mul_f32_e32 v19, 0xbfb8aa3b, v19
	v_exp_f32_e32 v19, v19
	v_mul_f32_e32 v12, 0xbfb8aa3b, v12
	v_add_f32_e32 v18, 1.0, v18
	v_rcp_f32_e32 v18, v18
	v_add_f32_e32 v19, 1.0, v19
	v_rcp_f32_e32 v19, v19
	v_exp_f32_e32 v12, v12
	v_mul_f32_e32 v13, 0xbfb8aa3b, v13
	v_exp_f32_e32 v13, v13
	v_mul_f32_e32 v14, 0xbfb8aa3b, v14
	v_add_f32_e32 v12, 1.0, v12
	v_rcp_f32_e32 v12, v12
	v_add_f32_e32 v13, 1.0, v13
	v_rcp_f32_e32 v13, v13
	v_exp_f32_e32 v14, v14
	v_mul_f32_e32 v15, 0xbfb8aa3b, v15
	v_exp_f32_e32 v15, v15
	v_mul_f32_e32 v8, 0xbfb8aa3b, v8
	v_add_f32_e32 v14, 1.0, v14
	v_rcp_f32_e32 v14, v14
	v_add_f32_e32 v15, 1.0, v15
	v_rcp_f32_e32 v15, v15
	v_exp_f32_e32 v8, v8
	v_mul_f32_e32 v9, 0xbfb8aa3b, v9
	v_exp_f32_e32 v9, v9
	v_mul_f32_e32 v10, 0xbfb8aa3b, v10
	v_add_f32_e32 v8, 1.0, v8
	v_rcp_f32_e32 v8, v8
	v_add_f32_e32 v9, 1.0, v9
	v_rcp_f32_e32 v9, v9
	v_exp_f32_e32 v10, v10
	v_mul_f32_e32 v11, 0xbfb8aa3b, v11
	v_exp_f32_e32 v11, v11
	v_mul_f32_e32 v4, 0xbfb8aa3b, v4
	v_add_f32_e32 v10, 1.0, v10
	v_rcp_f32_e32 v10, v10
	v_add_f32_e32 v11, 1.0, v11
	v_rcp_f32_e32 v11, v11
	v_exp_f32_e32 v4, v4
	v_mul_f32_e32 v5, 0xbfb8aa3b, v5
	v_exp_f32_e32 v5, v5
	v_mul_f32_e32 v6, 0xbfb8aa3b, v6
	v_add_f32_e32 v4, 1.0, v4
	v_rcp_f32_e32 v4, v4
	v_add_f32_e32 v5, 1.0, v5
	s_waitcnt vmcnt(0)
	v_sub_f32_e32 v71, v64, v90
	v_sub_f32_e32 v70, v65, v91
	v_max_f32_e32 v71, v71, v70
	v_sub_f32_e32 v70, v66, v92
	v_max_f32_e32 v71, v71, v70
	v_sub_f32_e32 v70, v67, v93
	v_max_f32_e32 v71, v71, v70
	v_sub_f32_e32 v70, v74, v82
	v_max_f32_e32 v71, v71, v70
	v_sub_f32_e32 v70, v75, v83
	v_max_f32_e32 v71, v71, v70
	v_sub_f32_e32 v70, v76, v84
	v_max_f32_e32 v71, v71, v70
	v_sub_f32_e32 v70, v77, v85
	v_max_f32_e32 v71, v71, v70
	v_cmp_nge_f32_e32 vcc, 0x42a00000, v71
	s_cbranch_vccz .Lhvy_fast2
	v_sub_f32_e32 v64, v64, v90
	v_mul_f32_e32 v64, 0x3fb8aa3b, v64
	v_exp_f32_e32 v64, v64
	v_rcp_f32_e32 v5, v5
	v_exp_f32_e32 v6, v6
	v_mul_f32_e32 v7, 0xbfb8aa3b, v7
	v_add_f32_e32 v64, 1.0, v64
	v_rcp_f32_e32 v71, v64
	v_sub_f32_e32 v64, v65, v91
	v_mul_f32_e32 v64, 0x3fb8aa3b, v64
	v_exp_f32_e32 v64, v64
	v_add_f32_e32 v6, 1.0, v6
	v_rcp_f32_e32 v6, v6
	v_exp_f32_e32 v7, v7
	v_add_f32_e32 v64, 1.0, v64
	v_rcp_f32_e32 v70, v64
	v_sub_f32_e32 v64, v66, v92
	v_mul_f32_e32 v64, 0x3fb8aa3b, v64
	v_exp_f32_e32 v64, v64
	v_add_f32_e32 v7, 1.0, v7
	v_rcp_f32_e32 v7, v7
	v_mul_f32_e32 v0, 0xbfb8aa3b, v0
	v_add_f32_e32 v64, 1.0, v64
	v_rcp_f32_e32 v69, v64
	v_sub_f32_e32 v64, v67, v93
	v_mul_f32_e32 v64, 0x3fb8aa3b, v64
	v_exp_f32_e32 v64, v64
	v_exp_f32_e32 v0, v0
	v_mul_f32_e32 v1, 0xbfb8aa3b, v1
	v_exp_f32_e32 v1, v1
	v_add_f32_e32 v64, 1.0, v64
	v_rcp_f32_e32 v68, v64
	v_sub_f32_e32 v64, v74, v82
	v_mul_f32_e32 v64, 0x3fb8aa3b, v64
	v_exp_f32_e32 v64, v64
	v_add_f32_e32 v0, 1.0, v0
	v_rcp_f32_e32 v0, v0
	v_add_f32_e32 v1, 1.0, v1
	v_add_f32_e32 v64, 1.0, v64
	v_rcp_f32_e32 v67, v64
	v_sub_f32_e32 v64, v75, v83
	v_sub_f32_e32 v75, 1.0, v71
	v_fma_f32 v60, v60, v75, v71
	v_cmp_gt_f32_e32 vcc, s86, v60
	v_mul_f32_e32 v64, 0x3fb8aa3b, v64
	v_exp_f32_e32 v64, v64
	v_cndmask_b32_e64 v74, 0, 32, vcc
	v_ldexp_f32 v60, v60, v74
	v_log_f32_e32 v60, v60
	v_add_f32_e32 v64, 1.0, v64
	v_rcp_f32_e32 v66, v64
	v_sub_f32_e32 v64, v76, v84
	v_mul_f32_e32 v74, 0x3f317217, v60
	v_fma_f32 v74, v60, s87, -v74
	v_fmac_f32_e32 v74, 0x3377d1cf, v60
	v_fmac_f32_e32 v74, 0x3f317217, v60
	v_cmp_lt_f32_e64 s[6:7], |v60|, s88
	v_mul_f32_e32 v64, 0x3fb8aa3b, v64
	v_exp_f32_e32 v64, v64
	v_cndmask_b32_e64 v60, v60, v74, s[6:7]
	v_cndmask_b32_e32 v74, 0, v174, vcc
	v_sub_f32_e32 v76, v60, v74
	v_mul_f32_e32 v60, 0xbfb8aa3b, v61
	v_exp_f32_e32 v60, v60
	v_sub_f32_e32 v74, 1.0, v70
	v_add_f32_e32 v64, 1.0, v64
	v_rcp_f32_e32 v65, v64
	v_add_f32_e32 v60, 1.0, v60
	v_rcp_f32_e32 v60, v60
	v_sub_f32_e32 v64, v77, v85
	v_mul_f32_e32 v64, 0x3fb8aa3b, v64
	v_exp_f32_e32 v64, v64
	v_fma_f32 v60, v60, v74, v70
	v_cmp_gt_f32_e32 vcc, s86, v60
	v_fma_f32 v52, v52, v75, v71
	v_add_f32_e32 v64, 1.0, v64
	v_cndmask_b32_e64 v61, 0, 32, vcc
	v_ldexp_f32 v60, v60, v61
	v_log_f32_e32 v60, v60
	v_rcp_f32_e32 v64, v64
	v_fma_f32 v53, v53, v74, v70
	v_fma_f32 v44, v44, v75, v71
	v_mul_f32_e32 v61, 0x3f317217, v60
	v_fma_f32 v61, v60, s87, -v61
	v_fmac_f32_e32 v61, 0x3377d1cf, v60
	v_fmac_f32_e32 v61, 0x3f317217, v60
	v_cmp_lt_f32_e64 s[6:7], |v60|, s88
	v_fma_f32 v45, v45, v74, v70
	v_fma_f32 v36, v36, v75, v71
	v_cndmask_b32_e64 v60, v60, v61, s[6:7]
	v_cndmask_b32_e32 v61, 0, v174, vcc
	v_sub_f32_e32 v82, v60, v61
	v_mul_f32_e32 v60, 0xbfb8aa3b, v62
	v_exp_f32_e32 v60, v60
	v_sub_f32_e32 v61, 1.0, v69
	v_fma_f32 v54, v54, v61, v69
	v_fma_f32 v46, v46, v61, v69
	v_add_f32_e32 v60, 1.0, v60
	v_rcp_f32_e32 v60, v60
	v_fma_f32 v37, v37, v74, v70
	v_fma_f32 v38, v38, v61, v69
	v_fma_f32 v28, v28, v75, v71
	v_fma_f32 v60, v60, v61, v69
	v_cmp_gt_f32_e32 vcc, s86, v60
	v_fma_f32 v29, v29, v74, v70
	v_fma_f32 v30, v30, v61, v69
	v_cndmask_b32_e64 v62, 0, 32, vcc
	v_ldexp_f32 v60, v60, v62
	v_log_f32_e32 v60, v60
	v_fma_f32 v20, v20, v75, v71
	v_fma_f32 v21, v21, v74, v70
	v_fma_f32 v22, v22, v61, v69
	v_mul_f32_e32 v62, 0x3f317217, v60
	v_fma_f32 v62, v60, s87, -v62
	v_fmac_f32_e32 v62, 0x3377d1cf, v60
	v_fmac_f32_e32 v62, 0x3f317217, v60
	v_cmp_lt_f32_e64 s[6:7], |v60|, s88
	v_fma_f32 v12, v12, v75, v71
	v_fma_f32 v13, v13, v74, v70
	v_cndmask_b32_e64 v60, v60, v62, s[6:7]
	v_cndmask_b32_e32 v62, 0, v174, vcc
	v_sub_f32_e32 v77, v60, v62
	v_mul_f32_e32 v60, 0xbfb8aa3b, v63
	v_exp_f32_e32 v60, v60
	v_fma_f32 v14, v14, v61, v69
	v_fmac_f32_e32 v71, v4, v75
	v_fmac_f32_e32 v70, v5, v74
	v_add_f32_e32 v60, 1.0, v60
	v_rcp_f32_e32 v62, v60
	v_sub_f32_e32 v60, 1.0, v68
	v_fma_f32 v55, v55, v60, v68
	v_fma_f32 v47, v47, v60, v68
	v_fma_f32 v62, v62, v60, v68
	v_cmp_gt_f32_e32 vcc, s86, v62
	v_fma_f32 v39, v39, v60, v68
	v_fma_f32 v31, v31, v60, v68
	v_cndmask_b32_e64 v63, 0, 32, vcc
	v_ldexp_f32 v62, v62, v63
	v_log_f32_e32 v62, v62
	v_fma_f32 v23, v23, v60, v68
	v_fma_f32 v15, v15, v60, v68
	v_fmac_f32_e32 v69, v6, v61
	v_mul_f32_e32 v63, 0x3f317217, v62
	v_fma_f32 v63, v62, s87, -v63
	v_fmac_f32_e32 v63, 0x3377d1cf, v62
	v_fmac_f32_e32 v63, 0x3f317217, v62
	v_cmp_lt_f32_e64 s[6:7], |v62|, s88
	v_fmac_f32_e32 v68, v7, v60
	v_rcp_f32_e32 v1, v1
	v_cndmask_b32_e64 v62, v62, v63, s[6:7]
	v_cndmask_b32_e32 v63, 0, v174, vcc
	v_sub_f32_e32 v63, v62, v63
	v_sub_f32_e32 v62, 1.0, v67
	v_fma_f32 v56, v56, v62, v67
	v_cmp_gt_f32_e32 vcc, s86, v56
	v_fma_f32 v48, v48, v62, v67
	v_fma_f32 v40, v40, v62, v67
	v_cndmask_b32_e64 v78, 0, 32, vcc
	v_ldexp_f32 v56, v56, v78
	v_log_f32_e32 v56, v56
	v_fma_f32 v32, v32, v62, v67
	v_fma_f32 v24, v24, v62, v67
	v_fma_f32 v16, v16, v62, v67
	v_mul_f32_e32 v78, 0x3f317217, v56
	v_fma_f32 v78, v56, s87, -v78
	v_fmac_f32_e32 v78, 0x3377d1cf, v56
	v_fmac_f32_e32 v78, 0x3f317217, v56
	v_cmp_lt_f32_e64 s[6:7], |v56|, s88
	v_fma_f32 v8, v8, v62, v67
	v_fmac_f32_e32 v67, v0, v62
	v_cndmask_b32_e64 v56, v56, v78, s[6:7]
	v_cndmask_b32_e32 v78, 0, v174, vcc
	v_sub_f32_e32 v78, v56, v78
	v_mul_f32_e32 v56, 0xbfb8aa3b, v57
	v_exp_f32_e32 v56, v56
	v_mul_f32_e32 v2, 0xbfb8aa3b, v2
	v_exp_f32_e32 v2, v2
	v_mul_f32_e32 v3, 0xbfb8aa3b, v3
	v_add_f32_e32 v56, 1.0, v56
	v_rcp_f32_e32 v57, v56
	v_sub_f32_e32 v56, 1.0, v66
	v_fma_f32 v49, v49, v56, v66
	v_fma_f32 v41, v41, v56, v66
	v_fma_f32 v57, v57, v56, v66
	v_cmp_gt_f32_e32 vcc, s86, v57
	v_fma_f32 v33, v33, v56, v66
	v_fma_f32 v25, v25, v56, v66
	v_cndmask_b32_e64 v79, 0, 32, vcc
	v_ldexp_f32 v57, v57, v79
	v_log_f32_e32 v57, v57
	v_fma_f32 v17, v17, v56, v66
	v_fma_f32 v9, v9, v56, v66
	v_fmac_f32_e32 v66, v1, v56
	v_mul_f32_e32 v79, 0x3f317217, v57
	v_fma_f32 v79, v57, s87, -v79
	v_fmac_f32_e32 v79, 0x3377d1cf, v57
	v_fmac_f32_e32 v79, 0x3f317217, v57
	v_cmp_lt_f32_e64 s[6:7], |v57|, s88
	v_add_f32_e32 v2, 1.0, v2
	v_rcp_f32_e32 v2, v2
	v_cndmask_b32_e64 v57, v57, v79, s[6:7]
	v_cndmask_b32_e32 v79, 0, v174, vcc
	v_sub_f32_e32 v83, v57, v79
	v_mul_f32_e32 v57, 0xbfb8aa3b, v58
	v_exp_f32_e32 v57, v57
	v_sub_f32_e32 v58, 1.0, v65
	v_fma_f32 v50, v50, v58, v65
	v_fma_f32 v42, v42, v58, v65
	v_add_f32_e32 v57, 1.0, v57
	v_rcp_f32_e32 v57, v57
	v_fma_f32 v34, v34, v58, v65
	v_fma_f32 v26, v26, v58, v65
	v_fma_f32 v18, v18, v58, v65
	v_fma_f32 v57, v57, v58, v65
	v_cmp_gt_f32_e32 vcc, s86, v57
	v_fma_f32 v10, v10, v58, v65
	v_fmac_f32_e32 v65, v2, v58
	v_cndmask_b32_e64 v79, 0, 32, vcc
	v_ldexp_f32 v57, v57, v79
	v_log_f32_e32 v57, v57
	v_exp_f32_e32 v3, v3
	v_cvt_pk_f16_f32 v78, v78, v83
	v_cvt_pk_f16_f32 v77, v77, v63
	v_mul_f32_e32 v79, 0x3f317217, v57
	v_fma_f32 v79, v57, s87, -v79
	v_fmac_f32_e32 v79, 0x3377d1cf, v57
	v_fmac_f32_e32 v79, 0x3f317217, v57
	v_cmp_lt_f32_e64 s[6:7], |v57|, s88
	v_add_f32_e32 v3, 1.0, v3
	v_rcp_f32_e32 v3, v3
	v_cndmask_b32_e64 v57, v57, v79, s[6:7]
	v_cndmask_b32_e32 v79, 0, v174, vcc
	v_sub_f32_e32 v79, v57, v79
	v_mul_f32_e32 v57, 0xbfb8aa3b, v59
	v_exp_f32_e32 v57, v57
	v_cvt_pk_f16_f32 v76, v76, v82
	v_add_f32_e32 v57, 1.0, v57
	v_rcp_f32_e32 v59, v57
	v_sub_f32_e32 v57, 1.0, v64
	v_fma_f32 v51, v51, v57, v64
	v_fma_f32 v43, v43, v57, v64
	v_fma_f32 v59, v59, v57, v64
	v_cmp_gt_f32_e32 vcc, s86, v59
	v_fma_f32 v35, v35, v57, v64
	v_fma_f32 v27, v27, v57, v64
	v_cndmask_b32_e64 v84, 0, 32, vcc
	v_ldexp_f32 v59, v59, v84
	v_log_f32_e32 v59, v59
	v_fma_f32 v19, v19, v57, v64
	v_fma_f32 v11, v11, v57, v64
	v_fmac_f32_e32 v64, v3, v57
	v_mul_f32_e32 v84, 0x3f317217, v59
	v_fma_f32 v84, v59, s87, -v84
	v_fmac_f32_e32 v84, 0x3377d1cf, v59
	v_fmac_f32_e32 v84, 0x3f317217, v59
	v_cmp_lt_f32_e64 s[6:7], |v59|, s88
	s_nop 1
	v_cndmask_b32_e64 v59, v59, v84, s[6:7]
	v_cndmask_b32_e32 v84, 0, v174, vcc
	v_sub_f32_e32 v59, v59, v84
	v_cmp_gt_f32_e32 vcc, s86, v52
	v_cvt_pk_f16_f32 v79, v79, v59
	global_store_dwordx4 v[148:149], v[76:79], off offset:-1792
	v_cndmask_b32_e64 v59, 0, 32, vcc
	v_ldexp_f32 v52, v52, v59
	v_log_f32_e32 v52, v52
	s_nop 0
	v_mul_f32_e32 v59, 0x3f317217, v52
	v_fma_f32 v59, v52, s87, -v59
	v_fmac_f32_e32 v59, 0x3377d1cf, v52
	v_fmac_f32_e32 v59, 0x3f317217, v52
	v_cmp_lt_f32_e64 s[6:7], |v52|, s88
	s_nop 1
	v_cndmask_b32_e64 v52, v52, v59, s[6:7]
	v_cndmask_b32_e32 v59, 0, v174, vcc
	v_cmp_gt_f32_e32 vcc, s86, v53
	v_sub_f32_e32 v52, v52, v59
	s_nop 0
	v_cndmask_b32_e64 v59, 0, 32, vcc
	v_ldexp_f32 v53, v53, v59
	v_log_f32_e32 v53, v53
	s_nop 0
	v_mul_f32_e32 v59, 0x3f317217, v53
	v_fma_f32 v59, v53, s87, -v59
	v_fmac_f32_e32 v59, 0x3377d1cf, v53
	v_fmac_f32_e32 v59, 0x3f317217, v53
	v_cmp_lt_f32_e64 s[6:7], |v53|, s88
	s_nop 1
	v_cndmask_b32_e64 v53, v53, v59, s[6:7]
	v_cndmask_b32_e32 v59, 0, v174, vcc
	v_cmp_gt_f32_e32 vcc, s86, v54
	v_sub_f32_e32 v53, v53, v59
	s_nop 0
	v_cndmask_b32_e64 v59, 0, 32, vcc
	v_ldexp_f32 v54, v54, v59
	v_log_f32_e32 v54, v54
	s_nop 0
	v_mul_f32_e32 v59, 0x3f317217, v54
	v_fma_f32 v59, v54, s87, -v59
	v_fmac_f32_e32 v59, 0x3377d1cf, v54
	v_fmac_f32_e32 v59, 0x3f317217, v54
	v_cmp_lt_f32_e64 s[6:7], |v54|, s88
	s_nop 1
	v_cndmask_b32_e64 v54, v54, v59, s[6:7]
	v_cndmask_b32_e32 v59, 0, v174, vcc
	v_cmp_gt_f32_e32 vcc, s86, v55
	v_sub_f32_e32 v54, v54, v59
	s_nop 0
	v_cndmask_b32_e64 v59, 0, 32, vcc
	v_ldexp_f32 v55, v55, v59
	v_log_f32_e32 v55, v55
	s_nop 0
	v_mul_f32_e32 v59, 0x3f317217, v55
	v_fma_f32 v59, v55, s87, -v59
	v_fmac_f32_e32 v59, 0x3377d1cf, v55
	v_fmac_f32_e32 v59, 0x3f317217, v55
	v_cmp_lt_f32_e64 s[6:7], |v55|, s88
	s_nop 1
	v_cndmask_b32_e64 v55, v55, v59, s[6:7]
	v_cndmask_b32_e32 v59, 0, v174, vcc
	v_cmp_gt_f32_e32 vcc, s86, v48
	v_sub_f32_e32 v55, v55, v59
	s_nop 0
	v_cndmask_b32_e64 v59, 0, 32, vcc
	v_ldexp_f32 v48, v48, v59
	v_log_f32_e32 v48, v48
	s_nop 0
	v_mul_f32_e32 v59, 0x3f317217, v48
	v_fma_f32 v59, v48, s87, -v59
	v_fmac_f32_e32 v59, 0x3377d1cf, v48
	v_fmac_f32_e32 v59, 0x3f317217, v48
	v_cmp_lt_f32_e64 s[6:7], |v48|, s88
	s_nop 1
	v_cndmask_b32_e64 v48, v48, v59, s[6:7]
	v_cndmask_b32_e32 v59, 0, v174, vcc
	v_cmp_gt_f32_e32 vcc, s86, v49
	v_sub_f32_e32 v48, v48, v59
	s_nop 0
	v_cndmask_b32_e64 v59, 0, 32, vcc
	v_ldexp_f32 v49, v49, v59
	v_log_f32_e32 v49, v49
	s_nop 0
	v_mul_f32_e32 v59, 0x3f317217, v49
	v_fma_f32 v59, v49, s87, -v59
	v_fmac_f32_e32 v59, 0x3377d1cf, v49
	v_fmac_f32_e32 v59, 0x3f317217, v49
	v_cmp_lt_f32_e64 s[6:7], |v49|, s88
	s_nop 1
	v_cndmask_b32_e64 v49, v49, v59, s[6:7]
	v_cndmask_b32_e32 v59, 0, v174, vcc
	v_cmp_gt_f32_e32 vcc, s86, v50
	v_sub_f32_e32 v49, v49, v59
	s_nop 0
	v_cndmask_b32_e64 v59, 0, 32, vcc
	v_ldexp_f32 v50, v50, v59
	v_log_f32_e32 v50, v50
	s_nop 0
	v_mul_f32_e32 v59, 0x3f317217, v50
	v_fma_f32 v59, v50, s87, -v59
	v_fmac_f32_e32 v59, 0x3377d1cf, v50
	v_fmac_f32_e32 v59, 0x3f317217, v50
	v_cmp_lt_f32_e64 s[6:7], |v50|, s88
	s_nop 1
	v_cndmask_b32_e64 v50, v50, v59, s[6:7]
	v_cndmask_b32_e32 v59, 0, v174, vcc
	v_cmp_gt_f32_e32 vcc, s86, v51
	v_sub_f32_e32 v50, v50, v59
	s_nop 0
	v_cndmask_b32_e64 v59, 0, 32, vcc
	v_ldexp_f32 v51, v51, v59
	v_log_f32_e32 v51, v51
	s_nop 0
	v_mul_f32_e32 v59, 0x3f317217, v51
	v_fma_f32 v59, v51, s87, -v59
	v_fmac_f32_e32 v59, 0x3377d1cf, v51
	v_fmac_f32_e32 v59, 0x3f317217, v51
	v_cmp_lt_f32_e64 s[6:7], |v51|, s88
	s_nop 1
	v_cndmask_b32_e64 v51, v51, v59, s[6:7]
	v_cndmask_b32_e32 v59, 0, v174, vcc
	v_sub_f32_e32 v51, v51, v59
	v_cvt_pk_f16_f32 v51, v50, v51
	v_cvt_pk_f16_f32 v50, v48, v49
	v_cvt_pk_f16_f32 v49, v54, v55
	v_cvt_pk_f16_f32 v48, v52, v53
	v_cmp_gt_f32_e32 vcc, s86, v44
	global_store_dwordx4 v[120:121], v[48:51], off offset:-1792
	s_nop 1
	v_cndmask_b32_e64 v48, 0, 32, vcc
	v_ldexp_f32 v44, v44, v48
	v_log_f32_e32 v44, v44
	s_nop 0
	v_mul_f32_e32 v48, 0x3f317217, v44
	v_fma_f32 v48, v44, s87, -v48
	v_fmac_f32_e32 v48, 0x3377d1cf, v44
	v_fmac_f32_e32 v48, 0x3f317217, v44
	v_cmp_lt_f32_e64 s[6:7], |v44|, s88
	s_nop 1
	v_cndmask_b32_e64 v44, v44, v48, s[6:7]
	v_cndmask_b32_e32 v48, 0, v174, vcc
	v_cmp_gt_f32_e32 vcc, s86, v45
	v_sub_f32_e32 v44, v44, v48
	s_nop 0
	v_cndmask_b32_e64 v48, 0, 32, vcc
	v_ldexp_f32 v45, v45, v48
	v_log_f32_e32 v45, v45
	s_nop 0
	v_mul_f32_e32 v48, 0x3f317217, v45
	v_fma_f32 v48, v45, s87, -v48
	v_fmac_f32_e32 v48, 0x3377d1cf, v45
	v_fmac_f32_e32 v48, 0x3f317217, v45
	v_cmp_lt_f32_e64 s[6:7], |v45|, s88
	s_nop 1
	v_cndmask_b32_e64 v45, v45, v48, s[6:7]
	v_cndmask_b32_e32 v48, 0, v174, vcc
	v_cmp_gt_f32_e32 vcc, s86, v46
	v_sub_f32_e32 v45, v45, v48
	s_nop 0
	v_cndmask_b32_e64 v48, 0, 32, vcc
	v_ldexp_f32 v46, v46, v48
	v_log_f32_e32 v46, v46
	s_nop 0
	v_mul_f32_e32 v48, 0x3f317217, v46
	v_fma_f32 v48, v46, s87, -v48
	v_fmac_f32_e32 v48, 0x3377d1cf, v46
	v_fmac_f32_e32 v48, 0x3f317217, v46
	v_cmp_lt_f32_e64 s[6:7], |v46|, s88
	s_nop 1
	v_cndmask_b32_e64 v46, v46, v48, s[6:7]
	v_cndmask_b32_e32 v48, 0, v174, vcc
	v_cmp_gt_f32_e32 vcc, s86, v47
	v_sub_f32_e32 v46, v46, v48
	s_nop 0
	v_cndmask_b32_e64 v48, 0, 32, vcc
	v_ldexp_f32 v47, v47, v48
	v_log_f32_e32 v47, v47
	s_nop 0
	v_mul_f32_e32 v48, 0x3f317217, v47
	v_fma_f32 v48, v47, s87, -v48
	v_fmac_f32_e32 v48, 0x3377d1cf, v47
	v_fmac_f32_e32 v48, 0x3f317217, v47
	v_cmp_lt_f32_e64 s[6:7], |v47|, s88
	s_nop 1
	v_cndmask_b32_e64 v47, v47, v48, s[6:7]
	v_cndmask_b32_e32 v48, 0, v174, vcc
	v_cmp_gt_f32_e32 vcc, s86, v40
	v_sub_f32_e32 v47, v47, v48
	s_nop 0
	v_cndmask_b32_e64 v48, 0, 32, vcc
	v_ldexp_f32 v40, v40, v48
	v_log_f32_e32 v40, v40
	s_nop 0
	v_mul_f32_e32 v48, 0x3f317217, v40
	v_fma_f32 v48, v40, s87, -v48
	v_fmac_f32_e32 v48, 0x3377d1cf, v40
	v_fmac_f32_e32 v48, 0x3f317217, v40
	v_cmp_lt_f32_e64 s[6:7], |v40|, s88
	s_nop 1
	v_cndmask_b32_e64 v40, v40, v48, s[6:7]
	v_cndmask_b32_e32 v48, 0, v174, vcc
	v_cmp_gt_f32_e32 vcc, s86, v41
	v_sub_f32_e32 v40, v40, v48
	s_nop 0
	v_cndmask_b32_e64 v48, 0, 32, vcc
	v_ldexp_f32 v41, v41, v48
	v_log_f32_e32 v41, v41
	s_nop 0
	v_mul_f32_e32 v48, 0x3f317217, v41
	v_fma_f32 v48, v41, s87, -v48
	v_fmac_f32_e32 v48, 0x3377d1cf, v41
	v_fmac_f32_e32 v48, 0x3f317217, v41
	v_cmp_lt_f32_e64 s[6:7], |v41|, s88
	s_nop 1
	v_cndmask_b32_e64 v41, v41, v48, s[6:7]
	v_cndmask_b32_e32 v48, 0, v174, vcc
	v_cmp_gt_f32_e32 vcc, s86, v42
	v_sub_f32_e32 v41, v41, v48
	s_nop 0
	v_cndmask_b32_e64 v48, 0, 32, vcc
	v_ldexp_f32 v42, v42, v48
	v_log_f32_e32 v42, v42
	s_nop 0
	v_mul_f32_e32 v48, 0x3f317217, v42
	v_fma_f32 v48, v42, s87, -v48
	v_fmac_f32_e32 v48, 0x3377d1cf, v42
	v_fmac_f32_e32 v48, 0x3f317217, v42
	v_cmp_lt_f32_e64 s[6:7], |v42|, s88
	s_nop 1
	v_cndmask_b32_e64 v42, v42, v48, s[6:7]
	v_cndmask_b32_e32 v48, 0, v174, vcc
	v_cmp_gt_f32_e32 vcc, s86, v43
	v_sub_f32_e32 v42, v42, v48
	s_nop 0
	v_cndmask_b32_e64 v48, 0, 32, vcc
	v_ldexp_f32 v43, v43, v48
	v_log_f32_e32 v43, v43
	s_nop 0
	v_mul_f32_e32 v48, 0x3f317217, v43
	v_fma_f32 v48, v43, s87, -v48
	v_fmac_f32_e32 v48, 0x3377d1cf, v43
	v_fmac_f32_e32 v48, 0x3f317217, v43
	v_cmp_lt_f32_e64 s[6:7], |v43|, s88
	s_nop 1
	v_cndmask_b32_e64 v43, v43, v48, s[6:7]
	v_cndmask_b32_e32 v48, 0, v174, vcc
	v_sub_f32_e32 v43, v43, v48
	v_cvt_pk_f16_f32 v43, v42, v43
	v_cvt_pk_f16_f32 v42, v40, v41
	v_cvt_pk_f16_f32 v41, v46, v47
	v_cvt_pk_f16_f32 v40, v44, v45
	v_cmp_gt_f32_e32 vcc, s86, v36
	global_store_dwordx4 v[112:113], v[40:43], off offset:-1792
	s_nop 1
	v_cndmask_b32_e64 v40, 0, 32, vcc
	v_ldexp_f32 v36, v36, v40
	v_log_f32_e32 v36, v36
	s_nop 0
	v_mul_f32_e32 v40, 0x3f317217, v36
	v_fma_f32 v40, v36, s87, -v40
	v_fmac_f32_e32 v40, 0x3377d1cf, v36
	v_fmac_f32_e32 v40, 0x3f317217, v36
	v_cmp_lt_f32_e64 s[6:7], |v36|, s88
	s_nop 1
	v_cndmask_b32_e64 v36, v36, v40, s[6:7]
	v_cndmask_b32_e32 v40, 0, v174, vcc
	v_cmp_gt_f32_e32 vcc, s86, v37
	v_sub_f32_e32 v36, v36, v40
	s_nop 0
	v_cndmask_b32_e64 v40, 0, 32, vcc
	v_ldexp_f32 v37, v37, v40
	v_log_f32_e32 v37, v37
	s_nop 0
	v_mul_f32_e32 v40, 0x3f317217, v37
	v_fma_f32 v40, v37, s87, -v40
	v_fmac_f32_e32 v40, 0x3377d1cf, v37
	v_fmac_f32_e32 v40, 0x3f317217, v37
	v_cmp_lt_f32_e64 s[6:7], |v37|, s88
	s_nop 1
	v_cndmask_b32_e64 v37, v37, v40, s[6:7]
	v_cndmask_b32_e32 v40, 0, v174, vcc
	v_cmp_gt_f32_e32 vcc, s86, v38
	v_sub_f32_e32 v37, v37, v40
	s_nop 0
	v_cndmask_b32_e64 v40, 0, 32, vcc
	v_ldexp_f32 v38, v38, v40
	v_log_f32_e32 v38, v38
	s_nop 0
	v_mul_f32_e32 v40, 0x3f317217, v38
	v_fma_f32 v40, v38, s87, -v40
	v_fmac_f32_e32 v40, 0x3377d1cf, v38
	v_fmac_f32_e32 v40, 0x3f317217, v38
	v_cmp_lt_f32_e64 s[6:7], |v38|, s88
	s_nop 1
	v_cndmask_b32_e64 v38, v38, v40, s[6:7]
	v_cndmask_b32_e32 v40, 0, v174, vcc
	v_cmp_gt_f32_e32 vcc, s86, v39
	v_sub_f32_e32 v38, v38, v40
	s_nop 0
	v_cndmask_b32_e64 v40, 0, 32, vcc
	v_ldexp_f32 v39, v39, v40
	v_log_f32_e32 v39, v39
	s_nop 0
	v_mul_f32_e32 v40, 0x3f317217, v39
	v_fma_f32 v40, v39, s87, -v40
	v_fmac_f32_e32 v40, 0x3377d1cf, v39
	v_fmac_f32_e32 v40, 0x3f317217, v39
	v_cmp_lt_f32_e64 s[6:7], |v39|, s88
	s_nop 1
	v_cndmask_b32_e64 v39, v39, v40, s[6:7]
	v_cndmask_b32_e32 v40, 0, v174, vcc
	v_cmp_gt_f32_e32 vcc, s86, v32
	v_sub_f32_e32 v39, v39, v40
	s_nop 0
	v_cndmask_b32_e64 v40, 0, 32, vcc
	v_ldexp_f32 v32, v32, v40
	v_log_f32_e32 v32, v32
	s_nop 0
	v_mul_f32_e32 v40, 0x3f317217, v32
	v_fma_f32 v40, v32, s87, -v40
	v_fmac_f32_e32 v40, 0x3377d1cf, v32
	v_fmac_f32_e32 v40, 0x3f317217, v32
	v_cmp_lt_f32_e64 s[6:7], |v32|, s88
	s_nop 1
	v_cndmask_b32_e64 v32, v32, v40, s[6:7]
	v_cndmask_b32_e32 v40, 0, v174, vcc
	v_cmp_gt_f32_e32 vcc, s86, v33
	v_sub_f32_e32 v32, v32, v40
	s_nop 0
	v_cndmask_b32_e64 v40, 0, 32, vcc
	v_ldexp_f32 v33, v33, v40
	v_log_f32_e32 v33, v33
	s_nop 0
	v_mul_f32_e32 v40, 0x3f317217, v33
	v_fma_f32 v40, v33, s87, -v40
	v_fmac_f32_e32 v40, 0x3377d1cf, v33
	v_fmac_f32_e32 v40, 0x3f317217, v33
	v_cmp_lt_f32_e64 s[6:7], |v33|, s88
	s_nop 1
	v_cndmask_b32_e64 v33, v33, v40, s[6:7]
	v_cndmask_b32_e32 v40, 0, v174, vcc
	v_cmp_gt_f32_e32 vcc, s86, v34
	v_sub_f32_e32 v33, v33, v40
	s_nop 0
	v_cndmask_b32_e64 v40, 0, 32, vcc
	v_ldexp_f32 v34, v34, v40
	v_log_f32_e32 v34, v34
	s_nop 0
	v_mul_f32_e32 v40, 0x3f317217, v34
	v_fma_f32 v40, v34, s87, -v40
	v_fmac_f32_e32 v40, 0x3377d1cf, v34
	v_fmac_f32_e32 v40, 0x3f317217, v34
	v_cmp_lt_f32_e64 s[6:7], |v34|, s88
	s_nop 1
	v_cndmask_b32_e64 v34, v34, v40, s[6:7]
	v_cndmask_b32_e32 v40, 0, v174, vcc
	v_cmp_gt_f32_e32 vcc, s86, v35
	v_sub_f32_e32 v34, v34, v40
	s_nop 0
	v_cndmask_b32_e64 v40, 0, 32, vcc
	v_ldexp_f32 v35, v35, v40
	v_log_f32_e32 v35, v35
	s_nop 0
	v_mul_f32_e32 v40, 0x3f317217, v35
	v_fma_f32 v40, v35, s87, -v40
	v_fmac_f32_e32 v40, 0x3377d1cf, v35
	v_fmac_f32_e32 v40, 0x3f317217, v35
	v_cmp_lt_f32_e64 s[6:7], |v35|, s88
	s_nop 1
	v_cndmask_b32_e64 v35, v35, v40, s[6:7]
	v_cndmask_b32_e32 v40, 0, v174, vcc
	v_sub_f32_e32 v35, v35, v40
	v_cvt_pk_f16_f32 v35, v34, v35
	v_cvt_pk_f16_f32 v34, v32, v33
	v_cvt_pk_f16_f32 v33, v38, v39
	v_cvt_pk_f16_f32 v32, v36, v37
	v_cmp_gt_f32_e32 vcc, s86, v28
	global_store_dwordx4 v[104:105], v[32:35], off offset:-1792
	s_nop 1
	v_cndmask_b32_e64 v32, 0, 32, vcc
	v_ldexp_f32 v28, v28, v32
	v_log_f32_e32 v28, v28
	s_nop 0
	v_mul_f32_e32 v32, 0x3f317217, v28
	v_fma_f32 v32, v28, s87, -v32
	v_fmac_f32_e32 v32, 0x3377d1cf, v28
	v_fmac_f32_e32 v32, 0x3f317217, v28
	v_cmp_lt_f32_e64 s[6:7], |v28|, s88
	s_nop 1
	v_cndmask_b32_e64 v28, v28, v32, s[6:7]
	v_cndmask_b32_e32 v32, 0, v174, vcc
	v_cmp_gt_f32_e32 vcc, s86, v29
	v_sub_f32_e32 v28, v28, v32
	s_nop 0
	v_cndmask_b32_e64 v32, 0, 32, vcc
	v_ldexp_f32 v29, v29, v32
	v_log_f32_e32 v29, v29
	s_nop 0
	v_mul_f32_e32 v32, 0x3f317217, v29
	v_fma_f32 v32, v29, s87, -v32
	v_fmac_f32_e32 v32, 0x3377d1cf, v29
	v_fmac_f32_e32 v32, 0x3f317217, v29
	v_cmp_lt_f32_e64 s[6:7], |v29|, s88
	s_nop 1
	v_cndmask_b32_e64 v29, v29, v32, s[6:7]
	v_cndmask_b32_e32 v32, 0, v174, vcc
	v_cmp_gt_f32_e32 vcc, s86, v30
	v_sub_f32_e32 v29, v29, v32
	s_nop 0
	v_cndmask_b32_e64 v32, 0, 32, vcc
	v_ldexp_f32 v30, v30, v32
	v_log_f32_e32 v30, v30
	s_nop 0
	v_mul_f32_e32 v32, 0x3f317217, v30
	v_fma_f32 v32, v30, s87, -v32
	v_fmac_f32_e32 v32, 0x3377d1cf, v30
	v_fmac_f32_e32 v32, 0x3f317217, v30
	v_cmp_lt_f32_e64 s[6:7], |v30|, s88
	s_nop 1
	v_cndmask_b32_e64 v30, v30, v32, s[6:7]
	v_cndmask_b32_e32 v32, 0, v174, vcc
	v_cmp_gt_f32_e32 vcc, s86, v31
	v_sub_f32_e32 v30, v30, v32
	s_nop 0
	v_cndmask_b32_e64 v32, 0, 32, vcc
	v_ldexp_f32 v31, v31, v32
	v_log_f32_e32 v31, v31
	s_nop 0
	v_mul_f32_e32 v32, 0x3f317217, v31
	v_fma_f32 v32, v31, s87, -v32
	v_fmac_f32_e32 v32, 0x3377d1cf, v31
	v_fmac_f32_e32 v32, 0x3f317217, v31
	v_cmp_lt_f32_e64 s[6:7], |v31|, s88
	s_nop 1
	v_cndmask_b32_e64 v31, v31, v32, s[6:7]
	v_cndmask_b32_e32 v32, 0, v174, vcc
	v_cmp_gt_f32_e32 vcc, s86, v24
	v_sub_f32_e32 v31, v31, v32
	s_nop 0
	v_cndmask_b32_e64 v32, 0, 32, vcc
	v_ldexp_f32 v24, v24, v32
	v_log_f32_e32 v24, v24
	s_nop 0
	v_mul_f32_e32 v32, 0x3f317217, v24
	v_fma_f32 v32, v24, s87, -v32
	v_fmac_f32_e32 v32, 0x3377d1cf, v24
	v_fmac_f32_e32 v32, 0x3f317217, v24
	v_cmp_lt_f32_e64 s[6:7], |v24|, s88
	s_nop 1
	v_cndmask_b32_e64 v24, v24, v32, s[6:7]
	v_cndmask_b32_e32 v32, 0, v174, vcc
	v_cmp_gt_f32_e32 vcc, s86, v25
	v_sub_f32_e32 v24, v24, v32
	s_nop 0
	v_cndmask_b32_e64 v32, 0, 32, vcc
	v_ldexp_f32 v25, v25, v32
	v_log_f32_e32 v25, v25
	s_nop 0
	v_mul_f32_e32 v32, 0x3f317217, v25
	v_fma_f32 v32, v25, s87, -v32
	v_fmac_f32_e32 v32, 0x3377d1cf, v25
	v_fmac_f32_e32 v32, 0x3f317217, v25
	v_cmp_lt_f32_e64 s[6:7], |v25|, s88
	s_nop 1
	v_cndmask_b32_e64 v25, v25, v32, s[6:7]
	v_cndmask_b32_e32 v32, 0, v174, vcc
	v_cmp_gt_f32_e32 vcc, s86, v26
	v_sub_f32_e32 v25, v25, v32
	s_nop 0
	v_cndmask_b32_e64 v32, 0, 32, vcc
	v_ldexp_f32 v26, v26, v32
	v_log_f32_e32 v26, v26
	s_nop 0
	v_mul_f32_e32 v32, 0x3f317217, v26
	v_fma_f32 v32, v26, s87, -v32
	v_fmac_f32_e32 v32, 0x3377d1cf, v26
	v_fmac_f32_e32 v32, 0x3f317217, v26
	v_cmp_lt_f32_e64 s[6:7], |v26|, s88
	s_nop 1
	v_cndmask_b32_e64 v26, v26, v32, s[6:7]
	v_cndmask_b32_e32 v32, 0, v174, vcc
	v_cmp_gt_f32_e32 vcc, s86, v27
	v_sub_f32_e32 v26, v26, v32
	s_nop 0
	v_cndmask_b32_e64 v32, 0, 32, vcc
	v_ldexp_f32 v27, v27, v32
	v_log_f32_e32 v27, v27
	s_nop 0
	v_mul_f32_e32 v32, 0x3f317217, v27
	v_fma_f32 v32, v27, s87, -v32
	v_fmac_f32_e32 v32, 0x3377d1cf, v27
	v_fmac_f32_e32 v32, 0x3f317217, v27
	v_cmp_lt_f32_e64 s[6:7], |v27|, s88
	s_nop 1
	v_cndmask_b32_e64 v27, v27, v32, s[6:7]
	v_cndmask_b32_e32 v32, 0, v174, vcc
	v_sub_f32_e32 v27, v27, v32
	v_cvt_pk_f16_f32 v27, v26, v27
	v_cvt_pk_f16_f32 v26, v24, v25
	v_cvt_pk_f16_f32 v25, v30, v31
	v_cvt_pk_f16_f32 v24, v28, v29
	v_cmp_gt_f32_e32 vcc, s86, v20
	global_store_dwordx4 v[96:97], v[24:27], off offset:-1792
	s_nop 1
	v_cndmask_b32_e64 v24, 0, 32, vcc
	v_ldexp_f32 v20, v20, v24
	v_log_f32_e32 v20, v20
	s_nop 0
	v_mul_f32_e32 v24, 0x3f317217, v20
	v_fma_f32 v24, v20, s87, -v24
	v_fmac_f32_e32 v24, 0x3377d1cf, v20
	v_fmac_f32_e32 v24, 0x3f317217, v20
	v_cmp_lt_f32_e64 s[6:7], |v20|, s88
	s_nop 1
	v_cndmask_b32_e64 v20, v20, v24, s[6:7]
	v_cndmask_b32_e32 v24, 0, v174, vcc
	v_cmp_gt_f32_e32 vcc, s86, v21
	v_sub_f32_e32 v20, v20, v24
	s_nop 0
	v_cndmask_b32_e64 v24, 0, 32, vcc
	v_ldexp_f32 v21, v21, v24
	v_log_f32_e32 v21, v21
	s_nop 0
	v_mul_f32_e32 v24, 0x3f317217, v21
	v_fma_f32 v24, v21, s87, -v24
	v_fmac_f32_e32 v24, 0x3377d1cf, v21
	v_fmac_f32_e32 v24, 0x3f317217, v21
	v_cmp_lt_f32_e64 s[6:7], |v21|, s88
	s_nop 1
	v_cndmask_b32_e64 v21, v21, v24, s[6:7]
	v_cndmask_b32_e32 v24, 0, v174, vcc
	v_cmp_gt_f32_e32 vcc, s86, v22
	v_sub_f32_e32 v21, v21, v24
	s_nop 0
	v_cndmask_b32_e64 v24, 0, 32, vcc
	v_ldexp_f32 v22, v22, v24
	v_log_f32_e32 v22, v22
	s_nop 0
	v_mul_f32_e32 v24, 0x3f317217, v22
	v_fma_f32 v24, v22, s87, -v24
	v_fmac_f32_e32 v24, 0x3377d1cf, v22
	v_fmac_f32_e32 v24, 0x3f317217, v22
	v_cmp_lt_f32_e64 s[6:7], |v22|, s88
	s_nop 1
	v_cndmask_b32_e64 v22, v22, v24, s[6:7]
	v_cndmask_b32_e32 v24, 0, v174, vcc
	v_cmp_gt_f32_e32 vcc, s86, v23
	v_sub_f32_e32 v22, v22, v24
	s_nop 0
	v_cndmask_b32_e64 v24, 0, 32, vcc
	v_ldexp_f32 v23, v23, v24
	v_log_f32_e32 v23, v23
	s_nop 0
	v_mul_f32_e32 v24, 0x3f317217, v23
	v_fma_f32 v24, v23, s87, -v24
	v_fmac_f32_e32 v24, 0x3377d1cf, v23
	v_fmac_f32_e32 v24, 0x3f317217, v23
	v_cmp_lt_f32_e64 s[6:7], |v23|, s88
	s_nop 1
	v_cndmask_b32_e64 v23, v23, v24, s[6:7]
	v_cndmask_b32_e32 v24, 0, v174, vcc
	v_cmp_gt_f32_e32 vcc, s86, v16
	v_sub_f32_e32 v23, v23, v24
	s_nop 0
	v_cndmask_b32_e64 v24, 0, 32, vcc
	v_ldexp_f32 v16, v16, v24
	v_log_f32_e32 v16, v16
	s_nop 0
	v_mul_f32_e32 v24, 0x3f317217, v16
	v_fma_f32 v24, v16, s87, -v24
	v_fmac_f32_e32 v24, 0x3377d1cf, v16
	v_fmac_f32_e32 v24, 0x3f317217, v16
	v_cmp_lt_f32_e64 s[6:7], |v16|, s88
	s_nop 1
	v_cndmask_b32_e64 v16, v16, v24, s[6:7]
	v_cndmask_b32_e32 v24, 0, v174, vcc
	v_cmp_gt_f32_e32 vcc, s86, v17
	v_sub_f32_e32 v16, v16, v24
	s_nop 0
	v_cndmask_b32_e64 v24, 0, 32, vcc
	v_ldexp_f32 v17, v17, v24
	v_log_f32_e32 v17, v17
	s_nop 0
	v_mul_f32_e32 v24, 0x3f317217, v17
	v_fma_f32 v24, v17, s87, -v24
	v_fmac_f32_e32 v24, 0x3377d1cf, v17
	v_fmac_f32_e32 v24, 0x3f317217, v17
	v_cmp_lt_f32_e64 s[6:7], |v17|, s88
	s_nop 1
	v_cndmask_b32_e64 v17, v17, v24, s[6:7]
	v_cndmask_b32_e32 v24, 0, v174, vcc
	v_cmp_gt_f32_e32 vcc, s86, v18
	v_sub_f32_e32 v17, v17, v24
	s_nop 0
	v_cndmask_b32_e64 v24, 0, 32, vcc
	v_ldexp_f32 v18, v18, v24
	v_log_f32_e32 v18, v18
	s_nop 0
	v_mul_f32_e32 v24, 0x3f317217, v18
	v_fma_f32 v24, v18, s87, -v24
	v_fmac_f32_e32 v24, 0x3377d1cf, v18
	v_fmac_f32_e32 v24, 0x3f317217, v18
	v_cmp_lt_f32_e64 s[6:7], |v18|, s88
	s_nop 1
	v_cndmask_b32_e64 v18, v18, v24, s[6:7]
	v_cndmask_b32_e32 v24, 0, v174, vcc
	v_cmp_gt_f32_e32 vcc, s86, v19
	v_sub_f32_e32 v18, v18, v24
	s_nop 0
	v_cndmask_b32_e64 v24, 0, 32, vcc
	v_ldexp_f32 v19, v19, v24
	v_log_f32_e32 v19, v19
	s_nop 0
	v_mul_f32_e32 v24, 0x3f317217, v19
	v_fma_f32 v24, v19, s87, -v24
	v_fmac_f32_e32 v24, 0x3377d1cf, v19
	v_fmac_f32_e32 v24, 0x3f317217, v19
	v_cmp_lt_f32_e64 s[6:7], |v19|, s88
	s_nop 1
	v_cndmask_b32_e64 v19, v19, v24, s[6:7]
	v_cndmask_b32_e32 v24, 0, v174, vcc
	v_sub_f32_e32 v19, v19, v24
	v_cvt_pk_f16_f32 v19, v18, v19
	v_cvt_pk_f16_f32 v18, v16, v17
	v_cvt_pk_f16_f32 v17, v22, v23
	v_cvt_pk_f16_f32 v16, v20, v21
	v_cmp_gt_f32_e32 vcc, s86, v12
	global_store_dwordx4 v[88:89], v[16:19], off offset:-1792
	s_nop 1
	v_cndmask_b32_e64 v16, 0, 32, vcc
	v_ldexp_f32 v12, v12, v16
	v_log_f32_e32 v12, v12
	s_nop 0
	v_mul_f32_e32 v16, 0x3f317217, v12
	v_fma_f32 v16, v12, s87, -v16
	v_fmac_f32_e32 v16, 0x3377d1cf, v12
	v_fmac_f32_e32 v16, 0x3f317217, v12
	v_cmp_lt_f32_e64 s[6:7], |v12|, s88
	s_nop 1
	v_cndmask_b32_e64 v12, v12, v16, s[6:7]
	v_cndmask_b32_e32 v16, 0, v174, vcc
	v_cmp_gt_f32_e32 vcc, s86, v13
	v_sub_f32_e32 v12, v12, v16
	s_nop 0
	v_cndmask_b32_e64 v16, 0, 32, vcc
	v_ldexp_f32 v13, v13, v16
	v_log_f32_e32 v13, v13
	s_nop 0
	v_mul_f32_e32 v16, 0x3f317217, v13
	v_fma_f32 v16, v13, s87, -v16
	v_fmac_f32_e32 v16, 0x3377d1cf, v13
	v_fmac_f32_e32 v16, 0x3f317217, v13
	v_cmp_lt_f32_e64 s[6:7], |v13|, s88
	s_nop 1
	v_cndmask_b32_e64 v13, v13, v16, s[6:7]
	v_cndmask_b32_e32 v16, 0, v174, vcc
	v_cmp_gt_f32_e32 vcc, s86, v14
	v_sub_f32_e32 v13, v13, v16
	s_nop 0
	v_cndmask_b32_e64 v16, 0, 32, vcc
	v_ldexp_f32 v14, v14, v16
	v_log_f32_e32 v14, v14
	s_nop 0
	v_mul_f32_e32 v16, 0x3f317217, v14
	v_fma_f32 v16, v14, s87, -v16
	v_fmac_f32_e32 v16, 0x3377d1cf, v14
	v_fmac_f32_e32 v16, 0x3f317217, v14
	v_cmp_lt_f32_e64 s[6:7], |v14|, s88
	s_nop 1
	v_cndmask_b32_e64 v14, v14, v16, s[6:7]
	v_cndmask_b32_e32 v16, 0, v174, vcc
	v_cmp_gt_f32_e32 vcc, s86, v15
	v_sub_f32_e32 v14, v14, v16
	s_nop 0
	v_cndmask_b32_e64 v16, 0, 32, vcc
	v_ldexp_f32 v15, v15, v16
	v_log_f32_e32 v15, v15
	s_nop 0
	v_mul_f32_e32 v16, 0x3f317217, v15
	v_fma_f32 v16, v15, s87, -v16
	v_fmac_f32_e32 v16, 0x3377d1cf, v15
	v_fmac_f32_e32 v16, 0x3f317217, v15
	v_cmp_lt_f32_e64 s[6:7], |v15|, s88
	s_nop 1
	v_cndmask_b32_e64 v15, v15, v16, s[6:7]
	v_cndmask_b32_e32 v16, 0, v174, vcc
	v_cmp_gt_f32_e32 vcc, s86, v8
	v_sub_f32_e32 v15, v15, v16
	s_nop 0
	v_cndmask_b32_e64 v16, 0, 32, vcc
	v_ldexp_f32 v8, v8, v16
	v_log_f32_e32 v8, v8
	s_nop 0
	v_mul_f32_e32 v16, 0x3f317217, v8
	v_fma_f32 v16, v8, s87, -v16
	v_fmac_f32_e32 v16, 0x3377d1cf, v8
	v_fmac_f32_e32 v16, 0x3f317217, v8
	v_cmp_lt_f32_e64 s[6:7], |v8|, s88
	s_nop 1
	v_cndmask_b32_e64 v8, v8, v16, s[6:7]
	v_cndmask_b32_e32 v16, 0, v174, vcc
	v_cmp_gt_f32_e32 vcc, s86, v9
	v_sub_f32_e32 v8, v8, v16
	s_nop 0
	v_cndmask_b32_e64 v16, 0, 32, vcc
	v_ldexp_f32 v9, v9, v16
	v_log_f32_e32 v9, v9
	s_nop 0
	v_mul_f32_e32 v16, 0x3f317217, v9
	v_fma_f32 v16, v9, s87, -v16
	v_fmac_f32_e32 v16, 0x3377d1cf, v9
	v_fmac_f32_e32 v16, 0x3f317217, v9
	v_cmp_lt_f32_e64 s[6:7], |v9|, s88
	s_nop 1
	v_cndmask_b32_e64 v9, v9, v16, s[6:7]
	v_cndmask_b32_e32 v16, 0, v174, vcc
	v_cmp_gt_f32_e32 vcc, s86, v10
	v_sub_f32_e32 v9, v9, v16
	s_nop 0
	v_cndmask_b32_e64 v16, 0, 32, vcc
	v_ldexp_f32 v10, v10, v16
	v_log_f32_e32 v10, v10
	s_nop 0
	v_mul_f32_e32 v16, 0x3f317217, v10
	v_fma_f32 v16, v10, s87, -v16
	v_fmac_f32_e32 v16, 0x3377d1cf, v10
	v_fmac_f32_e32 v16, 0x3f317217, v10
	v_cmp_lt_f32_e64 s[6:7], |v10|, s88
	s_nop 1
	v_cndmask_b32_e64 v10, v10, v16, s[6:7]
	v_cndmask_b32_e32 v16, 0, v174, vcc
	v_cmp_gt_f32_e32 vcc, s86, v11
	v_sub_f32_e32 v10, v10, v16
	s_nop 0
	v_cndmask_b32_e64 v16, 0, 32, vcc
	v_ldexp_f32 v11, v11, v16
	v_log_f32_e32 v11, v11
	s_nop 0
	v_mul_f32_e32 v16, 0x3f317217, v11
	v_fma_f32 v16, v11, s87, -v16
	v_fmac_f32_e32 v16, 0x3377d1cf, v11
	v_fmac_f32_e32 v16, 0x3f317217, v11
	v_cmp_lt_f32_e64 s[6:7], |v11|, s88
	s_nop 1
	v_cndmask_b32_e64 v11, v11, v16, s[6:7]
	v_cndmask_b32_e32 v16, 0, v174, vcc
	v_cmp_gt_f32_e32 vcc, s86, v71
	v_sub_f32_e32 v11, v11, v16
	v_cvt_pk_f16_f32 v11, v10, v11
	v_cndmask_b32_e64 v4, 0, 32, vcc
	v_ldexp_f32 v4, v71, v4
	v_log_f32_e32 v4, v4
	v_cvt_pk_f16_f32 v10, v8, v9
	v_cvt_pk_f16_f32 v9, v14, v15
	v_cvt_pk_f16_f32 v8, v12, v13
	global_store_dwordx4 v[80:81], v[8:11], off offset:-1792
	v_cmp_lt_f32_e64 s[6:7], |v4|, s88
	s_nop 0
	v_mul_f32_e32 v8, 0x3f317217, v4
	v_fma_f32 v8, v4, s87, -v8
	v_fmac_f32_e32 v8, 0x3377d1cf, v4
	v_fmac_f32_e32 v8, 0x3f317217, v4
	v_cndmask_b32_e64 v4, v4, v8, s[6:7]
	v_cndmask_b32_e32 v8, 0, v174, vcc
	v_cmp_gt_f32_e32 vcc, s86, v70
	v_sub_f32_e32 v4, v4, v8
	s_nop 0
	v_cndmask_b32_e64 v5, 0, 32, vcc
	v_ldexp_f32 v5, v70, v5
	v_log_f32_e32 v5, v5
	s_nop 0
	v_mul_f32_e32 v8, 0x3f317217, v5
	v_fma_f32 v8, v5, s87, -v8
	v_fmac_f32_e32 v8, 0x3377d1cf, v5
	v_fmac_f32_e32 v8, 0x3f317217, v5
	v_cmp_lt_f32_e64 s[6:7], |v5|, s88
	s_nop 1
	v_cndmask_b32_e64 v5, v5, v8, s[6:7]
	v_cndmask_b32_e32 v8, 0, v174, vcc
	v_cmp_gt_f32_e32 vcc, s86, v69
	v_sub_f32_e32 v5, v5, v8
	s_nop 0
	v_cndmask_b32_e64 v6, 0, 32, vcc
	v_ldexp_f32 v6, v69, v6
	v_log_f32_e32 v6, v6
	s_nop 0
	v_mul_f32_e32 v8, 0x3f317217, v6
	v_fma_f32 v8, v6, s87, -v8
	v_fmac_f32_e32 v8, 0x3377d1cf, v6
	v_fmac_f32_e32 v8, 0x3f317217, v6
	v_cmp_lt_f32_e64 s[6:7], |v6|, s88
	s_nop 1
	v_cndmask_b32_e64 v6, v6, v8, s[6:7]
	v_cndmask_b32_e32 v8, 0, v174, vcc
	v_cmp_gt_f32_e32 vcc, s86, v68
	v_sub_f32_e32 v6, v6, v8
	s_nop 0
	v_cndmask_b32_e64 v7, 0, 32, vcc
	v_ldexp_f32 v7, v68, v7
	v_log_f32_e32 v7, v7
	s_nop 0
	v_mul_f32_e32 v8, 0x3f317217, v7
	v_fma_f32 v8, v7, s87, -v8
	v_fmac_f32_e32 v8, 0x3377d1cf, v7
	v_fmac_f32_e32 v8, 0x3f317217, v7
	v_cmp_lt_f32_e64 s[6:7], |v7|, s88
	s_nop 1
	v_cndmask_b32_e64 v7, v7, v8, s[6:7]
	v_cndmask_b32_e32 v8, 0, v174, vcc
	v_cmp_gt_f32_e32 vcc, s86, v67
	v_sub_f32_e32 v7, v7, v8
	s_nop 0
	v_cndmask_b32_e64 v0, 0, 32, vcc
	v_ldexp_f32 v0, v67, v0
	v_log_f32_e32 v0, v0
	s_nop 0
	v_mul_f32_e32 v8, 0x3f317217, v0
	v_fma_f32 v8, v0, s87, -v8
	v_fmac_f32_e32 v8, 0x3377d1cf, v0
	v_fmac_f32_e32 v8, 0x3f317217, v0
	v_cmp_lt_f32_e64 s[6:7], |v0|, s88
	s_nop 1
	v_cndmask_b32_e64 v0, v0, v8, s[6:7]
	v_cndmask_b32_e32 v8, 0, v174, vcc
	v_cmp_gt_f32_e32 vcc, s86, v66
	v_sub_f32_e32 v0, v0, v8
	s_nop 0
	v_cndmask_b32_e64 v1, 0, 32, vcc
	v_ldexp_f32 v1, v66, v1
	v_log_f32_e32 v1, v1
	s_nop 0
	v_mul_f32_e32 v8, 0x3f317217, v1
	v_fma_f32 v8, v1, s87, -v8
	v_fmac_f32_e32 v8, 0x3377d1cf, v1
	v_fmac_f32_e32 v8, 0x3f317217, v1
	v_cmp_lt_f32_e64 s[6:7], |v1|, s88
	s_nop 1
	v_cndmask_b32_e64 v1, v1, v8, s[6:7]
	v_cndmask_b32_e32 v8, 0, v174, vcc
	v_cmp_gt_f32_e32 vcc, s86, v65
	v_sub_f32_e32 v1, v1, v8
	s_nop 0
	v_cndmask_b32_e64 v2, 0, 32, vcc
	v_ldexp_f32 v2, v65, v2
	v_log_f32_e32 v2, v2
	s_nop 0
	v_mul_f32_e32 v8, 0x3f317217, v2
	v_fma_f32 v8, v2, s87, -v8
	v_fmac_f32_e32 v8, 0x3377d1cf, v2
	v_fmac_f32_e32 v8, 0x3f317217, v2
	v_cmp_lt_f32_e64 s[6:7], |v2|, s88
	s_nop 1
	v_cndmask_b32_e64 v2, v2, v8, s[6:7]
	v_cndmask_b32_e32 v8, 0, v174, vcc
	v_cmp_gt_f32_e32 vcc, s86, v64
	v_sub_f32_e32 v2, v2, v8
	s_nop 0
	v_cndmask_b32_e64 v3, 0, 32, vcc
	v_ldexp_f32 v3, v64, v3
	v_log_f32_e32 v3, v3
	s_nop 0
	v_mul_f32_e32 v8, 0x3f317217, v3
	v_fma_f32 v8, v3, s87, -v8
	v_fmac_f32_e32 v8, 0x3377d1cf, v3
	v_fmac_f32_e32 v8, 0x3f317217, v3
	v_cmp_lt_f32_e64 s[6:7], |v3|, s88
	s_nop 1
	v_cndmask_b32_e64 v3, v3, v8, s[6:7]
	v_cndmask_b32_e32 v8, 0, v174, vcc
	v_sub_f32_e32 v3, v3, v8
	v_cvt_pk_f16_f32 v3, v2, v3
	v_cvt_pk_f16_f32 v2, v0, v1
	v_cvt_pk_f16_f32 v1, v6, v7
	v_cvt_pk_f16_f32 v0, v4, v5
	global_store_dwordx4 v[72:73], v[0:3], off offset:-1792
	s_branch .LBB0_237
.Lhvy_fast1:
	v_sub_f32_e32 v136, v152, v180
	v_mul_f32_e32 v136, 0x3fb8aa3b, v136
	v_exp_f32_e32 v136, v136
	v_add_f32_e32 v104, 1.0, v104
	v_rcp_f32_e32 v104, v104
	v_exp_f32_e32 v105, v105
	v_add_f32_e32 v136, 1.0, v136
	v_rcp_f32_e32 v158, v136
	v_sub_f32_e32 v136, v153, v181
	v_mul_f32_e32 v136, 0x3fb8aa3b, v136
	v_exp_f32_e32 v136, v136
	v_sub_f32_e32 v124, 1.0, v158
	v_fma_f32 v147, v147, v124, v158
	v_add_f32_e32 v136, 1.0, v136
	v_rcp_f32_e32 v157, v136
	v_sub_f32_e32 v136, v154, v182
	v_mul_f32_e32 v136, 0x3fb8aa3b, v136
	v_exp_f32_e32 v136, v136
	v_log_f32_e32 v147, v147
	v_add_f32_e32 v136, 1.0, v136
	v_rcp_f32_e32 v156, v136
	v_sub_f32_e32 v136, v155, v183
	v_mul_f32_e32 v136, 0x3fb8aa3b, v136
	v_exp_f32_e32 v136, v136
	v_mul_f32_e32 v159, 0x3f317217, v147
	v_fma_f32 v159, v147, s87, -v159
	v_fmac_f32_e32 v159, 0x3377d1cf, v147
	v_add_f32_e32 v136, 1.0, v136
	v_rcp_f32_e32 v155, v136
	v_sub_f32_e32 v136, v160, v176
	v_mul_f32_e32 v136, 0x3fb8aa3b, v136
	v_exp_f32_e32 v136, v136
	v_fma_f32 v116, v116, v124, v158
	v_add_f32_e32 v136, 1.0, v136
	v_rcp_f32_e32 v154, v136
	v_sub_f32_e32 v136, v161, v177
	v_fma_f32 v161, v147, s87, v159
	v_rcp_f32_e32 v147, v125
	v_sub_f32_e32 v125, 1.0, v157
	v_mul_f32_e32 v136, 0x3fb8aa3b, v136
	v_exp_f32_e32 v136, v136
	v_fma_f32 v147, v147, v125, v157
	v_sub_f32_e32 v160, 1.0, v154
	v_add_f32_e32 v136, 1.0, v136
	v_log_f32_e32 v147, v147
	v_rcp_f32_e32 v153, v136
	v_sub_f32_e32 v136, v162, v178
	v_mul_f32_e32 v136, 0x3fb8aa3b, v136
	v_mul_f32_e32 v159, 0x3f317217, v147
	v_fma_f32 v159, v147, s87, -v159
	v_fmac_f32_e32 v159, 0x3377d1cf, v147
	v_exp_f32_e32 v136, v136
	v_fma_f32 v120, v120, v160, v154
	v_fma_f32 v162, v147, s87, v159
	v_rcp_f32_e32 v147, v126
	v_sub_f32_e32 v126, 1.0, v156
	v_add_f32_e32 v136, 1.0, v136
	v_rcp_f32_e32 v152, v136
	v_fma_f32 v147, v147, v126, v156
	v_sub_f32_e32 v136, v163, v179
	v_mul_f32_e32 v136, 0x3fb8aa3b, v136
	v_log_f32_e32 v147, v147
	v_exp_f32_e32 v136, v136
	v_fma_f32 v117, v117, v125, v157
	v_fma_f32 v118, v118, v126, v156
	v_mul_f32_e32 v159, 0x3f317217, v147
	v_fma_f32 v159, v147, s87, -v159
	v_fmac_f32_e32 v159, 0x3377d1cf, v147
	v_add_f32_e32 v136, 1.0, v136
	v_rcp_f32_e32 v151, v136
	v_fma_f32 v163, v147, s87, v159
	v_rcp_f32_e32 v147, v127
	v_sub_f32_e32 v127, 1.0, v155
	v_fma_f32 v119, v119, v127, v155
	v_fma_f32 v112, v112, v160, v154
	v_fma_f32 v147, v147, v127, v155
	v_lshlrev_b32_e32 v136, 1, v150
	v_fma_f32 v108, v108, v124, v158
	v_log_f32_e32 v147, v147
	v_fma_f32 v109, v109, v125, v157
	v_fma_f32 v110, v110, v126, v156
	v_fma_f32 v111, v111, v127, v155
	v_mul_f32_e32 v159, 0x3f317217, v147
	v_fma_f32 v159, v147, s87, -v159
	v_fmac_f32_e32 v159, 0x3377d1cf, v147
	v_fma_f32 v104, v104, v160, v154
	v_add_f32_e32 v105, 1.0, v105
	v_fma_f32 v176, v147, s87, v159
	v_rcp_f32_e32 v105, v105
	v_log_f32_e32 v120, v120
	v_mul_f32_e32 v106, 0xbfb8aa3b, v106
	v_exp_f32_e32 v106, v106
	v_mul_f32_e32 v107, 0xbfb8aa3b, v107
	v_mul_f32_e32 v147, 0x3f317217, v120
	v_fma_f32 v147, v120, s87, -v147
	v_fmac_f32_e32 v147, 0x3377d1cf, v120
	v_add_f32_e32 v106, 1.0, v106
	v_rcp_f32_e32 v106, v106
	v_fma_f32 v120, v120, s87, v147
	v_sub_f32_e32 v147, 1.0, v153
	v_fma_f32 v121, v121, v147, v153
	v_fma_f32 v113, v113, v147, v153
	v_fma_f32 v105, v105, v147, v153
	v_log_f32_e32 v121, v121
	v_exp_f32_e32 v107, v107
	v_mul_f32_e32 v100, 0xbfb8aa3b, v100
	v_exp_f32_e32 v100, v100
	v_mul_f32_e32 v159, 0x3f317217, v121
	v_fma_f32 v159, v121, s87, -v159
	v_fmac_f32_e32 v159, 0x3377d1cf, v121
	v_add_f32_e32 v107, 1.0, v107
	v_rcp_f32_e32 v107, v107
	v_fma_f32 v121, v121, s87, v159
	v_sub_f32_e32 v159, 1.0, v152
	v_fma_f32 v122, v122, v159, v152
	v_fma_f32 v114, v114, v159, v152
	v_fma_f32 v106, v106, v159, v152
	v_log_f32_e32 v122, v122
	v_add_f32_e32 v100, 1.0, v100
	v_rcp_f32_e32 v100, v100
	v_mul_f32_e32 v101, 0xbfb8aa3b, v101
	v_mul_f32_e32 v164, 0x3f317217, v122
	v_fma_f32 v164, v122, s87, -v164
	v_fmac_f32_e32 v164, 0x3377d1cf, v122
	v_fma_f32 v100, v100, v124, v158
	v_exp_f32_e32 v101, v101
	v_fma_f32 v164, v122, s87, v164
	v_mul_f32_e32 v122, 0xbfb8aa3b, v123
	v_exp_f32_e32 v122, v122
	v_add_f32_e32 v101, 1.0, v101
	v_rcp_f32_e32 v101, v101
	v_mul_f32_e32 v102, 0xbfb8aa3b, v102
	v_add_f32_e32 v122, 1.0, v122
	v_rcp_f32_e32 v123, v122
	v_sub_f32_e32 v122, 1.0, v151
	v_fma_f32 v115, v115, v122, v151
	v_fma_f32 v107, v107, v122, v151
	v_fma_f32 v123, v123, v122, v151
	v_fma_f32 v101, v101, v125, v157
	v_exp_f32_e32 v102, v102
	v_log_f32_e32 v123, v123
	v_add_f32_e32 v102, 1.0, v102
	v_rcp_f32_e32 v102, v102
	v_mul_f32_e32 v103, 0xbfb8aa3b, v103
	v_mul_f32_e32 v165, 0x3f317217, v123
	v_fma_f32 v165, v123, s87, -v165
	v_fmac_f32_e32 v165, 0x3377d1cf, v123
	v_fma_f32 v102, v102, v126, v156
	v_exp_f32_e32 v103, v103
	v_fma_f32 v123, v123, s87, v165
	v_cvt_pk_f16_f32 v165, v164, v123
	v_cvt_pk_f16_f32 v164, v120, v121
	v_log_f32_e32 v116, v116
	v_or_b32_e32 v120, 16, v146
	v_ashrrev_i32_e32 v121, 31, v120
	v_lshlrev_b64 v[120:121], 11, v[120:121]
	v_mul_f32_e32 v123, 0x3f317217, v116
	v_fma_f32 v123, v116, s87, -v123
	v_fmac_f32_e32 v123, 0x3377d1cf, v116
	v_lshl_add_u64 v[120:121], s[84:85], 0, v[120:121]
	v_lshl_add_u64 v[120:121], v[120:121], 0, v[136:137]
	v_fma_f32 v116, v116, s87, v123
	v_add_f32_e32 v103, 1.0, v103
	v_log_f32_e32 v117, v117
	v_rcp_f32_e32 v103, v103
	v_mul_f32_e32 v96, 0xbfb8aa3b, v96
	v_exp_f32_e32 v96, v96
	v_mul_f32_e32 v123, 0x3f317217, v117
	v_fma_f32 v123, v117, s87, -v123
	v_fmac_f32_e32 v123, 0x3377d1cf, v117
	v_fma_f32 v103, v103, v127, v155
	v_add_f32_e32 v96, 1.0, v96
	v_fma_f32 v117, v117, s87, v123
	v_rcp_f32_e32 v96, v96
	v_log_f32_e32 v118, v118
	v_fma_f32 v96, v96, v160, v154
	v_mul_f32_e32 v97, 0xbfb8aa3b, v97
	v_exp_f32_e32 v97, v97
	v_mul_f32_e32 v123, 0x3f317217, v118
	v_fma_f32 v123, v118, s87, -v123
	v_fmac_f32_e32 v123, 0x3377d1cf, v118
	v_add_f32_e32 v97, 1.0, v97
	v_rcp_f32_e32 v97, v97
	v_fma_f32 v118, v118, s87, v123
	v_fma_f32 v97, v97, v147, v153
	v_log_f32_e32 v119, v119
	v_mul_f32_e32 v98, 0xbfb8aa3b, v98
	v_exp_f32_e32 v98, v98
	v_mul_f32_e32 v99, 0xbfb8aa3b, v99
	v_mul_f32_e32 v123, 0x3f317217, v119
	v_fma_f32 v123, v119, s87, -v123
	v_fmac_f32_e32 v123, 0x3377d1cf, v119
	v_add_f32_e32 v98, 1.0, v98
	v_rcp_f32_e32 v98, v98
	v_fma_f32 v119, v119, s87, v123
	v_fma_f32 v98, v98, v159, v152
	v_log_f32_e32 v112, v112
	v_exp_f32_e32 v99, v99
	v_mul_f32_e32 v92, 0xbfb8aa3b, v92
	v_exp_f32_e32 v92, v92
	v_mul_f32_e32 v123, 0x3f317217, v112
	v_fma_f32 v123, v112, s87, -v123
	v_fmac_f32_e32 v123, 0x3377d1cf, v112
	v_add_f32_e32 v99, 1.0, v99
	v_rcp_f32_e32 v99, v99
	v_fma_f32 v112, v112, s87, v123
	v_fma_f32 v99, v99, v122, v151
	v_log_f32_e32 v113, v113
	v_add_f32_e32 v92, 1.0, v92
	v_rcp_f32_e32 v92, v92
	v_mul_f32_e32 v93, 0xbfb8aa3b, v93
	v_mul_f32_e32 v123, 0x3f317217, v113
	v_fma_f32 v123, v113, s87, -v123
	v_fmac_f32_e32 v123, 0x3377d1cf, v113
	v_fma_f32 v92, v92, v124, v158
	v_exp_f32_e32 v93, v93
	v_fma_f32 v113, v113, s87, v123
	v_add_f32_e32 v93, 1.0, v93
	v_log_f32_e32 v114, v114
	v_rcp_f32_e32 v93, v93
	v_lshl_add_u64 v[148:149], s[84:85], 0, v[148:149]
	v_lshl_add_u64 v[148:149], v[148:149], 0, v[136:137]
	v_mul_f32_e32 v123, 0x3f317217, v114
	v_fma_f32 v123, v114, s87, -v123
	v_fmac_f32_e32 v123, 0x3377d1cf, v114
	v_fma_f32 v93, v93, v125, v157
	v_mul_f32_e32 v94, 0xbfb8aa3b, v94
	v_fma_f32 v114, v114, s87, v123
	v_exp_f32_e32 v94, v94
	v_log_f32_e32 v115, v115
	v_add_f32_e32 v94, 1.0, v94
	v_rcp_f32_e32 v94, v94
	v_mul_f32_e32 v95, 0xbfb8aa3b, v95
	v_mul_f32_e32 v123, 0x3f317217, v115
	v_fma_f32 v123, v115, s87, -v123
	v_fmac_f32_e32 v123, 0x3377d1cf, v115
	v_fma_f32 v94, v94, v126, v156
	v_exp_f32_e32 v95, v95
	v_fma_f32 v115, v115, s87, v123
	v_cvt_pk_f16_f32 v115, v114, v115
	v_cvt_pk_f16_f32 v114, v112, v113
	v_cvt_pk_f16_f32 v113, v118, v119
	v_cvt_pk_f16_f32 v112, v116, v117
	global_store_dwordx4 v[120:121], v[112:115], off offset:-2048
	v_add_f32_e32 v95, 1.0, v95
	v_rcp_f32_e32 v95, v95
	v_log_f32_e32 v108, v108
	v_or_b32_e32 v112, 32, v146
	v_ashrrev_i32_e32 v113, 31, v112
	v_lshlrev_b64 v[112:113], 11, v[112:113]
	v_mul_f32_e32 v114, 0x3f317217, v108
	v_fma_f32 v114, v108, s87, -v114
	v_fmac_f32_e32 v114, 0x3377d1cf, v108
	v_lshl_add_u64 v[112:113], s[84:85], 0, v[112:113]
	v_lshl_add_u64 v[112:113], v[112:113], 0, v[136:137]
	v_fma_f32 v108, v108, s87, v114
	v_fma_f32 v95, v95, v127, v155
	v_log_f32_e32 v109, v109
	v_mul_f32_e32 v88, 0xbfb8aa3b, v88
	v_exp_f32_e32 v88, v88
	v_mul_f32_e32 v89, 0xbfb8aa3b, v89
	v_mul_f32_e32 v114, 0x3f317217, v109
	v_fma_f32 v114, v109, s87, -v114
	v_fmac_f32_e32 v114, 0x3377d1cf, v109
	v_add_f32_e32 v88, 1.0, v88
	v_rcp_f32_e32 v88, v88
	v_fma_f32 v109, v109, s87, v114
	v_fma_f32 v88, v88, v160, v154
	v_log_f32_e32 v110, v110
	v_exp_f32_e32 v89, v89
	v_mul_f32_e32 v90, 0xbfb8aa3b, v90
	v_exp_f32_e32 v90, v90
	v_mul_f32_e32 v114, 0x3f317217, v110
	v_fma_f32 v114, v110, s87, -v114
	v_fmac_f32_e32 v114, 0x3377d1cf, v110
	v_add_f32_e32 v89, 1.0, v89
	v_rcp_f32_e32 v89, v89
	v_fma_f32 v110, v110, s87, v114
	v_fma_f32 v89, v89, v147, v153
	v_log_f32_e32 v111, v111
	v_add_f32_e32 v90, 1.0, v90
	v_rcp_f32_e32 v90, v90
	v_mul_f32_e32 v91, 0xbfb8aa3b, v91
	v_mul_f32_e32 v114, 0x3f317217, v111
	v_fma_f32 v114, v111, s87, -v114
	v_fmac_f32_e32 v114, 0x3377d1cf, v111
	v_fma_f32 v90, v90, v159, v152
	v_exp_f32_e32 v91, v91
	v_fma_f32 v111, v111, s87, v114
	v_add_f32_e32 v91, 1.0, v91
	v_log_f32_e32 v104, v104
	v_rcp_f32_e32 v91, v91
	v_mul_f32_e32 v84, 0xbfb8aa3b, v84
	v_exp_f32_e32 v84, v84
	v_mul_f32_e32 v114, 0x3f317217, v104
	v_fma_f32 v114, v104, s87, -v114
	v_fmac_f32_e32 v114, 0x3377d1cf, v104
	v_fma_f32 v91, v91, v122, v151
	v_add_f32_e32 v84, 1.0, v84
	v_fma_f32 v104, v104, s87, v114
	v_rcp_f32_e32 v84, v84
	v_log_f32_e32 v105, v105
	v_fma_f32 v84, v84, v124, v158
	v_mul_f32_e32 v85, 0xbfb8aa3b, v85
	v_exp_f32_e32 v85, v85
	v_mul_f32_e32 v114, 0x3f317217, v105
	v_fma_f32 v114, v105, s87, -v114
	v_fmac_f32_e32 v114, 0x3377d1cf, v105
	v_add_f32_e32 v85, 1.0, v85
	v_rcp_f32_e32 v85, v85
	v_fma_f32 v105, v105, s87, v114
	v_fma_f32 v85, v85, v125, v157
	v_log_f32_e32 v106, v106
	v_mul_f32_e32 v86, 0xbfb8aa3b, v86
	v_exp_f32_e32 v86, v86
	v_mul_f32_e32 v87, 0xbfb8aa3b, v87
	v_mul_f32_e32 v114, 0x3f317217, v106
	v_fma_f32 v114, v106, s87, -v114
	v_fmac_f32_e32 v114, 0x3377d1cf, v106
	v_add_f32_e32 v86, 1.0, v86
	v_rcp_f32_e32 v86, v86
	v_fma_f32 v106, v106, s87, v114
	v_fma_f32 v86, v86, v126, v156
	v_log_f32_e32 v107, v107
	v_exp_f32_e32 v87, v87
	v_mul_f32_e32 v80, 0xbfb8aa3b, v80
	v_exp_f32_e32 v80, v80
	v_mul_f32_e32 v114, 0x3f317217, v107
	v_fma_f32 v114, v107, s87, -v114
	v_fmac_f32_e32 v114, 0x3377d1cf, v107
	v_add_f32_e32 v87, 1.0, v87
	v_rcp_f32_e32 v87, v87
	v_fma_f32 v107, v107, s87, v114
	v_cvt_pk_f16_f32 v107, v106, v107
	v_cvt_pk_f16_f32 v106, v104, v105
	v_cvt_pk_f16_f32 v105, v110, v111
	v_cvt_pk_f16_f32 v104, v108, v109
	global_store_dwordx4 v[112:113], v[104:107], off offset:-2048
	v_fma_f32 v87, v87, v127, v155
	v_add_f32_e32 v80, 1.0, v80
	v_log_f32_e32 v100, v100
	v_or_b32_e32 v104, 48, v146
	v_ashrrev_i32_e32 v105, 31, v104
	v_lshlrev_b64 v[104:105], 11, v[104:105]
	v_mul_f32_e32 v106, 0x3f317217, v100
	v_fma_f32 v106, v100, s87, -v106
	v_fmac_f32_e32 v106, 0x3377d1cf, v100
	v_lshl_add_u64 v[104:105], s[84:85], 0, v[104:105]
	v_lshl_add_u64 v[104:105], v[104:105], 0, v[136:137]
	v_fma_f32 v100, v100, s87, v106
	v_rcp_f32_e32 v80, v80
	v_log_f32_e32 v101, v101
	v_fma_f32 v80, v80, v160, v154
	v_mul_f32_e32 v81, 0xbfb8aa3b, v81
	v_exp_f32_e32 v81, v81
	v_mul_f32_e32 v106, 0x3f317217, v101
	v_fma_f32 v106, v101, s87, -v106
	v_fmac_f32_e32 v106, 0x3377d1cf, v101
	v_add_f32_e32 v81, 1.0, v81
	v_rcp_f32_e32 v81, v81
	v_fma_f32 v101, v101, s87, v106
	v_fma_f32 v81, v81, v147, v153
	v_log_f32_e32 v102, v102
	v_mul_f32_e32 v82, 0xbfb8aa3b, v82
	v_exp_f32_e32 v82, v82
	v_mul_f32_e32 v83, 0xbfb8aa3b, v83
	v_mul_f32_e32 v106, 0x3f317217, v102
	v_fma_f32 v106, v102, s87, -v106
	v_fmac_f32_e32 v106, 0x3377d1cf, v102
	v_add_f32_e32 v82, 1.0, v82
	v_rcp_f32_e32 v82, v82
	v_fma_f32 v102, v102, s87, v106
	v_fma_f32 v82, v82, v159, v152
	v_log_f32_e32 v103, v103
	v_exp_f32_e32 v83, v83
	v_mul_f32_e32 v76, 0xbfb8aa3b, v76
	v_exp_f32_e32 v76, v76
	v_mul_f32_e32 v106, 0x3f317217, v103
	v_fma_f32 v106, v103, s87, -v106
	v_fmac_f32_e32 v106, 0x3377d1cf, v103
	v_add_f32_e32 v83, 1.0, v83
	v_rcp_f32_e32 v83, v83
	v_fma_f32 v103, v103, s87, v106
	v_fma_f32 v83, v83, v122, v151
	v_log_f32_e32 v96, v96
	v_add_f32_e32 v76, 1.0, v76
	v_rcp_f32_e32 v76, v76
	v_mul_f32_e32 v77, 0xbfb8aa3b, v77
	v_mul_f32_e32 v106, 0x3f317217, v96
	v_fma_f32 v106, v96, s87, -v106
	v_fmac_f32_e32 v106, 0x3377d1cf, v96
	v_fma_f32 v76, v76, v124, v158
	v_exp_f32_e32 v77, v77
	v_fma_f32 v96, v96, s87, v106
	v_add_f32_e32 v77, 1.0, v77
	v_log_f32_e32 v97, v97
	v_rcp_f32_e32 v77, v77
	v_mul_f32_e32 v78, 0xbfb8aa3b, v78
	v_exp_f32_e32 v78, v78
	v_mul_f32_e32 v106, 0x3f317217, v97
	v_fma_f32 v106, v97, s87, -v106
	v_fmac_f32_e32 v106, 0x3377d1cf, v97
	v_fma_f32 v77, v77, v125, v157
	v_add_f32_e32 v78, 1.0, v78
	v_fma_f32 v97, v97, s87, v106
	v_rcp_f32_e32 v78, v78
	v_log_f32_e32 v98, v98
	v_fma_f32 v78, v78, v126, v156
	v_mul_f32_e32 v79, 0xbfb8aa3b, v79
	v_exp_f32_e32 v79, v79
	v_mul_f32_e32 v106, 0x3f317217, v98
	v_fma_f32 v106, v98, s87, -v106
	v_fmac_f32_e32 v106, 0x3377d1cf, v98
	v_add_f32_e32 v79, 1.0, v79
	v_rcp_f32_e32 v79, v79
	v_fma_f32 v98, v98, s87, v106
	v_fma_f32 v79, v79, v127, v155
	v_log_f32_e32 v99, v99
	v_mul_f32_e32 v72, 0xbfb8aa3b, v72
	v_exp_f32_e32 v72, v72
	v_mul_f32_e32 v73, 0xbfb8aa3b, v73
	v_mul_f32_e32 v106, 0x3f317217, v99
	v_fma_f32 v106, v99, s87, -v106
	v_fmac_f32_e32 v106, 0x3377d1cf, v99
	v_add_f32_e32 v72, 1.0, v72
	v_rcp_f32_e32 v72, v72
	v_fma_f32 v99, v99, s87, v106
	v_cvt_pk_f16_f32 v99, v98, v99
	v_cvt_pk_f16_f32 v98, v96, v97
	v_cvt_pk_f16_f32 v97, v102, v103
	v_cvt_pk_f16_f32 v96, v100, v101
	global_store_dwordx4 v[104:105], v[96:99], off offset:-2048
	s_mov_b64 s[6:7], 0x40000
	v_fma_f32 v72, v72, v160, v154
	v_log_f32_e32 v92, v92
	v_lshl_add_u64 v[96:97], v[148:149], 0, s[6:7]
	v_exp_f32_e32 v73, v73
	v_mul_f32_e32 v74, 0xbfb8aa3b, v74
	v_mul_f32_e32 v98, 0x3f317217, v92
	v_fma_f32 v98, v92, s87, -v98
	v_fmac_f32_e32 v98, 0x3377d1cf, v92
	v_add_f32_e32 v73, 1.0, v73
	v_rcp_f32_e32 v73, v73
	v_fma_f32 v92, v92, s87, v98
	v_fma_f32 v73, v73, v147, v153
	v_log_f32_e32 v93, v93
	v_exp_f32_e32 v74, v74
	v_mul_f32_e32 v75, 0xbfb8aa3b, v75
	v_exp_f32_e32 v75, v75
	v_mul_f32_e32 v98, 0x3f317217, v93
	v_fma_f32 v98, v93, s87, -v98
	v_fmac_f32_e32 v98, 0x3377d1cf, v93
	v_add_f32_e32 v74, 1.0, v74
	v_rcp_f32_e32 v74, v74
	v_fma_f32 v93, v93, s87, v98
	v_fma_f32 v74, v74, v159, v152
	v_log_f32_e32 v94, v94
	v_add_f32_e32 v75, 1.0, v75
	v_rcp_f32_e32 v75, v75
	v_mul_f32_e32 v68, 0xbfb8aa3b, v68
	v_mul_f32_e32 v98, 0x3f317217, v94
	v_fma_f32 v98, v94, s87, -v98
	v_fmac_f32_e32 v98, 0x3377d1cf, v94
	v_fma_f32 v75, v75, v122, v151
	v_exp_f32_e32 v68, v68
	v_fma_f32 v94, v94, s87, v98
	v_add_f32_e32 v68, 1.0, v68
	v_log_f32_e32 v95, v95
	v_rcp_f32_e32 v68, v68
	v_mul_f32_e32 v69, 0xbfb8aa3b, v69
	v_exp_f32_e32 v69, v69
	v_mul_f32_e32 v98, 0x3f317217, v95
	v_fma_f32 v98, v95, s87, -v98
	v_fmac_f32_e32 v98, 0x3377d1cf, v95
	v_fmac_f32_e32 v158, v68, v124
	v_add_f32_e32 v69, 1.0, v69
	v_fma_f32 v95, v95, s87, v98
	v_rcp_f32_e32 v69, v69
	v_log_f32_e32 v88, v88
	v_fmac_f32_e32 v157, v69, v125
	v_mul_f32_e32 v70, 0xbfb8aa3b, v70
	v_exp_f32_e32 v70, v70
	v_mul_f32_e32 v98, 0x3f317217, v88
	v_fma_f32 v98, v88, s87, -v98
	v_fmac_f32_e32 v98, 0x3377d1cf, v88
	v_add_f32_e32 v70, 1.0, v70
	v_rcp_f32_e32 v70, v70
	v_fma_f32 v88, v88, s87, v98
	v_fmac_f32_e32 v156, v70, v126
	v_log_f32_e32 v89, v89
	v_mul_f32_e32 v71, 0xbfb8aa3b, v71
	v_exp_f32_e32 v71, v71
	v_mul_f32_e32 v64, 0xbfb8aa3b, v64
	v_mul_f32_e32 v98, 0x3f317217, v89
	v_fma_f32 v98, v89, s87, -v98
	v_fmac_f32_e32 v98, 0x3377d1cf, v89
	v_add_f32_e32 v71, 1.0, v71
	v_rcp_f32_e32 v71, v71
	v_fma_f32 v89, v89, s87, v98
	v_fmac_f32_e32 v155, v71, v127
	v_log_f32_e32 v90, v90
	v_exp_f32_e32 v64, v64
	v_mul_f32_e32 v65, 0xbfb8aa3b, v65
	v_exp_f32_e32 v65, v65
	v_mul_f32_e32 v98, 0x3f317217, v90
	v_fma_f32 v98, v90, s87, -v98
	v_fmac_f32_e32 v98, 0x3377d1cf, v90
	v_add_f32_e32 v64, 1.0, v64
	v_rcp_f32_e32 v64, v64
	v_fma_f32 v90, v90, s87, v98
	v_fmac_f32_e32 v154, v64, v160
	v_log_f32_e32 v91, v91
	v_add_f32_e32 v65, 1.0, v65
	v_rcp_f32_e32 v65, v65
	v_mul_f32_e32 v66, 0xbfb8aa3b, v66
	v_mul_f32_e32 v98, 0x3f317217, v91
	v_fma_f32 v98, v91, s87, -v98
	v_fmac_f32_e32 v98, 0x3377d1cf, v91
	v_fmac_f32_e32 v153, v65, v147
	v_exp_f32_e32 v66, v66
	v_fma_f32 v91, v91, s87, v98
	v_cvt_pk_f16_f32 v91, v90, v91
	v_cvt_pk_f16_f32 v90, v88, v89
	v_cvt_pk_f16_f32 v89, v94, v95
	v_cvt_pk_f16_f32 v88, v92, v93
	global_store_dwordx4 v[96:97], v[88:91], off offset:-2048
	s_mov_b64 s[6:7], 0x48000
	v_add_f32_e32 v66, 1.0, v66
	v_log_f32_e32 v84, v84
	v_lshl_add_u64 v[88:89], v[148:149], 0, s[6:7]
	v_rcp_f32_e32 v66, v66
	v_mul_f32_e32 v67, 0xbfb8aa3b, v67
	v_mul_f32_e32 v90, 0x3f317217, v84
	v_fma_f32 v90, v84, s87, -v90
	v_fmac_f32_e32 v90, 0x3377d1cf, v84
	v_fmac_f32_e32 v152, v66, v159
	v_exp_f32_e32 v67, v67
	v_fma_f32 v84, v84, s87, v90
	v_add_f32_e32 v67, 1.0, v67
	v_log_f32_e32 v85, v85
	v_rcp_f32_e32 v67, v67
	s_movk_i32 s0, 0x1f8
	v_cvt_pk_f16_f32 v163, v163, v176
	v_mul_f32_e32 v90, 0x3f317217, v85
	v_fma_f32 v90, v85, s87, -v90
	v_fmac_f32_e32 v90, 0x3377d1cf, v85
	v_fmac_f32_e32 v151, v67, v122
	v_cvt_pk_f16_f32 v162, v161, v162
	v_fma_f32 v85, v85, s87, v90
	global_store_dwordx4 v[148:149], v[162:165], off offset:-2048
	v_log_f32_e32 v86, v86
	v_mul_f32_e32 v60, 0xbfb8aa3b, v60
	v_exp_f32_e32 v60, v60
	v_mul_f32_e32 v56, 0xbfb8aa3b, v56
	v_mul_f32_e32 v90, 0x3f317217, v86
	v_fma_f32 v90, v86, s87, -v90
	v_fmac_f32_e32 v90, 0x3377d1cf, v86
	v_add_f32_e32 v60, 1.0, v60
	v_rcp_f32_e32 v60, v60
	v_fma_f32 v86, v86, s87, v90
	v_exp_f32_e32 v56, v56
	v_log_f32_e32 v87, v87
	v_add_f32_e32 v56, 1.0, v56
	v_rcp_f32_e32 v56, v56
	v_mul_f32_e32 v52, 0xbfb8aa3b, v52
	v_mul_f32_e32 v90, 0x3f317217, v87
	v_fma_f32 v90, v87, s87, -v90
	v_fmac_f32_e32 v90, 0x3377d1cf, v87
	v_exp_f32_e32 v52, v52
	v_mul_f32_e32 v53, 0xbfb8aa3b, v53
	v_fma_f32 v87, v87, s87, v90
	v_add_f32_e32 v52, 1.0, v52
	v_log_f32_e32 v80, v80
	v_rcp_f32_e32 v52, v52
	v_exp_f32_e32 v53, v53
	v_mul_f32_e32 v54, 0xbfb8aa3b, v54
	v_mul_f32_e32 v90, 0x3f317217, v80
	v_fma_f32 v90, v80, s87, -v90
	v_fmac_f32_e32 v90, 0x3377d1cf, v80
	v_add_f32_e32 v53, 1.0, v53
	v_rcp_f32_e32 v53, v53
	v_fma_f32 v80, v80, s87, v90
	v_exp_f32_e32 v54, v54
	v_log_f32_e32 v81, v81
	v_add_f32_e32 v54, 1.0, v54
	v_rcp_f32_e32 v54, v54
	v_mul_f32_e32 v55, 0xbfb8aa3b, v55
	v_mul_f32_e32 v90, 0x3f317217, v81
	v_fma_f32 v90, v81, s87, -v90
	v_fmac_f32_e32 v90, 0x3377d1cf, v81
	v_exp_f32_e32 v55, v55
	v_mul_f32_e32 v48, 0xbfb8aa3b, v48
	v_fma_f32 v81, v81, s87, v90
	v_add_f32_e32 v55, 1.0, v55
	v_log_f32_e32 v82, v82
	v_rcp_f32_e32 v55, v55
	v_exp_f32_e32 v48, v48
	v_mul_f32_e32 v49, 0xbfb8aa3b, v49
	v_mul_f32_e32 v90, 0x3f317217, v82
	v_fma_f32 v90, v82, s87, -v90
	v_fmac_f32_e32 v90, 0x3377d1cf, v82
	v_add_f32_e32 v48, 1.0, v48
	v_rcp_f32_e32 v48, v48
	v_fma_f32 v82, v82, s87, v90
	v_exp_f32_e32 v49, v49
	v_log_f32_e32 v83, v83
	v_add_f32_e32 v49, 1.0, v49
	v_rcp_f32_e32 v49, v49
	v_mul_f32_e32 v50, 0xbfb8aa3b, v50
	v_mul_f32_e32 v90, 0x3f317217, v83
	v_fma_f32 v90, v83, s87, -v90
	v_fmac_f32_e32 v90, 0x3377d1cf, v83
	v_exp_f32_e32 v50, v50
	v_mul_f32_e32 v51, 0xbfb8aa3b, v51
	v_fma_f32 v83, v83, s87, v90
	v_cvt_pk_f16_f32 v83, v82, v83
	v_cvt_pk_f16_f32 v82, v80, v81
	v_cvt_pk_f16_f32 v81, v86, v87
	v_cvt_pk_f16_f32 v80, v84, v85
	global_store_dwordx4 v[88:89], v[80:83], off offset:-2048
	s_mov_b64 s[6:7], 0x50000
	v_add_f32_e32 v50, 1.0, v50
	v_log_f32_e32 v76, v76
	v_lshl_add_u64 v[80:81], v[148:149], 0, s[6:7]
	v_rcp_f32_e32 v50, v50
	v_exp_f32_e32 v51, v51
	v_mul_f32_e32 v82, 0x3f317217, v76
	v_fma_f32 v82, v76, s87, -v82
	v_fmac_f32_e32 v82, 0x3377d1cf, v76
	v_add_f32_e32 v51, 1.0, v51
	v_rcp_f32_e32 v51, v51
	v_fma_f32 v76, v76, s87, v82
	v_mul_f32_e32 v44, 0xbfb8aa3b, v44
	v_log_f32_e32 v77, v77
	v_exp_f32_e32 v44, v44
	v_mul_f32_e32 v45, 0xbfb8aa3b, v45
	v_exp_f32_e32 v45, v45
	v_mul_f32_e32 v82, 0x3f317217, v77
	v_fma_f32 v82, v77, s87, -v82
	v_fmac_f32_e32 v82, 0x3377d1cf, v77
	v_add_f32_e32 v44, 1.0, v44
	v_rcp_f32_e32 v44, v44
	v_fma_f32 v77, v77, s87, v82
	v_add_f32_e32 v45, 1.0, v45
	v_log_f32_e32 v78, v78
	v_rcp_f32_e32 v45, v45
	v_mul_f32_e32 v46, 0xbfb8aa3b, v46
	v_exp_f32_e32 v46, v46
	v_mul_f32_e32 v82, 0x3f317217, v78
	v_fma_f32 v82, v78, s87, -v82
	v_fmac_f32_e32 v82, 0x3377d1cf, v78
	v_add_f32_e32 v46, 1.0, v46
	v_rcp_f32_e32 v46, v46
	v_fma_f32 v78, v78, s87, v82
	v_mul_f32_e32 v47, 0xbfb8aa3b, v47
	v_log_f32_e32 v79, v79
	v_exp_f32_e32 v47, v47
	v_mul_f32_e32 v40, 0xbfb8aa3b, v40
	v_exp_f32_e32 v40, v40
	v_mul_f32_e32 v82, 0x3f317217, v79
	v_fma_f32 v82, v79, s87, -v82
	v_fmac_f32_e32 v82, 0x3377d1cf, v79
	v_add_f32_e32 v47, 1.0, v47
	v_rcp_f32_e32 v47, v47
	v_fma_f32 v79, v79, s87, v82
	v_add_f32_e32 v40, 1.0, v40
	v_log_f32_e32 v72, v72
	v_rcp_f32_e32 v40, v40
	v_mul_f32_e32 v41, 0xbfb8aa3b, v41
	v_exp_f32_e32 v41, v41
	v_mul_f32_e32 v82, 0x3f317217, v72
	v_fma_f32 v82, v72, s87, -v82
	v_fmac_f32_e32 v82, 0x3377d1cf, v72
	v_add_f32_e32 v41, 1.0, v41
	v_rcp_f32_e32 v41, v41
	v_fma_f32 v72, v72, s87, v82
	v_mul_f32_e32 v42, 0xbfb8aa3b, v42
	v_log_f32_e32 v73, v73
	v_exp_f32_e32 v42, v42
	v_mul_f32_e32 v43, 0xbfb8aa3b, v43
	v_exp_f32_e32 v43, v43
	v_mul_f32_e32 v82, 0x3f317217, v73
	v_fma_f32 v82, v73, s87, -v82
	v_fmac_f32_e32 v82, 0x3377d1cf, v73
	v_add_f32_e32 v42, 1.0, v42
	v_rcp_f32_e32 v42, v42
	v_fma_f32 v73, v73, s87, v82
	v_add_f32_e32 v43, 1.0, v43
	v_log_f32_e32 v74, v74
	v_rcp_f32_e32 v43, v43
	v_mul_f32_e32 v36, 0xbfb8aa3b, v36
	v_exp_f32_e32 v36, v36
	v_mul_f32_e32 v82, 0x3f317217, v74
	v_fma_f32 v82, v74, s87, -v82
	v_fmac_f32_e32 v82, 0x3377d1cf, v74
	v_add_f32_e32 v36, 1.0, v36
	v_rcp_f32_e32 v36, v36
	v_fma_f32 v74, v74, s87, v82
	v_mul_f32_e32 v37, 0xbfb8aa3b, v37
	v_log_f32_e32 v75, v75
	v_exp_f32_e32 v37, v37
	v_mul_f32_e32 v38, 0xbfb8aa3b, v38
	v_exp_f32_e32 v38, v38
	v_mul_f32_e32 v82, 0x3f317217, v75
	v_fma_f32 v82, v75, s87, -v82
	v_fmac_f32_e32 v82, 0x3377d1cf, v75
	v_add_f32_e32 v37, 1.0, v37
	v_rcp_f32_e32 v37, v37
	v_fma_f32 v75, v75, s87, v82
	v_cvt_pk_f16_f32 v75, v74, v75
	v_log_f32_e32 v68, v158
	v_cvt_pk_f16_f32 v74, v72, v73
	v_cvt_pk_f16_f32 v73, v78, v79
	v_cvt_pk_f16_f32 v72, v76, v77
	global_store_dwordx4 v[80:81], v[72:75], off offset:-2048
	s_mov_b64 s[6:7], 0x58000
	v_add_f32_e32 v38, 1.0, v38
	v_mul_f32_e32 v74, 0x3f317217, v68
	v_fma_f32 v74, v68, s87, -v74
	v_fmac_f32_e32 v74, 0x3377d1cf, v68
	v_lshl_add_u64 v[72:73], v[148:149], 0, s[6:7]
	v_rcp_f32_e32 v38, v38
	v_mul_f32_e32 v39, 0xbfb8aa3b, v39
	v_fma_f32 v68, v68, s87, v74
	v_exp_f32_e32 v39, v39
	v_log_f32_e32 v69, v157
	v_add_f32_e32 v39, 1.0, v39
	v_rcp_f32_e32 v39, v39
	v_mul_f32_e32 v32, 0xbfb8aa3b, v32
	v_mul_f32_e32 v74, 0x3f317217, v69
	v_fma_f32 v74, v69, s87, -v74
	v_fmac_f32_e32 v74, 0x3377d1cf, v69
	v_exp_f32_e32 v32, v32
	v_mul_f32_e32 v33, 0xbfb8aa3b, v33
	v_fma_f32 v69, v69, s87, v74
	v_add_f32_e32 v32, 1.0, v32
	v_log_f32_e32 v70, v156
	v_rcp_f32_e32 v32, v32
	v_exp_f32_e32 v33, v33
	v_mul_f32_e32 v34, 0xbfb8aa3b, v34
	v_mul_f32_e32 v74, 0x3f317217, v70
	v_fma_f32 v74, v70, s87, -v74
	v_fmac_f32_e32 v74, 0x3377d1cf, v70
	v_add_f32_e32 v33, 1.0, v33
	v_rcp_f32_e32 v33, v33
	v_fma_f32 v70, v70, s87, v74
	v_exp_f32_e32 v34, v34
	v_log_f32_e32 v71, v155
	v_add_f32_e32 v34, 1.0, v34
	v_rcp_f32_e32 v34, v34
	v_mul_f32_e32 v35, 0xbfb8aa3b, v35
	v_mul_f32_e32 v74, 0x3f317217, v71
	v_fma_f32 v74, v71, s87, -v74
	v_fmac_f32_e32 v74, 0x3377d1cf, v71
	v_exp_f32_e32 v35, v35
	v_mul_f32_e32 v28, 0xbfb8aa3b, v28
	v_fma_f32 v71, v71, s87, v74
	v_add_f32_e32 v35, 1.0, v35
	v_log_f32_e32 v64, v154
	v_rcp_f32_e32 v35, v35
	v_exp_f32_e32 v28, v28
	v_mul_f32_e32 v29, 0xbfb8aa3b, v29
	v_mul_f32_e32 v74, 0x3f317217, v64
	v_fma_f32 v74, v64, s87, -v74
	v_fmac_f32_e32 v74, 0x3377d1cf, v64
	v_add_f32_e32 v28, 1.0, v28
	v_rcp_f32_e32 v28, v28
	v_fma_f32 v64, v64, s87, v74
	v_exp_f32_e32 v29, v29
	v_log_f32_e32 v65, v153
	v_add_f32_e32 v29, 1.0, v29
	v_rcp_f32_e32 v29, v29
	v_mul_f32_e32 v30, 0xbfb8aa3b, v30
	v_mul_f32_e32 v74, 0x3f317217, v65
	v_fma_f32 v74, v65, s87, -v74
	v_fmac_f32_e32 v74, 0x3377d1cf, v65
	v_exp_f32_e32 v30, v30
	v_mul_f32_e32 v31, 0xbfb8aa3b, v31
	v_fma_f32 v65, v65, s87, v74
	v_add_f32_e32 v30, 1.0, v30
	v_log_f32_e32 v66, v152
	v_rcp_f32_e32 v30, v30
	v_exp_f32_e32 v31, v31
	v_mul_f32_e32 v24, 0xbfb8aa3b, v24
	v_mul_f32_e32 v74, 0x3f317217, v66
	v_fma_f32 v74, v66, s87, -v74
	v_fmac_f32_e32 v74, 0x3377d1cf, v66
	v_add_f32_e32 v31, 1.0, v31
	v_rcp_f32_e32 v31, v31
	v_fma_f32 v66, v66, s87, v74
	v_exp_f32_e32 v24, v24
	v_log_f32_e32 v67, v151
	v_add_f32_e32 v24, 1.0, v24
	v_rcp_f32_e32 v24, v24
	v_mul_f32_e32 v25, 0xbfb8aa3b, v25
	v_mul_f32_e32 v74, 0x3f317217, v67
	v_fma_f32 v74, v67, s87, -v74
	v_fmac_f32_e32 v74, 0x3377d1cf, v67
	v_exp_f32_e32 v25, v25
	v_mul_f32_e32 v26, 0xbfb8aa3b, v26
	v_fma_f32 v67, v67, s87, v74
	v_cvt_pk_f16_f32 v67, v66, v67
	v_cvt_pk_f16_f32 v66, v64, v65
	v_cvt_pk_f16_f32 v65, v70, v71
	v_cvt_pk_f16_f32 v64, v68, v69
	global_store_dwordx4 v[72:73], v[64:67], off offset:-2048
	v_add_f32_e32 v25, 1.0, v25
	v_rcp_f32_e32 v25, v25
	s_branch .Lhvy_join1
.Lhvy_fast2:
	v_sub_f32_e32 v64, v64, v90
	v_mul_f32_e32 v64, 0x3fb8aa3b, v64
	v_exp_f32_e32 v64, v64
	v_rcp_f32_e32 v5, v5
	v_exp_f32_e32 v6, v6
	v_mul_f32_e32 v7, 0xbfb8aa3b, v7
	v_add_f32_e32 v64, 1.0, v64
	v_rcp_f32_e32 v71, v64
	v_sub_f32_e32 v64, v65, v91
	v_mul_f32_e32 v64, 0x3fb8aa3b, v64
	v_exp_f32_e32 v64, v64
	v_add_f32_e32 v6, 1.0, v6
	v_rcp_f32_e32 v6, v6
	v_exp_f32_e32 v7, v7
	v_add_f32_e32 v64, 1.0, v64
	v_rcp_f32_e32 v70, v64
	v_sub_f32_e32 v64, v66, v92
	v_mul_f32_e32 v64, 0x3fb8aa3b, v64
	v_exp_f32_e32 v64, v64
	v_add_f32_e32 v7, 1.0, v7
	v_rcp_f32_e32 v7, v7
	v_mul_f32_e32 v0, 0xbfb8aa3b, v0
	v_add_f32_e32 v64, 1.0, v64
	v_rcp_f32_e32 v69, v64
	v_sub_f32_e32 v64, v67, v93
	v_mul_f32_e32 v64, 0x3fb8aa3b, v64
	v_exp_f32_e32 v64, v64
	v_exp_f32_e32 v0, v0
	v_mul_f32_e32 v1, 0xbfb8aa3b, v1
	v_exp_f32_e32 v1, v1
	v_add_f32_e32 v64, 1.0, v64
	v_rcp_f32_e32 v68, v64
	v_sub_f32_e32 v64, v74, v82
	v_mul_f32_e32 v64, 0x3fb8aa3b, v64
	v_exp_f32_e32 v64, v64
	v_add_f32_e32 v0, 1.0, v0
	v_rcp_f32_e32 v0, v0
	v_add_f32_e32 v1, 1.0, v1
	v_add_f32_e32 v64, 1.0, v64
	v_rcp_f32_e32 v67, v64
	v_sub_f32_e32 v64, v75, v83
	v_sub_f32_e32 v75, 1.0, v71
	v_fma_f32 v60, v60, v75, v71
	v_mul_f32_e32 v64, 0x3fb8aa3b, v64
	v_exp_f32_e32 v64, v64
	v_log_f32_e32 v60, v60
	v_add_f32_e32 v64, 1.0, v64
	v_rcp_f32_e32 v66, v64
	v_sub_f32_e32 v64, v76, v84
	v_mul_f32_e32 v74, 0x3f317217, v60
	v_fma_f32 v74, v60, s87, -v74
	v_fmac_f32_e32 v74, 0x3377d1cf, v60
	v_mul_f32_e32 v64, 0x3fb8aa3b, v64
	v_exp_f32_e32 v64, v64
	v_fma_f32 v76, v60, s87, v74
	v_mul_f32_e32 v60, 0xbfb8aa3b, v61
	v_exp_f32_e32 v60, v60
	v_sub_f32_e32 v74, 1.0, v70
	v_add_f32_e32 v64, 1.0, v64
	v_rcp_f32_e32 v65, v64
	v_add_f32_e32 v60, 1.0, v60
	v_rcp_f32_e32 v60, v60
	v_sub_f32_e32 v64, v77, v85
	v_mul_f32_e32 v64, 0x3fb8aa3b, v64
	v_exp_f32_e32 v64, v64
	v_fma_f32 v60, v60, v74, v70
	v_fma_f32 v52, v52, v75, v71
	v_add_f32_e32 v64, 1.0, v64
	v_log_f32_e32 v60, v60
	v_rcp_f32_e32 v64, v64
	v_fma_f32 v53, v53, v74, v70
	v_fma_f32 v44, v44, v75, v71
	v_mul_f32_e32 v61, 0x3f317217, v60
	v_fma_f32 v61, v60, s87, -v61
	v_fmac_f32_e32 v61, 0x3377d1cf, v60
	v_fma_f32 v45, v45, v74, v70
	v_fma_f32 v36, v36, v75, v71
	v_fma_f32 v82, v60, s87, v61
	v_mul_f32_e32 v60, 0xbfb8aa3b, v62
	v_exp_f32_e32 v60, v60
	v_sub_f32_e32 v61, 1.0, v69
	v_fma_f32 v54, v54, v61, v69
	v_fma_f32 v46, v46, v61, v69
	v_add_f32_e32 v60, 1.0, v60
	v_rcp_f32_e32 v60, v60
	v_fma_f32 v37, v37, v74, v70
	v_fma_f32 v38, v38, v61, v69
	v_fma_f32 v28, v28, v75, v71
	v_fma_f32 v60, v60, v61, v69
	v_fma_f32 v29, v29, v74, v70
	v_fma_f32 v30, v30, v61, v69
	v_log_f32_e32 v60, v60
	v_fma_f32 v20, v20, v75, v71
	v_fma_f32 v21, v21, v74, v70
	v_fma_f32 v22, v22, v61, v69
	v_mul_f32_e32 v62, 0x3f317217, v60
	v_fma_f32 v62, v60, s87, -v62
	v_fmac_f32_e32 v62, 0x3377d1cf, v60
	v_fma_f32 v12, v12, v75, v71
	v_fma_f32 v13, v13, v74, v70
	v_fma_f32 v77, v60, s87, v62
	v_mul_f32_e32 v60, 0xbfb8aa3b, v63
	v_exp_f32_e32 v60, v60
	v_fma_f32 v14, v14, v61, v69
	v_fmac_f32_e32 v71, v4, v75
	v_fmac_f32_e32 v70, v5, v74
	v_add_f32_e32 v60, 1.0, v60
	v_rcp_f32_e32 v62, v60
	v_sub_f32_e32 v60, 1.0, v68
	v_fma_f32 v55, v55, v60, v68
	v_fma_f32 v47, v47, v60, v68
	v_fma_f32 v62, v62, v60, v68
	v_fma_f32 v39, v39, v60, v68
	v_fma_f32 v31, v31, v60, v68
	v_log_f32_e32 v62, v62
	v_fma_f32 v23, v23, v60, v68
	v_fma_f32 v15, v15, v60, v68
	v_fmac_f32_e32 v69, v6, v61
	v_mul_f32_e32 v63, 0x3f317217, v62
	v_fma_f32 v63, v62, s87, -v63
	v_fmac_f32_e32 v63, 0x3377d1cf, v62
	v_fmac_f32_e32 v68, v7, v60
	v_rcp_f32_e32 v1, v1
	v_fma_f32 v63, v62, s87, v63
	v_sub_f32_e32 v62, 1.0, v67
	v_fma_f32 v56, v56, v62, v67
	v_fma_f32 v48, v48, v62, v67
	v_fma_f32 v40, v40, v62, v67
	v_log_f32_e32 v56, v56
	v_fma_f32 v32, v32, v62, v67
	v_fma_f32 v24, v24, v62, v67
	v_fma_f32 v16, v16, v62, v67
	v_mul_f32_e32 v78, 0x3f317217, v56
	v_fma_f32 v78, v56, s87, -v78
	v_fmac_f32_e32 v78, 0x3377d1cf, v56
	v_fma_f32 v8, v8, v62, v67
	v_fmac_f32_e32 v67, v0, v62
	v_fma_f32 v78, v56, s87, v78
	v_mul_f32_e32 v56, 0xbfb8aa3b, v57
	v_exp_f32_e32 v56, v56
	v_mul_f32_e32 v2, 0xbfb8aa3b, v2
	v_exp_f32_e32 v2, v2
	v_mul_f32_e32 v3, 0xbfb8aa3b, v3
	v_add_f32_e32 v56, 1.0, v56
	v_rcp_f32_e32 v57, v56
	v_sub_f32_e32 v56, 1.0, v66
	v_fma_f32 v49, v49, v56, v66
	v_fma_f32 v41, v41, v56, v66
	v_fma_f32 v57, v57, v56, v66
	v_fma_f32 v33, v33, v56, v66
	v_fma_f32 v25, v25, v56, v66
	v_log_f32_e32 v57, v57
	v_fma_f32 v17, v17, v56, v66
	v_fma_f32 v9, v9, v56, v66
	v_fmac_f32_e32 v66, v1, v56
	v_mul_f32_e32 v79, 0x3f317217, v57
	v_fma_f32 v79, v57, s87, -v79
	v_fmac_f32_e32 v79, 0x3377d1cf, v57
	v_add_f32_e32 v2, 1.0, v2
	v_rcp_f32_e32 v2, v2
	v_fma_f32 v83, v57, s87, v79
	v_mul_f32_e32 v57, 0xbfb8aa3b, v58
	v_exp_f32_e32 v57, v57
	v_sub_f32_e32 v58, 1.0, v65
	v_fma_f32 v50, v50, v58, v65
	v_fma_f32 v42, v42, v58, v65
	v_add_f32_e32 v57, 1.0, v57
	v_rcp_f32_e32 v57, v57
	v_fma_f32 v34, v34, v58, v65
	v_fma_f32 v26, v26, v58, v65
	v_fma_f32 v18, v18, v58, v65
	v_fma_f32 v57, v57, v58, v65
	v_fma_f32 v10, v10, v58, v65
	v_fmac_f32_e32 v65, v2, v58
	v_log_f32_e32 v57, v57
	v_exp_f32_e32 v3, v3
	v_cvt_pk_f16_f32 v78, v78, v83
	v_cvt_pk_f16_f32 v77, v77, v63
	v_mul_f32_e32 v79, 0x3f317217, v57
	v_fma_f32 v79, v57, s87, -v79
	v_fmac_f32_e32 v79, 0x3377d1cf, v57
	v_add_f32_e32 v3, 1.0, v3
	v_rcp_f32_e32 v3, v3
	v_fma_f32 v79, v57, s87, v79
	v_mul_f32_e32 v57, 0xbfb8aa3b, v59
	v_exp_f32_e32 v57, v57
	v_cvt_pk_f16_f32 v76, v76, v82
	v_add_f32_e32 v57, 1.0, v57
	v_rcp_f32_e32 v59, v57
	v_sub_f32_e32 v57, 1.0, v64
	v_fma_f32 v51, v51, v57, v64
	v_fma_f32 v43, v43, v57, v64
	v_fma_f32 v59, v59, v57, v64
	v_fma_f32 v35, v35, v57, v64
	v_fma_f32 v27, v27, v57, v64
	v_log_f32_e32 v59, v59
	v_fma_f32 v19, v19, v57, v64
	v_fma_f32 v11, v11, v57, v64
	v_fmac_f32_e32 v64, v3, v57
	v_mul_f32_e32 v84, 0x3f317217, v59
	v_fma_f32 v84, v59, s87, -v84
	v_fmac_f32_e32 v84, 0x3377d1cf, v59
	v_fma_f32 v59, v59, s87, v84
	v_cvt_pk_f16_f32 v79, v79, v59
	global_store_dwordx4 v[148:149], v[76:79], off offset:-1792
	v_log_f32_e32 v52, v52
	s_nop 0
	v_mul_f32_e32 v59, 0x3f317217, v52
	v_fma_f32 v59, v52, s87, -v59
	v_fmac_f32_e32 v59, 0x3377d1cf, v52
	v_fma_f32 v52, v52, s87, v59
	v_log_f32_e32 v53, v53
	s_nop 0
	v_mul_f32_e32 v59, 0x3f317217, v53
	v_fma_f32 v59, v53, s87, -v59
	v_fmac_f32_e32 v59, 0x3377d1cf, v53
	v_fma_f32 v53, v53, s87, v59
	v_log_f32_e32 v54, v54
	s_nop 0
	v_mul_f32_e32 v59, 0x3f317217, v54
	v_fma_f32 v59, v54, s87, -v59
	v_fmac_f32_e32 v59, 0x3377d1cf, v54
	v_fma_f32 v54, v54, s87, v59
	v_log_f32_e32 v55, v55
	s_nop 0
	v_mul_f32_e32 v59, 0x3f317217, v55
	v_fma_f32 v59, v55, s87, -v59
	v_fmac_f32_e32 v59, 0x3377d1cf, v55
	v_fma_f32 v55, v55, s87, v59
	v_log_f32_e32 v48, v48
	s_nop 0
	v_mul_f32_e32 v59, 0x3f317217, v48
	v_fma_f32 v59, v48, s87, -v59
	v_fmac_f32_e32 v59, 0x3377d1cf, v48
	v_fma_f32 v48, v48, s87, v59
	v_log_f32_e32 v49, v49
	s_nop 0
	v_mul_f32_e32 v59, 0x3f317217, v49
	v_fma_f32 v59, v49, s87, -v59
	v_fmac_f32_e32 v59, 0x3377d1cf, v49
	v_fma_f32 v49, v49, s87, v59
	v_log_f32_e32 v50, v50
	s_nop 0
	v_mul_f32_e32 v59, 0x3f317217, v50
	v_fma_f32 v59, v50, s87, -v59
	v_fmac_f32_e32 v59, 0x3377d1cf, v50
	v_fma_f32 v50, v50, s87, v59
	v_log_f32_e32 v51, v51
	s_nop 0
	v_mul_f32_e32 v59, 0x3f317217, v51
	v_fma_f32 v59, v51, s87, -v59
	v_fmac_f32_e32 v59, 0x3377d1cf, v51
	v_fma_f32 v51, v51, s87, v59
	v_cvt_pk_f16_f32 v51, v50, v51
	v_cvt_pk_f16_f32 v50, v48, v49
	v_cvt_pk_f16_f32 v49, v54, v55
	v_cvt_pk_f16_f32 v48, v52, v53
	global_store_dwordx4 v[120:121], v[48:51], off offset:-1792
	v_log_f32_e32 v44, v44
	s_nop 0
	v_mul_f32_e32 v48, 0x3f317217, v44
	v_fma_f32 v48, v44, s87, -v48
	v_fmac_f32_e32 v48, 0x3377d1cf, v44
	v_fma_f32 v44, v44, s87, v48
	v_log_f32_e32 v45, v45
	s_nop 0
	v_mul_f32_e32 v48, 0x3f317217, v45
	v_fma_f32 v48, v45, s87, -v48
	v_fmac_f32_e32 v48, 0x3377d1cf, v45
	v_fma_f32 v45, v45, s87, v48
	v_log_f32_e32 v46, v46
	s_nop 0
	v_mul_f32_e32 v48, 0x3f317217, v46
	v_fma_f32 v48, v46, s87, -v48
	v_fmac_f32_e32 v48, 0x3377d1cf, v46
	v_fma_f32 v46, v46, s87, v48
	v_log_f32_e32 v47, v47
	s_nop 0
	v_mul_f32_e32 v48, 0x3f317217, v47
	v_fma_f32 v48, v47, s87, -v48
	v_fmac_f32_e32 v48, 0x3377d1cf, v47
	v_fma_f32 v47, v47, s87, v48
	v_log_f32_e32 v40, v40
	s_nop 0
	v_mul_f32_e32 v48, 0x3f317217, v40
	v_fma_f32 v48, v40, s87, -v48
	v_fmac_f32_e32 v48, 0x3377d1cf, v40
	v_fma_f32 v40, v40, s87, v48
	v_log_f32_e32 v41, v41
	s_nop 0
	v_mul_f32_e32 v48, 0x3f317217, v41
	v_fma_f32 v48, v41, s87, -v48
	v_fmac_f32_e32 v48, 0x3377d1cf, v41
	v_fma_f32 v41, v41, s87, v48
	v_log_f32_e32 v42, v42
	s_nop 0
	v_mul_f32_e32 v48, 0x3f317217, v42
	v_fma_f32 v48, v42, s87, -v48
	v_fmac_f32_e32 v48, 0x3377d1cf, v42
	v_fma_f32 v42, v42, s87, v48
	v_log_f32_e32 v43, v43
	s_nop 0
	v_mul_f32_e32 v48, 0x3f317217, v43
	v_fma_f32 v48, v43, s87, -v48
	v_fmac_f32_e32 v48, 0x3377d1cf, v43
	v_fma_f32 v43, v43, s87, v48
	v_cvt_pk_f16_f32 v43, v42, v43
	v_cvt_pk_f16_f32 v42, v40, v41
	v_cvt_pk_f16_f32 v41, v46, v47
	v_cvt_pk_f16_f32 v40, v44, v45
	global_store_dwordx4 v[112:113], v[40:43], off offset:-1792
	v_log_f32_e32 v36, v36
	s_nop 0
	v_mul_f32_e32 v40, 0x3f317217, v36
	v_fma_f32 v40, v36, s87, -v40
	v_fmac_f32_e32 v40, 0x3377d1cf, v36
	v_fma_f32 v36, v36, s87, v40
	v_log_f32_e32 v37, v37
	s_nop 0
	v_mul_f32_e32 v40, 0x3f317217, v37
	v_fma_f32 v40, v37, s87, -v40
	v_fmac_f32_e32 v40, 0x3377d1cf, v37
	v_fma_f32 v37, v37, s87, v40
	v_log_f32_e32 v38, v38
	s_nop 0
	v_mul_f32_e32 v40, 0x3f317217, v38
	v_fma_f32 v40, v38, s87, -v40
	v_fmac_f32_e32 v40, 0x3377d1cf, v38
	v_fma_f32 v38, v38, s87, v40
	v_log_f32_e32 v39, v39
	s_nop 0
	v_mul_f32_e32 v40, 0x3f317217, v39
	v_fma_f32 v40, v39, s87, -v40
	v_fmac_f32_e32 v40, 0x3377d1cf, v39
	v_fma_f32 v39, v39, s87, v40
	v_log_f32_e32 v32, v32
	s_nop 0
	v_mul_f32_e32 v40, 0x3f317217, v32
	v_fma_f32 v40, v32, s87, -v40
	v_fmac_f32_e32 v40, 0x3377d1cf, v32
	v_fma_f32 v32, v32, s87, v40
	v_log_f32_e32 v33, v33
	s_nop 0
	v_mul_f32_e32 v40, 0x3f317217, v33
	v_fma_f32 v40, v33, s87, -v40
	v_fmac_f32_e32 v40, 0x3377d1cf, v33
	v_fma_f32 v33, v33, s87, v40
	v_log_f32_e32 v34, v34
	s_nop 0
	v_mul_f32_e32 v40, 0x3f317217, v34
	v_fma_f32 v40, v34, s87, -v40
	v_fmac_f32_e32 v40, 0x3377d1cf, v34
	v_fma_f32 v34, v34, s87, v40
	v_log_f32_e32 v35, v35
	s_nop 0
	v_mul_f32_e32 v40, 0x3f317217, v35
	v_fma_f32 v40, v35, s87, -v40
	v_fmac_f32_e32 v40, 0x3377d1cf, v35
	v_fma_f32 v35, v35, s87, v40
	v_cvt_pk_f16_f32 v35, v34, v35
	v_cvt_pk_f16_f32 v34, v32, v33
	v_cvt_pk_f16_f32 v33, v38, v39
	v_cvt_pk_f16_f32 v32, v36, v37
	global_store_dwordx4 v[104:105], v[32:35], off offset:-1792
	v_log_f32_e32 v28, v28
	s_nop 0
	v_mul_f32_e32 v32, 0x3f317217, v28
	v_fma_f32 v32, v28, s87, -v32
	v_fmac_f32_e32 v32, 0x3377d1cf, v28
	v_fma_f32 v28, v28, s87, v32
	v_log_f32_e32 v29, v29
	s_nop 0
	v_mul_f32_e32 v32, 0x3f317217, v29
	v_fma_f32 v32, v29, s87, -v32
	v_fmac_f32_e32 v32, 0x3377d1cf, v29
	v_fma_f32 v29, v29, s87, v32
	v_log_f32_e32 v30, v30
	s_nop 0
	v_mul_f32_e32 v32, 0x3f317217, v30
	v_fma_f32 v32, v30, s87, -v32
	v_fmac_f32_e32 v32, 0x3377d1cf, v30
	v_fma_f32 v30, v30, s87, v32
	v_log_f32_e32 v31, v31
	s_nop 0
	v_mul_f32_e32 v32, 0x3f317217, v31
	v_fma_f32 v32, v31, s87, -v32
	v_fmac_f32_e32 v32, 0x3377d1cf, v31
	v_fma_f32 v31, v31, s87, v32
	v_log_f32_e32 v24, v24
	s_nop 0
	v_mul_f32_e32 v32, 0x3f317217, v24
	v_fma_f32 v32, v24, s87, -v32
	v_fmac_f32_e32 v32, 0x3377d1cf, v24
	v_fma_f32 v24, v24, s87, v32
	v_log_f32_e32 v25, v25
	s_nop 0
	v_mul_f32_e32 v32, 0x3f317217, v25
	v_fma_f32 v32, v25, s87, -v32
	v_fmac_f32_e32 v32, 0x3377d1cf, v25
	v_fma_f32 v25, v25, s87, v32
	v_log_f32_e32 v26, v26
	s_nop 0
	v_mul_f32_e32 v32, 0x3f317217, v26
	v_fma_f32 v32, v26, s87, -v32
	v_fmac_f32_e32 v32, 0x3377d1cf, v26
	v_fma_f32 v26, v26, s87, v32
	v_log_f32_e32 v27, v27
	s_nop 0
	v_mul_f32_e32 v32, 0x3f317217, v27
	v_fma_f32 v32, v27, s87, -v32
	v_fmac_f32_e32 v32, 0x3377d1cf, v27
	v_fma_f32 v27, v27, s87, v32
	v_cvt_pk_f16_f32 v27, v26, v27
	v_cvt_pk_f16_f32 v26, v24, v25
	v_cvt_pk_f16_f32 v25, v30, v31
	v_cvt_pk_f16_f32 v24, v28, v29
	global_store_dwordx4 v[96:97], v[24:27], off offset:-1792
	v_log_f32_e32 v20, v20
	s_nop 0
	v_mul_f32_e32 v24, 0x3f317217, v20
	v_fma_f32 v24, v20, s87, -v24
	v_fmac_f32_e32 v24, 0x3377d1cf, v20
	v_fma_f32 v20, v20, s87, v24
	v_log_f32_e32 v21, v21
	s_nop 0
	v_mul_f32_e32 v24, 0x3f317217, v21
	v_fma_f32 v24, v21, s87, -v24
	v_fmac_f32_e32 v24, 0x3377d1cf, v21
	v_fma_f32 v21, v21, s87, v24
	v_log_f32_e32 v22, v22
	s_nop 0
	v_mul_f32_e32 v24, 0x3f317217, v22
	v_fma_f32 v24, v22, s87, -v24
	v_fmac_f32_e32 v24, 0x3377d1cf, v22
	v_fma_f32 v22, v22, s87, v24
	v_log_f32_e32 v23, v23
	s_nop 0
	v_mul_f32_e32 v24, 0x3f317217, v23
	v_fma_f32 v24, v23, s87, -v24
	v_fmac_f32_e32 v24, 0x3377d1cf, v23
	v_fma_f32 v23, v23, s87, v24
	v_log_f32_e32 v16, v16
	s_nop 0
	v_mul_f32_e32 v24, 0x3f317217, v16
	v_fma_f32 v24, v16, s87, -v24
	v_fmac_f32_e32 v24, 0x3377d1cf, v16
	v_fma_f32 v16, v16, s87, v24
	v_log_f32_e32 v17, v17
	s_nop 0
	v_mul_f32_e32 v24, 0x3f317217, v17
	v_fma_f32 v24, v17, s87, -v24
	v_fmac_f32_e32 v24, 0x3377d1cf, v17
	v_fma_f32 v17, v17, s87, v24
	v_log_f32_e32 v18, v18
	s_nop 0
	v_mul_f32_e32 v24, 0x3f317217, v18
	v_fma_f32 v24, v18, s87, -v24
	v_fmac_f32_e32 v24, 0x3377d1cf, v18
	v_fma_f32 v18, v18, s87, v24
	v_log_f32_e32 v19, v19
	s_nop 0
	v_mul_f32_e32 v24, 0x3f317217, v19
	v_fma_f32 v24, v19, s87, -v24
	v_fmac_f32_e32 v24, 0x3377d1cf, v19
	v_fma_f32 v19, v19, s87, v24
	v_cvt_pk_f16_f32 v19, v18, v19
	v_cvt_pk_f16_f32 v18, v16, v17
	v_cvt_pk_f16_f32 v17, v22, v23
	v_cvt_pk_f16_f32 v16, v20, v21
	global_store_dwordx4 v[88:89], v[16:19], off offset:-1792
	v_log_f32_e32 v12, v12
	s_nop 0
	v_mul_f32_e32 v16, 0x3f317217, v12
	v_fma_f32 v16, v12, s87, -v16
	v_fmac_f32_e32 v16, 0x3377d1cf, v12
	v_fma_f32 v12, v12, s87, v16
	v_log_f32_e32 v13, v13
	s_nop 0
	v_mul_f32_e32 v16, 0x3f317217, v13
	v_fma_f32 v16, v13, s87, -v16
	v_fmac_f32_e32 v16, 0x3377d1cf, v13
	v_fma_f32 v13, v13, s87, v16
	v_log_f32_e32 v14, v14
	s_nop 0
	v_mul_f32_e32 v16, 0x3f317217, v14
	v_fma_f32 v16, v14, s87, -v16
	v_fmac_f32_e32 v16, 0x3377d1cf, v14
	v_fma_f32 v14, v14, s87, v16
	v_log_f32_e32 v15, v15
	s_nop 0
	v_mul_f32_e32 v16, 0x3f317217, v15
	v_fma_f32 v16, v15, s87, -v16
	v_fmac_f32_e32 v16, 0x3377d1cf, v15
	v_fma_f32 v15, v15, s87, v16
	v_log_f32_e32 v8, v8
	s_nop 0
	v_mul_f32_e32 v16, 0x3f317217, v8
	v_fma_f32 v16, v8, s87, -v16
	v_fmac_f32_e32 v16, 0x3377d1cf, v8
	v_fma_f32 v8, v8, s87, v16
	v_log_f32_e32 v9, v9
	s_nop 0
	v_mul_f32_e32 v16, 0x3f317217, v9
	v_fma_f32 v16, v9, s87, -v16
	v_fmac_f32_e32 v16, 0x3377d1cf, v9
	v_fma_f32 v9, v9, s87, v16
	v_log_f32_e32 v10, v10
	s_nop 0
	v_mul_f32_e32 v16, 0x3f317217, v10
	v_fma_f32 v16, v10, s87, -v16
	v_fmac_f32_e32 v16, 0x3377d1cf, v10
	v_fma_f32 v10, v10, s87, v16
	v_log_f32_e32 v11, v11
	s_nop 0
	v_mul_f32_e32 v16, 0x3f317217, v11
	v_fma_f32 v16, v11, s87, -v16
	v_fmac_f32_e32 v16, 0x3377d1cf, v11
	v_fma_f32 v11, v11, s87, v16
	v_cvt_pk_f16_f32 v11, v10, v11
	v_log_f32_e32 v4, v71
	v_cvt_pk_f16_f32 v10, v8, v9
	v_cvt_pk_f16_f32 v9, v14, v15
	v_cvt_pk_f16_f32 v8, v12, v13
	global_store_dwordx4 v[80:81], v[8:11], off offset:-1792
	s_nop 1
	v_mul_f32_e32 v8, 0x3f317217, v4
	v_fma_f32 v8, v4, s87, -v8
	v_fmac_f32_e32 v8, 0x3377d1cf, v4
	v_fma_f32 v4, v4, s87, v8
	v_log_f32_e32 v5, v70
	s_nop 0
	v_mul_f32_e32 v8, 0x3f317217, v5
	v_fma_f32 v8, v5, s87, -v8
	v_fmac_f32_e32 v8, 0x3377d1cf, v5
	v_fma_f32 v5, v5, s87, v8
	v_log_f32_e32 v6, v69
	s_nop 0
	v_mul_f32_e32 v8, 0x3f317217, v6
	v_fma_f32 v8, v6, s87, -v8
	v_fmac_f32_e32 v8, 0x3377d1cf, v6
	v_fma_f32 v6, v6, s87, v8
	v_log_f32_e32 v7, v68
	s_nop 0
	v_mul_f32_e32 v8, 0x3f317217, v7
	v_fma_f32 v8, v7, s87, -v8
	v_fmac_f32_e32 v8, 0x3377d1cf, v7
	v_fma_f32 v7, v7, s87, v8
	v_log_f32_e32 v0, v67
	s_nop 0
	v_mul_f32_e32 v8, 0x3f317217, v0
	v_fma_f32 v8, v0, s87, -v8
	v_fmac_f32_e32 v8, 0x3377d1cf, v0
	v_fma_f32 v0, v0, s87, v8
	v_log_f32_e32 v1, v66
	s_nop 0
	v_mul_f32_e32 v8, 0x3f317217, v1
	v_fma_f32 v8, v1, s87, -v8
	v_fmac_f32_e32 v8, 0x3377d1cf, v1
	v_fma_f32 v1, v1, s87, v8
	v_log_f32_e32 v2, v65
	s_nop 0
	v_mul_f32_e32 v8, 0x3f317217, v2
	v_fma_f32 v8, v2, s87, -v8
	v_fmac_f32_e32 v8, 0x3377d1cf, v2
	v_fma_f32 v2, v2, s87, v8
	v_log_f32_e32 v3, v64
	s_nop 0
	v_mul_f32_e32 v8, 0x3f317217, v3
	v_fma_f32 v8, v3, s87, -v8
	v_fmac_f32_e32 v8, 0x3377d1cf, v3
	v_fma_f32 v3, v3, s87, v8
	v_cvt_pk_f16_f32 v3, v2, v3
	v_cvt_pk_f16_f32 v2, v0, v1
	v_cvt_pk_f16_f32 v1, v6, v7
	v_cvt_pk_f16_f32 v0, v4, v5
	global_store_dwordx4 v[72:73], v[0:3], off offset:-1792
	s_branch .LBB0_237
